# GEMM K-loops: LDS-DMA addresses as scalar base + 32-bit lane offset (saddr form), 64-bit VALU adds removed
# speedup vs baseline: 1.0004x; 1.0004x over previous
.LBB0_757:
	s_ashr_i32 s17, s16, 31
	s_lshl_b64 s[18:19], s[16:17], 20
	s_add_u32 s18, s35, s18
	s_addc_u32 s19, s40, s19
	s_and_b64 s[20:21], s[4:5], exec
	s_cselect_b32 s17, s19, s29
	s_cselect_b32 s23, s18, s28
	s_ashr_i32 s15, s14, 31
	s_lshl_b64 s[20:21], s[14:15], 19
	s_add_u32 s20, s38, s20
	s_addc_u32 s21, s39, s21
	s_and_b64 s[30:31], s[4:5], exec
	s_cselect_b32 s15, s21, s27
	s_cselect_b32 s25, s20, s26
	s_add_u32 s52, s26, 0x100
	s_addc_u32 s53, s27, 0
	s_add_u32 s26, s28, 0x80080
	s_addc_u32 s27, s29, 0
	s_mov_b32 s54, -2
	s_waitcnt lgkmcnt(0)
	s_add_u32 s28, s26, 0xfff80080
	s_addc_u32 s29, s27, -1
	s_add_i32 s55, 0, 0x10000
	s_cmp_eq_u32 s54, 12
	s_cselect_b32 s31, s17, s29
	s_cselect_b32 s30, s23, s28
	s_cselect_b32 s29, s15, s53
	s_cselect_b32 s28, s25, s52
	s_add_i32 s58, 0, 0x14000
	v_add_u32_e32 v156, s55, v145
	v_add_u32_e32 v172, s58, v145
	ds_read_b128 v[140:143], v156
	ds_read_b128 v[148:151], v156 offset:1024
	ds_read_b128 v[152:155], v156 offset:2048
	ds_read_b128 v[156:159], v156 offset:3072
	ds_read_b128 v[160:163], v172
	ds_read_b128 v[164:167], v172 offset:1024
	ds_read_b128 v[168:171], v172 offset:2048
	ds_read_b128 v[172:175], v172 offset:3072
	s_add_i32 m0, s42, 0xc000
	ds_read_b128 v[176:179], v147
	ds_read_b128 v[180:183], v147 offset:1024
	ds_read_b128 v[184:187], v147 offset:2048
	ds_read_b128 v[208:211], v147 offset:3072
	ds_read_b128 v[230:233], v147 offset:4096
	ds_read_b128 v[234:237], v147 offset:5120
	ds_read_b128 v[238:241], v147 offset:6144
	ds_read_b128 v[242:245], v147 offset:7168
	global_load_lds_dwordx4 v138, s[26:27]
	s_add_i32 m0, s42, 0xe000
	s_nop 0
	global_load_lds_dwordx4 v136, s[26:27]
	s_waitcnt vmcnt(8)
	s_waitcnt lgkmcnt(0)
	s_barrier
	s_setprio 1
	s_waitcnt lgkmcnt(0)
	v_mfma_f32_16x16x32_bf16 v[126:129], v[140:143], v[176:179], 0
	v_mfma_f32_16x16x32_bf16 v[122:125], v[152:155], v[176:179], 0
	v_mfma_f32_16x16x32_bf16 v[108:111], v[140:143], v[184:187], 0
	v_mfma_f32_16x16x32_bf16 v[104:107], v[152:155], v[184:187], 0
	v_mfma_f32_16x16x32_bf16 v[92:95], v[140:143], v[230:233], 0
	v_mfma_f32_16x16x32_bf16 v[88:91], v[152:155], v[230:233], 0
	v_mfma_f32_16x16x32_bf16 v[76:79], v[140:143], v[238:241], 0
	v_mfma_f32_16x16x32_bf16 v[72:75], v[152:155], v[238:241], 0
	v_mfma_f32_16x16x32_bf16 v[126:129], v[148:151], v[180:183], v[126:129]
	v_mfma_f32_16x16x32_bf16 v[122:125], v[156:159], v[180:183], v[122:125]
	v_mfma_f32_16x16x32_bf16 v[108:111], v[148:151], v[208:211], v[108:111]
	v_mfma_f32_16x16x32_bf16 v[104:107], v[156:159], v[208:211], v[104:107]
	v_mfma_f32_16x16x32_bf16 v[92:95], v[148:151], v[234:237], v[92:95]
	v_mfma_f32_16x16x32_bf16 v[88:91], v[156:159], v[234:237], v[88:91]
	v_mfma_f32_16x16x32_bf16 v[76:79], v[148:151], v[242:245], v[76:79]
	v_mfma_f32_16x16x32_bf16 v[72:75], v[156:159], v[242:245], v[72:75]
	s_setprio 0
	s_setprio 1
	v_mfma_f32_16x16x32_bf16 v[118:121], v[160:163], v[176:179], 0
	v_mfma_f32_16x16x32_bf16 v[114:117], v[168:171], v[176:179], 0
	v_mfma_f32_16x16x32_bf16 v[100:103], v[160:163], v[184:187], 0
	v_mfma_f32_16x16x32_bf16 v[96:99], v[168:171], v[184:187], 0
	v_mfma_f32_16x16x32_bf16 v[84:87], v[160:163], v[230:233], 0
	v_mfma_f32_16x16x32_bf16 v[80:83], v[168:171], v[230:233], 0
	v_mfma_f32_16x16x32_bf16 v[68:71], v[160:163], v[238:241], 0
	v_mfma_f32_16x16x32_bf16 v[64:67], v[168:171], v[238:241], 0
	v_mfma_f32_16x16x32_bf16 v[118:121], v[164:167], v[180:183], v[118:121]
	v_mfma_f32_16x16x32_bf16 v[114:117], v[172:175], v[180:183], v[114:117]
	v_mfma_f32_16x16x32_bf16 v[100:103], v[164:167], v[208:211], v[100:103]
	v_mfma_f32_16x16x32_bf16 v[96:99], v[172:175], v[208:211], v[96:99]
	v_mfma_f32_16x16x32_bf16 v[84:87], v[164:167], v[234:237], v[84:87]
	v_mfma_f32_16x16x32_bf16 v[80:83], v[172:175], v[234:237], v[80:83]
	v_mfma_f32_16x16x32_bf16 v[68:71], v[164:167], v[242:245], v[68:71]
	v_mfma_f32_16x16x32_bf16 v[64:67], v[172:175], v[242:245], v[64:67]
	s_setprio 0
	s_barrier
	s_add_i32 s55, s55, s41
	s_mov_b32 m0, s55
	ds_read_b128 v[176:179], v147 offset:16384
	ds_read_b128 v[180:183], v147 offset:17408
	ds_read_b128 v[184:187], v147 offset:18432
	ds_read_b128 v[208:211], v147 offset:19456
	ds_read_b128 v[230:233], v147 offset:20480
	ds_read_b128 v[234:237], v147 offset:21504
	ds_read_b128 v[238:241], v147 offset:22528
	ds_read_b128 v[242:245], v147 offset:23552
	global_load_lds_dwordx4 v112, s[28:29]
	s_add_i32 m0, s55, 0x2000
	s_add_u32 s56, s28, 0x40000
	v_lshl_add_u64 v[212:213], s[28:29], 0, v[134:135]
	s_addc_u32 s57, s29, 0
	s_add_i32 s55, s58, s41
	global_load_lds_dwordx4 v134, s[28:29]
	s_mov_b32 m0, s55
	v_lshl_add_u64 v[246:247], s[30:31], 0, v[132:133]
	global_load_lds_dwordx4 v112, s[56:57]
	s_add_i32 m0, s55, 0x2000
	s_nop 0
	global_load_lds_dwordx4 v134, s[56:57]
	v_lshl_add_u64 v[228:229], s[30:31], 0, v[130:131]
	s_mov_b32 m0, s42
	s_nop 0
	global_load_lds_dwordx4 v130, s[30:31]
	s_mov_b32 m0, s43
	s_nop 0
	global_load_lds_dwordx4 v132, s[30:31]
	s_waitcnt vmcnt(8)
	s_waitcnt lgkmcnt(0)
	s_barrier
	s_setprio 1
	s_waitcnt lgkmcnt(0)
	v_mfma_f32_16x16x32_bf16 v[60:63], v[140:143], v[176:179], 0
	v_mfma_f32_16x16x32_bf16 v[56:59], v[152:155], v[176:179], 0
	v_mfma_f32_16x16x32_bf16 v[44:47], v[140:143], v[184:187], 0
	v_mfma_f32_16x16x32_bf16 v[40:43], v[152:155], v[184:187], 0
	v_mfma_f32_16x16x32_bf16 v[28:31], v[140:143], v[230:233], 0
	v_mfma_f32_16x16x32_bf16 v[24:27], v[152:155], v[230:233], 0
	v_mfma_f32_16x16x32_bf16 v[12:15], v[140:143], v[238:241], 0
	v_mfma_f32_16x16x32_bf16 v[8:11], v[152:155], v[238:241], 0
	v_mfma_f32_16x16x32_bf16 v[60:63], v[148:151], v[180:183], v[60:63]
	v_mfma_f32_16x16x32_bf16 v[56:59], v[156:159], v[180:183], v[56:59]
	v_mfma_f32_16x16x32_bf16 v[44:47], v[148:151], v[208:211], v[44:47]
	v_mfma_f32_16x16x32_bf16 v[40:43], v[156:159], v[208:211], v[40:43]
	v_mfma_f32_16x16x32_bf16 v[28:31], v[148:151], v[234:237], v[28:31]
	v_mfma_f32_16x16x32_bf16 v[24:27], v[156:159], v[234:237], v[24:27]
	v_mfma_f32_16x16x32_bf16 v[12:15], v[148:151], v[242:245], v[12:15]
	v_mfma_f32_16x16x32_bf16 v[8:11], v[156:159], v[242:245], v[8:11]
	s_setprio 0
	s_setprio 1
	v_mfma_f32_16x16x32_bf16 v[52:55], v[160:163], v[176:179], 0
	v_mfma_f32_16x16x32_bf16 v[48:51], v[168:171], v[176:179], 0
	v_mfma_f32_16x16x32_bf16 v[36:39], v[160:163], v[184:187], 0
	v_mfma_f32_16x16x32_bf16 v[32:35], v[168:171], v[184:187], 0
	v_mfma_f32_16x16x32_bf16 v[20:23], v[160:163], v[230:233], 0
	v_mfma_f32_16x16x32_bf16 v[16:19], v[168:171], v[230:233], 0
	v_mfma_f32_16x16x32_bf16 v[4:7], v[160:163], v[238:241], 0
	v_mfma_f32_16x16x32_bf16 v[0:3], v[168:171], v[238:241], 0
	v_mfma_f32_16x16x32_bf16 v[52:55], v[164:167], v[180:183], v[52:55]
	v_mfma_f32_16x16x32_bf16 v[48:51], v[172:175], v[180:183], v[48:51]
	v_mfma_f32_16x16x32_bf16 v[36:39], v[164:167], v[208:211], v[36:39]
	v_mfma_f32_16x16x32_bf16 v[32:35], v[172:175], v[208:211], v[32:35]
	v_mfma_f32_16x16x32_bf16 v[20:23], v[164:167], v[234:237], v[20:23]
	v_mfma_f32_16x16x32_bf16 v[16:19], v[172:175], v[234:237], v[16:19]
	v_mfma_f32_16x16x32_bf16 v[4:7], v[164:167], v[242:245], v[4:7]
	v_mfma_f32_16x16x32_bf16 v[0:3], v[172:175], v[242:245], v[0:3]
	s_setprio 0
	s_barrier
	s_add_i32 s55, 0, 0x18000
	s_add_i32 s56, 0, 0x1c000
	v_add_u32_e32 v156, s55, v145
	v_add_u32_e32 v172, s56, v145
	ds_read_b128 v[140:143], v156
	ds_read_b128 v[148:151], v156 offset:1024
	ds_read_b128 v[152:155], v156 offset:2048
	ds_read_b128 v[156:159], v156 offset:3072
	ds_read_b128 v[160:163], v172
	ds_read_b128 v[164:167], v172 offset:1024
	ds_read_b128 v[168:171], v172 offset:2048
	ds_read_b128 v[172:175], v172 offset:3072
	s_add_u32 s30, s30, 0x80000
	s_addc_u32 s31, s31, 0
	s_mov_b32 m0, s44
	ds_read_b128 v[176:179], v147 offset:32768
	ds_read_b128 v[180:183], v147 offset:33792
	ds_read_b128 v[184:187], v147 offset:34816
	ds_read_b128 v[208:211], v147 offset:35840
	ds_read_b128 v[230:233], v147 offset:36864
	ds_read_b128 v[234:237], v147 offset:37888
	ds_read_b128 v[238:241], v147 offset:38912
	ds_read_b128 v[242:245], v147 offset:39936
	global_load_lds_dwordx4 v130, s[30:31]
	s_mov_b32 m0, s45
	s_nop 0
	global_load_lds_dwordx4 v132, s[30:31]
	s_waitcnt vmcnt(8)
	s_waitcnt lgkmcnt(0)
	s_barrier
	s_setprio 1
	s_waitcnt lgkmcnt(0)
	v_mfma_f32_16x16x32_bf16 v[126:129], v[140:143], v[176:179], v[126:129]
	v_mfma_f32_16x16x32_bf16 v[122:125], v[152:155], v[176:179], v[122:125]
	v_mfma_f32_16x16x32_bf16 v[108:111], v[140:143], v[184:187], v[108:111]
	v_mfma_f32_16x16x32_bf16 v[104:107], v[152:155], v[184:187], v[104:107]
	v_mfma_f32_16x16x32_bf16 v[92:95], v[140:143], v[230:233], v[92:95]
	v_mfma_f32_16x16x32_bf16 v[88:91], v[152:155], v[230:233], v[88:91]
	v_mfma_f32_16x16x32_bf16 v[76:79], v[140:143], v[238:241], v[76:79]
	v_mfma_f32_16x16x32_bf16 v[72:75], v[152:155], v[238:241], v[72:75]
	v_mfma_f32_16x16x32_bf16 v[126:129], v[148:151], v[180:183], v[126:129]
	v_mfma_f32_16x16x32_bf16 v[122:125], v[156:159], v[180:183], v[122:125]
	v_mfma_f32_16x16x32_bf16 v[108:111], v[148:151], v[208:211], v[108:111]
	v_mfma_f32_16x16x32_bf16 v[104:107], v[156:159], v[208:211], v[104:107]
	v_mfma_f32_16x16x32_bf16 v[92:95], v[148:151], v[234:237], v[92:95]
	v_mfma_f32_16x16x32_bf16 v[88:91], v[156:159], v[234:237], v[88:91]
	v_mfma_f32_16x16x32_bf16 v[76:79], v[148:151], v[242:245], v[76:79]
	v_mfma_f32_16x16x32_bf16 v[72:75], v[156:159], v[242:245], v[72:75]
	s_setprio 0
	s_setprio 1
	v_mfma_f32_16x16x32_bf16 v[118:121], v[160:163], v[176:179], v[118:121]
	v_mfma_f32_16x16x32_bf16 v[114:117], v[168:171], v[176:179], v[114:117]
	v_mfma_f32_16x16x32_bf16 v[100:103], v[160:163], v[184:187], v[100:103]
	v_mfma_f32_16x16x32_bf16 v[96:99], v[168:171], v[184:187], v[96:99]
	v_mfma_f32_16x16x32_bf16 v[84:87], v[160:163], v[230:233], v[84:87]
	v_mfma_f32_16x16x32_bf16 v[80:83], v[168:171], v[230:233], v[80:83]
	v_mfma_f32_16x16x32_bf16 v[68:71], v[160:163], v[238:241], v[68:71]
	v_mfma_f32_16x16x32_bf16 v[64:67], v[168:171], v[238:241], v[64:67]
	v_mfma_f32_16x16x32_bf16 v[118:121], v[164:167], v[180:183], v[118:121]
	v_mfma_f32_16x16x32_bf16 v[114:117], v[172:175], v[180:183], v[114:117]
	v_mfma_f32_16x16x32_bf16 v[100:103], v[164:167], v[208:211], v[100:103]
	v_mfma_f32_16x16x32_bf16 v[96:99], v[172:175], v[208:211], v[96:99]
	v_mfma_f32_16x16x32_bf16 v[84:87], v[164:167], v[234:237], v[84:87]
	v_mfma_f32_16x16x32_bf16 v[80:83], v[172:175], v[234:237], v[80:83]
	v_mfma_f32_16x16x32_bf16 v[68:71], v[164:167], v[242:245], v[68:71]
	v_mfma_f32_16x16x32_bf16 v[64:67], v[172:175], v[242:245], v[64:67]
	s_setprio 0
	s_barrier
	s_add_i32 s30, s55, s41
	s_mov_b32 m0, s30
	ds_read_b128 v[176:179], v147 offset:49152
	ds_read_b128 v[180:183], v147 offset:50176
	ds_read_b128 v[184:187], v147 offset:51200
	ds_read_b128 v[208:211], v147 offset:52224
	ds_read_b128 v[230:233], v147 offset:53248
	ds_read_b128 v[234:237], v147 offset:54272
	ds_read_b128 v[238:241], v147 offset:55296
	ds_read_b128 v[242:245], v147 offset:56320
	s_add_u32 s98, s28, 0x80
	s_addc_u32 s99, s29, 0
	global_load_lds_dwordx4 v112, s[98:99]
	s_add_i32 m0, s30, 0x2000
	s_add_u32 s28, s28, 0x40080
	v_lshl_add_u64 v[188:189], v[212:213], 0, s[96:97]
	s_addc_u32 s29, s29, 0
	s_add_i32 s30, s56, s41
	global_load_lds_dwordx4 v[188:189], off
	s_mov_b32 m0, s30
	s_nop 0
	global_load_lds_dwordx4 v112, s[28:29]
	s_add_i32 m0, s30, 0x2000
	s_nop 0
	global_load_lds_dwordx4 v134, s[28:29]
	v_lshl_add_u64 v[188:189], v[228:229], 0, s[96:97]
	s_mov_b32 m0, s47
	s_nop 0
	global_load_lds_dwordx4 v[188:189], off
	v_lshl_add_u64 v[188:189], v[246:247], 0, s[96:97]
	s_mov_b32 m0, s48
	s_nop 0
	global_load_lds_dwordx4 v[188:189], off
	s_waitcnt vmcnt(8)
	s_waitcnt lgkmcnt(0)
	s_barrier
	s_setprio 1
	s_waitcnt lgkmcnt(0)
	v_mfma_f32_16x16x32_bf16 v[60:63], v[140:143], v[176:179], v[60:63]
	v_mfma_f32_16x16x32_bf16 v[56:59], v[152:155], v[176:179], v[56:59]
	v_mfma_f32_16x16x32_bf16 v[44:47], v[140:143], v[184:187], v[44:47]
	v_mfma_f32_16x16x32_bf16 v[40:43], v[152:155], v[184:187], v[40:43]
	v_mfma_f32_16x16x32_bf16 v[28:31], v[140:143], v[230:233], v[28:31]
	v_mfma_f32_16x16x32_bf16 v[24:27], v[152:155], v[230:233], v[24:27]
	v_mfma_f32_16x16x32_bf16 v[12:15], v[140:143], v[238:241], v[12:15]
	v_mfma_f32_16x16x32_bf16 v[8:11], v[152:155], v[238:241], v[8:11]
	v_mfma_f32_16x16x32_bf16 v[60:63], v[148:151], v[180:183], v[60:63]
	v_mfma_f32_16x16x32_bf16 v[56:59], v[156:159], v[180:183], v[56:59]
	v_mfma_f32_16x16x32_bf16 v[44:47], v[148:151], v[208:211], v[44:47]
	v_mfma_f32_16x16x32_bf16 v[40:43], v[156:159], v[208:211], v[40:43]
	v_mfma_f32_16x16x32_bf16 v[28:31], v[148:151], v[234:237], v[28:31]
	v_mfma_f32_16x16x32_bf16 v[24:27], v[156:159], v[234:237], v[24:27]
	v_mfma_f32_16x16x32_bf16 v[12:15], v[148:151], v[242:245], v[12:15]
	v_mfma_f32_16x16x32_bf16 v[8:11], v[156:159], v[242:245], v[8:11]
	s_setprio 0
	s_setprio 1
	v_mfma_f32_16x16x32_bf16 v[52:55], v[160:163], v[176:179], v[52:55]
	v_mfma_f32_16x16x32_bf16 v[48:51], v[168:171], v[176:179], v[48:51]
	v_mfma_f32_16x16x32_bf16 v[36:39], v[160:163], v[184:187], v[36:39]
	v_mfma_f32_16x16x32_bf16 v[32:35], v[168:171], v[184:187], v[32:35]
	v_mfma_f32_16x16x32_bf16 v[20:23], v[160:163], v[230:233], v[20:23]
	v_mfma_f32_16x16x32_bf16 v[16:19], v[168:171], v[230:233], v[16:19]
	v_mfma_f32_16x16x32_bf16 v[4:7], v[160:163], v[238:241], v[4:7]
	v_mfma_f32_16x16x32_bf16 v[0:3], v[168:171], v[238:241], v[0:3]
	v_mfma_f32_16x16x32_bf16 v[52:55], v[164:167], v[180:183], v[52:55]
	v_mfma_f32_16x16x32_bf16 v[48:51], v[172:175], v[180:183], v[48:51]
	v_mfma_f32_16x16x32_bf16 v[36:39], v[164:167], v[208:211], v[36:39]
	v_mfma_f32_16x16x32_bf16 v[32:35], v[172:175], v[208:211], v[32:35]
	v_mfma_f32_16x16x32_bf16 v[20:23], v[164:167], v[234:237], v[20:23]
	v_mfma_f32_16x16x32_bf16 v[16:19], v[172:175], v[234:237], v[16:19]
	v_mfma_f32_16x16x32_bf16 v[4:7], v[164:167], v[242:245], v[4:7]
	v_mfma_f32_16x16x32_bf16 v[0:3], v[172:175], v[242:245], v[0:3]
	s_setprio 0
	s_barrier
	s_add_i32 s54, s54, 2
	s_add_u32 s52, s52, 0x100
	s_addc_u32 s53, s53, 0
	s_add_u32 s26, s26, 0x100
	s_addc_u32 s27, s27, 0
	s_cmp_gt_u32 s54, 13
	s_cbranch_scc0 .LBB0_758
	s_branch .Lpeel_exit_758
.LBB0_758:
	s_add_u32 s28, s26, 0xfff80080
	s_addc_u32 s29, s27, -1
	s_add_i32 s55, 0, 0x10000
	s_cmp_eq_u32 s54, 12
	s_cselect_b32 s31, s17, s29
	s_cselect_b32 s30, s23, s28
	s_cselect_b32 s29, s15, s53
	s_cselect_b32 s28, s25, s52
	s_add_i32 s58, 0, 0x14000
	v_add_u32_e32 v156, s55, v145
	v_add_u32_e32 v172, s58, v145
	ds_read_b128 v[140:143], v156
	ds_read_b128 v[148:151], v156 offset:1024
	ds_read_b128 v[152:155], v156 offset:2048
	ds_read_b128 v[156:159], v156 offset:3072
	ds_read_b128 v[160:163], v172
	ds_read_b128 v[164:167], v172 offset:1024
	ds_read_b128 v[168:171], v172 offset:2048
	ds_read_b128 v[172:175], v172 offset:3072
	s_add_i32 m0, s42, 0xc000
	ds_read_b128 v[176:179], v147
	ds_read_b128 v[180:183], v147 offset:1024
	ds_read_b128 v[184:187], v147 offset:2048
	ds_read_b128 v[208:211], v147 offset:3072
	ds_read_b128 v[230:233], v147 offset:4096
	ds_read_b128 v[234:237], v147 offset:5120
	ds_read_b128 v[238:241], v147 offset:6144
	ds_read_b128 v[242:245], v147 offset:7168
	global_load_lds_dwordx4 v138, s[26:27]
	s_add_i32 m0, s42, 0xe000
	s_nop 0
	global_load_lds_dwordx4 v136, s[26:27]
	s_waitcnt vmcnt(8)
	s_waitcnt lgkmcnt(0)
	s_barrier
	s_setprio 1
	s_waitcnt lgkmcnt(0)
	v_mfma_f32_16x16x32_bf16 v[126:129], v[140:143], v[176:179], v[126:129]
	v_mfma_f32_16x16x32_bf16 v[122:125], v[152:155], v[176:179], v[122:125]
	v_mfma_f32_16x16x32_bf16 v[108:111], v[140:143], v[184:187], v[108:111]
	v_mfma_f32_16x16x32_bf16 v[104:107], v[152:155], v[184:187], v[104:107]
	v_mfma_f32_16x16x32_bf16 v[92:95], v[140:143], v[230:233], v[92:95]
	v_mfma_f32_16x16x32_bf16 v[88:91], v[152:155], v[230:233], v[88:91]
	v_mfma_f32_16x16x32_bf16 v[76:79], v[140:143], v[238:241], v[76:79]
	v_mfma_f32_16x16x32_bf16 v[72:75], v[152:155], v[238:241], v[72:75]
	v_mfma_f32_16x16x32_bf16 v[126:129], v[148:151], v[180:183], v[126:129]
	v_mfma_f32_16x16x32_bf16 v[122:125], v[156:159], v[180:183], v[122:125]
	v_mfma_f32_16x16x32_bf16 v[108:111], v[148:151], v[208:211], v[108:111]
	v_mfma_f32_16x16x32_bf16 v[104:107], v[156:159], v[208:211], v[104:107]
	v_mfma_f32_16x16x32_bf16 v[92:95], v[148:151], v[234:237], v[92:95]
	v_mfma_f32_16x16x32_bf16 v[88:91], v[156:159], v[234:237], v[88:91]
	v_mfma_f32_16x16x32_bf16 v[76:79], v[148:151], v[242:245], v[76:79]
	v_mfma_f32_16x16x32_bf16 v[72:75], v[156:159], v[242:245], v[72:75]
	s_setprio 0
	s_setprio 1
	v_mfma_f32_16x16x32_bf16 v[118:121], v[160:163], v[176:179], v[118:121]
	v_mfma_f32_16x16x32_bf16 v[114:117], v[168:171], v[176:179], v[114:117]
	v_mfma_f32_16x16x32_bf16 v[100:103], v[160:163], v[184:187], v[100:103]
	v_mfma_f32_16x16x32_bf16 v[96:99], v[168:171], v[184:187], v[96:99]
	v_mfma_f32_16x16x32_bf16 v[84:87], v[160:163], v[230:233], v[84:87]
	v_mfma_f32_16x16x32_bf16 v[80:83], v[168:171], v[230:233], v[80:83]
	v_mfma_f32_16x16x32_bf16 v[68:71], v[160:163], v[238:241], v[68:71]
	v_mfma_f32_16x16x32_bf16 v[64:67], v[168:171], v[238:241], v[64:67]
	v_mfma_f32_16x16x32_bf16 v[118:121], v[164:167], v[180:183], v[118:121]
	v_mfma_f32_16x16x32_bf16 v[114:117], v[172:175], v[180:183], v[114:117]
	v_mfma_f32_16x16x32_bf16 v[100:103], v[164:167], v[208:211], v[100:103]
	v_mfma_f32_16x16x32_bf16 v[96:99], v[172:175], v[208:211], v[96:99]
	v_mfma_f32_16x16x32_bf16 v[84:87], v[164:167], v[234:237], v[84:87]
	v_mfma_f32_16x16x32_bf16 v[80:83], v[172:175], v[234:237], v[80:83]
	v_mfma_f32_16x16x32_bf16 v[68:71], v[164:167], v[242:245], v[68:71]
	v_mfma_f32_16x16x32_bf16 v[64:67], v[172:175], v[242:245], v[64:67]
	s_setprio 0
	s_barrier
	s_add_i32 s55, s55, s41
	s_mov_b32 m0, s55
	ds_read_b128 v[176:179], v147 offset:16384
	ds_read_b128 v[180:183], v147 offset:17408
	ds_read_b128 v[184:187], v147 offset:18432
	ds_read_b128 v[208:211], v147 offset:19456
	ds_read_b128 v[230:233], v147 offset:20480
	ds_read_b128 v[234:237], v147 offset:21504
	ds_read_b128 v[238:241], v147 offset:22528
	ds_read_b128 v[242:245], v147 offset:23552
	global_load_lds_dwordx4 v112, s[28:29]
	s_add_i32 m0, s55, 0x2000
	s_add_u32 s56, s28, 0x40000
	v_lshl_add_u64 v[212:213], s[28:29], 0, v[134:135]
	s_addc_u32 s57, s29, 0
	s_add_i32 s55, s58, s41
	global_load_lds_dwordx4 v134, s[28:29]
	s_mov_b32 m0, s55
	v_lshl_add_u64 v[246:247], s[30:31], 0, v[132:133]
	global_load_lds_dwordx4 v112, s[56:57]
	s_add_i32 m0, s55, 0x2000
	s_nop 0
	global_load_lds_dwordx4 v134, s[56:57]
	v_lshl_add_u64 v[228:229], s[30:31], 0, v[130:131]
	s_mov_b32 m0, s42
	s_nop 0
	global_load_lds_dwordx4 v130, s[30:31]
	s_mov_b32 m0, s43
	s_nop 0
	global_load_lds_dwordx4 v132, s[30:31]
	s_waitcnt vmcnt(8)
	s_waitcnt lgkmcnt(0)
	s_barrier
	s_setprio 1
	s_waitcnt lgkmcnt(0)
	v_mfma_f32_16x16x32_bf16 v[60:63], v[140:143], v[176:179], v[60:63]
	v_mfma_f32_16x16x32_bf16 v[56:59], v[152:155], v[176:179], v[56:59]
	v_mfma_f32_16x16x32_bf16 v[44:47], v[140:143], v[184:187], v[44:47]
	v_mfma_f32_16x16x32_bf16 v[40:43], v[152:155], v[184:187], v[40:43]
	v_mfma_f32_16x16x32_bf16 v[28:31], v[140:143], v[230:233], v[28:31]
	v_mfma_f32_16x16x32_bf16 v[24:27], v[152:155], v[230:233], v[24:27]
	v_mfma_f32_16x16x32_bf16 v[12:15], v[140:143], v[238:241], v[12:15]
	v_mfma_f32_16x16x32_bf16 v[8:11], v[152:155], v[238:241], v[8:11]
	v_mfma_f32_16x16x32_bf16 v[60:63], v[148:151], v[180:183], v[60:63]
	v_mfma_f32_16x16x32_bf16 v[56:59], v[156:159], v[180:183], v[56:59]
	v_mfma_f32_16x16x32_bf16 v[44:47], v[148:151], v[208:211], v[44:47]
	v_mfma_f32_16x16x32_bf16 v[40:43], v[156:159], v[208:211], v[40:43]
	v_mfma_f32_16x16x32_bf16 v[28:31], v[148:151], v[234:237], v[28:31]
	v_mfma_f32_16x16x32_bf16 v[24:27], v[156:159], v[234:237], v[24:27]
	v_mfma_f32_16x16x32_bf16 v[12:15], v[148:151], v[242:245], v[12:15]
	v_mfma_f32_16x16x32_bf16 v[8:11], v[156:159], v[242:245], v[8:11]
	s_setprio 0
	s_setprio 1
	v_mfma_f32_16x16x32_bf16 v[52:55], v[160:163], v[176:179], v[52:55]
	v_mfma_f32_16x16x32_bf16 v[48:51], v[168:171], v[176:179], v[48:51]
	v_mfma_f32_16x16x32_bf16 v[36:39], v[160:163], v[184:187], v[36:39]
	v_mfma_f32_16x16x32_bf16 v[32:35], v[168:171], v[184:187], v[32:35]
	v_mfma_f32_16x16x32_bf16 v[20:23], v[160:163], v[230:233], v[20:23]
	v_mfma_f32_16x16x32_bf16 v[16:19], v[168:171], v[230:233], v[16:19]
	v_mfma_f32_16x16x32_bf16 v[4:7], v[160:163], v[238:241], v[4:7]
	v_mfma_f32_16x16x32_bf16 v[0:3], v[168:171], v[238:241], v[0:3]
	v_mfma_f32_16x16x32_bf16 v[52:55], v[164:167], v[180:183], v[52:55]
	v_mfma_f32_16x16x32_bf16 v[48:51], v[172:175], v[180:183], v[48:51]
	v_mfma_f32_16x16x32_bf16 v[36:39], v[164:167], v[208:211], v[36:39]
	v_mfma_f32_16x16x32_bf16 v[32:35], v[172:175], v[208:211], v[32:35]
	v_mfma_f32_16x16x32_bf16 v[20:23], v[164:167], v[234:237], v[20:23]
	v_mfma_f32_16x16x32_bf16 v[16:19], v[172:175], v[234:237], v[16:19]
	v_mfma_f32_16x16x32_bf16 v[4:7], v[164:167], v[242:245], v[4:7]
	v_mfma_f32_16x16x32_bf16 v[0:3], v[172:175], v[242:245], v[0:3]
	s_setprio 0
	s_barrier
	s_add_i32 s55, 0, 0x18000
	s_add_i32 s56, 0, 0x1c000
	v_add_u32_e32 v156, s55, v145
	v_add_u32_e32 v172, s56, v145
	ds_read_b128 v[140:143], v156
	ds_read_b128 v[148:151], v156 offset:1024
	ds_read_b128 v[152:155], v156 offset:2048
	ds_read_b128 v[156:159], v156 offset:3072
	ds_read_b128 v[160:163], v172
	ds_read_b128 v[164:167], v172 offset:1024
	ds_read_b128 v[168:171], v172 offset:2048
	ds_read_b128 v[172:175], v172 offset:3072
	s_add_u32 s30, s30, 0x80000
	s_addc_u32 s31, s31, 0
	s_mov_b32 m0, s44
	ds_read_b128 v[176:179], v147 offset:32768
	ds_read_b128 v[180:183], v147 offset:33792
	ds_read_b128 v[184:187], v147 offset:34816
	ds_read_b128 v[208:211], v147 offset:35840
	ds_read_b128 v[230:233], v147 offset:36864
	ds_read_b128 v[234:237], v147 offset:37888
	ds_read_b128 v[238:241], v147 offset:38912
	ds_read_b128 v[242:245], v147 offset:39936
	global_load_lds_dwordx4 v130, s[30:31]
	s_mov_b32 m0, s45
	s_nop 0
	global_load_lds_dwordx4 v132, s[30:31]
	s_waitcnt vmcnt(8)
	s_waitcnt lgkmcnt(0)
	s_barrier
	s_setprio 1
	s_waitcnt lgkmcnt(0)
	v_mfma_f32_16x16x32_bf16 v[126:129], v[140:143], v[176:179], v[126:129]
	v_mfma_f32_16x16x32_bf16 v[122:125], v[152:155], v[176:179], v[122:125]
	v_mfma_f32_16x16x32_bf16 v[108:111], v[140:143], v[184:187], v[108:111]
	v_mfma_f32_16x16x32_bf16 v[104:107], v[152:155], v[184:187], v[104:107]
	v_mfma_f32_16x16x32_bf16 v[92:95], v[140:143], v[230:233], v[92:95]
	v_mfma_f32_16x16x32_bf16 v[88:91], v[152:155], v[230:233], v[88:91]
	v_mfma_f32_16x16x32_bf16 v[76:79], v[140:143], v[238:241], v[76:79]
	v_mfma_f32_16x16x32_bf16 v[72:75], v[152:155], v[238:241], v[72:75]
	v_mfma_f32_16x16x32_bf16 v[126:129], v[148:151], v[180:183], v[126:129]
	v_mfma_f32_16x16x32_bf16 v[122:125], v[156:159], v[180:183], v[122:125]
	v_mfma_f32_16x16x32_bf16 v[108:111], v[148:151], v[208:211], v[108:111]
	v_mfma_f32_16x16x32_bf16 v[104:107], v[156:159], v[208:211], v[104:107]
	v_mfma_f32_16x16x32_bf16 v[92:95], v[148:151], v[234:237], v[92:95]
	v_mfma_f32_16x16x32_bf16 v[88:91], v[156:159], v[234:237], v[88:91]
	v_mfma_f32_16x16x32_bf16 v[76:79], v[148:151], v[242:245], v[76:79]
	v_mfma_f32_16x16x32_bf16 v[72:75], v[156:159], v[242:245], v[72:75]
	s_setprio 0
	s_setprio 1
	v_mfma_f32_16x16x32_bf16 v[118:121], v[160:163], v[176:179], v[118:121]
	v_mfma_f32_16x16x32_bf16 v[114:117], v[168:171], v[176:179], v[114:117]
	v_mfma_f32_16x16x32_bf16 v[100:103], v[160:163], v[184:187], v[100:103]
	v_mfma_f32_16x16x32_bf16 v[96:99], v[168:171], v[184:187], v[96:99]
	v_mfma_f32_16x16x32_bf16 v[84:87], v[160:163], v[230:233], v[84:87]
	v_mfma_f32_16x16x32_bf16 v[80:83], v[168:171], v[230:233], v[80:83]
	v_mfma_f32_16x16x32_bf16 v[68:71], v[160:163], v[238:241], v[68:71]
	v_mfma_f32_16x16x32_bf16 v[64:67], v[168:171], v[238:241], v[64:67]
	v_mfma_f32_16x16x32_bf16 v[118:121], v[164:167], v[180:183], v[118:121]
	v_mfma_f32_16x16x32_bf16 v[114:117], v[172:175], v[180:183], v[114:117]
	v_mfma_f32_16x16x32_bf16 v[100:103], v[164:167], v[208:211], v[100:103]
	v_mfma_f32_16x16x32_bf16 v[96:99], v[172:175], v[208:211], v[96:99]
	v_mfma_f32_16x16x32_bf16 v[84:87], v[164:167], v[234:237], v[84:87]
	v_mfma_f32_16x16x32_bf16 v[80:83], v[172:175], v[234:237], v[80:83]
	v_mfma_f32_16x16x32_bf16 v[68:71], v[164:167], v[242:245], v[68:71]
	v_mfma_f32_16x16x32_bf16 v[64:67], v[172:175], v[242:245], v[64:67]
	s_setprio 0
	s_barrier
	s_add_i32 s30, s55, s41
	s_mov_b32 m0, s30
	ds_read_b128 v[176:179], v147 offset:49152
	ds_read_b128 v[180:183], v147 offset:50176
	ds_read_b128 v[184:187], v147 offset:51200
	ds_read_b128 v[208:211], v147 offset:52224
	ds_read_b128 v[230:233], v147 offset:53248
	ds_read_b128 v[234:237], v147 offset:54272
	ds_read_b128 v[238:241], v147 offset:55296
	ds_read_b128 v[242:245], v147 offset:56320
	s_add_u32 s98, s28, 0x80
	s_addc_u32 s99, s29, 0
	global_load_lds_dwordx4 v112, s[98:99]
	s_add_i32 m0, s30, 0x2000
	s_add_u32 s28, s28, 0x40080
	v_lshl_add_u64 v[188:189], v[212:213], 0, s[96:97]
	s_addc_u32 s29, s29, 0
	s_add_i32 s30, s56, s41
	global_load_lds_dwordx4 v[188:189], off
	s_mov_b32 m0, s30
	s_nop 0
	global_load_lds_dwordx4 v112, s[28:29]
	s_add_i32 m0, s30, 0x2000
	s_nop 0
	global_load_lds_dwordx4 v134, s[28:29]
	v_lshl_add_u64 v[188:189], v[228:229], 0, s[96:97]
	s_mov_b32 m0, s47
	s_nop 0
	global_load_lds_dwordx4 v[188:189], off
	v_lshl_add_u64 v[188:189], v[246:247], 0, s[96:97]
	s_mov_b32 m0, s48
	s_nop 0
	global_load_lds_dwordx4 v[188:189], off
	s_waitcnt vmcnt(8)
	s_waitcnt lgkmcnt(0)
	s_barrier
	s_setprio 1
	s_waitcnt lgkmcnt(0)
	v_mfma_f32_16x16x32_bf16 v[60:63], v[140:143], v[176:179], v[60:63]
	v_mfma_f32_16x16x32_bf16 v[56:59], v[152:155], v[176:179], v[56:59]
	v_mfma_f32_16x16x32_bf16 v[44:47], v[140:143], v[184:187], v[44:47]
	v_mfma_f32_16x16x32_bf16 v[40:43], v[152:155], v[184:187], v[40:43]
	v_mfma_f32_16x16x32_bf16 v[28:31], v[140:143], v[230:233], v[28:31]
	v_mfma_f32_16x16x32_bf16 v[24:27], v[152:155], v[230:233], v[24:27]
	v_mfma_f32_16x16x32_bf16 v[12:15], v[140:143], v[238:241], v[12:15]
	v_mfma_f32_16x16x32_bf16 v[8:11], v[152:155], v[238:241], v[8:11]
	v_mfma_f32_16x16x32_bf16 v[60:63], v[148:151], v[180:183], v[60:63]
	v_mfma_f32_16x16x32_bf16 v[56:59], v[156:159], v[180:183], v[56:59]
	v_mfma_f32_16x16x32_bf16 v[44:47], v[148:151], v[208:211], v[44:47]
	v_mfma_f32_16x16x32_bf16 v[40:43], v[156:159], v[208:211], v[40:43]
	v_mfma_f32_16x16x32_bf16 v[28:31], v[148:151], v[234:237], v[28:31]
	v_mfma_f32_16x16x32_bf16 v[24:27], v[156:159], v[234:237], v[24:27]
	v_mfma_f32_16x16x32_bf16 v[12:15], v[148:151], v[242:245], v[12:15]
	v_mfma_f32_16x16x32_bf16 v[8:11], v[156:159], v[242:245], v[8:11]
	s_setprio 0
	s_setprio 1
	v_mfma_f32_16x16x32_bf16 v[52:55], v[160:163], v[176:179], v[52:55]
	v_mfma_f32_16x16x32_bf16 v[48:51], v[168:171], v[176:179], v[48:51]
	v_mfma_f32_16x16x32_bf16 v[36:39], v[160:163], v[184:187], v[36:39]
	v_mfma_f32_16x16x32_bf16 v[32:35], v[168:171], v[184:187], v[32:35]
	v_mfma_f32_16x16x32_bf16 v[20:23], v[160:163], v[230:233], v[20:23]
	v_mfma_f32_16x16x32_bf16 v[16:19], v[168:171], v[230:233], v[16:19]
	v_mfma_f32_16x16x32_bf16 v[4:7], v[160:163], v[238:241], v[4:7]
	v_mfma_f32_16x16x32_bf16 v[0:3], v[168:171], v[238:241], v[0:3]
	v_mfma_f32_16x16x32_bf16 v[52:55], v[164:167], v[180:183], v[52:55]
	v_mfma_f32_16x16x32_bf16 v[48:51], v[172:175], v[180:183], v[48:51]
	v_mfma_f32_16x16x32_bf16 v[36:39], v[164:167], v[208:211], v[36:39]
	v_mfma_f32_16x16x32_bf16 v[32:35], v[172:175], v[208:211], v[32:35]
	v_mfma_f32_16x16x32_bf16 v[20:23], v[164:167], v[234:237], v[20:23]
	v_mfma_f32_16x16x32_bf16 v[16:19], v[172:175], v[234:237], v[16:19]
	v_mfma_f32_16x16x32_bf16 v[4:7], v[164:167], v[242:245], v[4:7]
	v_mfma_f32_16x16x32_bf16 v[0:3], v[172:175], v[242:245], v[0:3]
	s_setprio 0
	s_barrier
	s_add_i32 s54, s54, 2
	s_add_u32 s52, s52, 0x100
	s_addc_u32 s53, s53, 0
	s_add_u32 s26, s26, 0x100
	s_addc_u32 s27, s27, 0
	s_cmp_gt_u32 s54, 13
	s_cbranch_scc0 .LBB0_758

.LBB0_803:
	s_ashr_i32 s15, s14, 31
	s_lshl_b64 s[18:19], s[14:15], 20
	s_add_u32 s18, s38, s18
	s_addc_u32 s19, s39, s19
	s_and_b64 s[0:1], s[0:1], exec
	s_cselect_b32 s15, s19, s25
	s_cselect_b32 s21, s18, s24
	s_add_u32 s50, s24, 0x100
	s_addc_u32 s51, s25, 0
	s_mov_b32 s52, -2
	s_waitcnt lgkmcnt(0)
	s_add_u32 s0, s22, 0x100
	s_addc_u32 s1, s23, 0
	s_add_i32 s53, 0, 0x10000
	s_cmp_eq_u32 s52, 28
	s_cselect_b32 s27, s17, s1
	s_cselect_b32 s26, s16, s0
	s_cselect_b32 s25, s15, s51
	s_cselect_b32 s24, s21, s50
	s_add_i32 s54, 0, 0x14000
	v_add_u32_e32 v156, s53, v145
	v_add_u32_e32 v172, s54, v145
	ds_read_b128 v[140:143], v156
	ds_read_b128 v[148:151], v156 offset:1024
	ds_read_b128 v[152:155], v156 offset:2048
	ds_read_b128 v[156:159], v156 offset:3072
	ds_read_b128 v[160:163], v172
	ds_read_b128 v[164:167], v172 offset:1024
	ds_read_b128 v[168:171], v172 offset:2048
	ds_read_b128 v[172:175], v172 offset:3072
	s_add_i32 m0, s31, 0xc000
	ds_read_b128 v[176:179], v147
	ds_read_b128 v[180:183], v147 offset:1024
	ds_read_b128 v[184:187], v147 offset:2048
	ds_read_b128 v[208:211], v147 offset:3072
	ds_read_b128 v[230:233], v147 offset:4096
	ds_read_b128 v[234:237], v147 offset:5120
	ds_read_b128 v[238:241], v147 offset:6144
	ds_read_b128 v[242:245], v147 offset:7168
	global_load_lds_dwordx4 v138, s[22:23]
	s_add_i32 m0, s31, 0xe000
	s_nop 0
	global_load_lds_dwordx4 v136, s[22:23]
	s_waitcnt vmcnt(8)
	s_waitcnt lgkmcnt(0)
	s_barrier
	s_setprio 1
	s_waitcnt lgkmcnt(0)
	v_mfma_f32_16x16x32_bf16 v[126:129], v[140:143], v[176:179], 0
	v_mfma_f32_16x16x32_bf16 v[122:125], v[152:155], v[176:179], 0
	v_mfma_f32_16x16x32_bf16 v[108:111], v[140:143], v[184:187], 0
	v_mfma_f32_16x16x32_bf16 v[104:107], v[152:155], v[184:187], 0
	v_mfma_f32_16x16x32_bf16 v[92:95], v[140:143], v[230:233], 0
	v_mfma_f32_16x16x32_bf16 v[88:91], v[152:155], v[230:233], 0
	v_mfma_f32_16x16x32_bf16 v[76:79], v[140:143], v[238:241], 0
	v_mfma_f32_16x16x32_bf16 v[72:75], v[152:155], v[238:241], 0
	v_mfma_f32_16x16x32_bf16 v[126:129], v[148:151], v[180:183], v[126:129]
	v_mfma_f32_16x16x32_bf16 v[122:125], v[156:159], v[180:183], v[122:125]
	v_mfma_f32_16x16x32_bf16 v[108:111], v[148:151], v[208:211], v[108:111]
	v_mfma_f32_16x16x32_bf16 v[104:107], v[156:159], v[208:211], v[104:107]
	v_mfma_f32_16x16x32_bf16 v[92:95], v[148:151], v[234:237], v[92:95]
	v_mfma_f32_16x16x32_bf16 v[88:91], v[156:159], v[234:237], v[88:91]
	v_mfma_f32_16x16x32_bf16 v[76:79], v[148:151], v[242:245], v[76:79]
	v_mfma_f32_16x16x32_bf16 v[72:75], v[156:159], v[242:245], v[72:75]
	s_setprio 0
	s_setprio 1
	v_mfma_f32_16x16x32_bf16 v[118:121], v[160:163], v[176:179], 0
	v_mfma_f32_16x16x32_bf16 v[114:117], v[168:171], v[176:179], 0
	v_mfma_f32_16x16x32_bf16 v[100:103], v[160:163], v[184:187], 0
	v_mfma_f32_16x16x32_bf16 v[96:99], v[168:171], v[184:187], 0
	v_mfma_f32_16x16x32_bf16 v[84:87], v[160:163], v[230:233], 0
	v_mfma_f32_16x16x32_bf16 v[80:83], v[168:171], v[230:233], 0
	v_mfma_f32_16x16x32_bf16 v[68:71], v[160:163], v[238:241], 0
	v_mfma_f32_16x16x32_bf16 v[64:67], v[168:171], v[238:241], 0
	v_mfma_f32_16x16x32_bf16 v[118:121], v[164:167], v[180:183], v[118:121]
	v_mfma_f32_16x16x32_bf16 v[114:117], v[172:175], v[180:183], v[114:117]
	v_mfma_f32_16x16x32_bf16 v[100:103], v[164:167], v[208:211], v[100:103]
	v_mfma_f32_16x16x32_bf16 v[96:99], v[172:175], v[208:211], v[96:99]
	v_mfma_f32_16x16x32_bf16 v[84:87], v[164:167], v[234:237], v[84:87]
	v_mfma_f32_16x16x32_bf16 v[80:83], v[172:175], v[234:237], v[80:83]
	v_mfma_f32_16x16x32_bf16 v[68:71], v[164:167], v[242:245], v[68:71]
	v_mfma_f32_16x16x32_bf16 v[64:67], v[172:175], v[242:245], v[64:67]
	s_setprio 0
	s_barrier
	s_add_i32 s22, s53, s30
	s_mov_b32 m0, s22
	ds_read_b128 v[176:179], v147 offset:16384
	ds_read_b128 v[180:183], v147 offset:17408
	ds_read_b128 v[184:187], v147 offset:18432
	ds_read_b128 v[208:211], v147 offset:19456
	ds_read_b128 v[230:233], v147 offset:20480
	ds_read_b128 v[234:237], v147 offset:21504
	ds_read_b128 v[238:241], v147 offset:22528
	ds_read_b128 v[242:245], v147 offset:23552
	global_load_lds_dwordx4 v112, s[24:25]
	s_add_i32 m0, s22, 0x2000
	s_add_u32 s22, s24, 0x80000
	v_lshl_add_u64 v[212:213], s[24:25], 0, v[134:135]
	s_addc_u32 s23, s25, 0
	s_add_i32 s53, s54, s30
	global_load_lds_dwordx4 v134, s[24:25]
	s_mov_b32 m0, s53
	s_nop 0
	global_load_lds_dwordx4 v112, s[22:23]
	s_add_i32 m0, s53, 0x2000
	s_nop 0
	global_load_lds_dwordx4 v134, s[22:23]
	s_mov_b32 m0, s31
	s_nop 0
	global_load_lds_dwordx4 v130, s[26:27]
	s_mov_b32 m0, s35
	s_nop 0
	global_load_lds_dwordx4 v132, s[26:27]
	s_waitcnt vmcnt(8)
	s_waitcnt lgkmcnt(0)
	s_barrier
	s_setprio 1
	s_waitcnt lgkmcnt(0)
	v_mfma_f32_16x16x32_bf16 v[60:63], v[140:143], v[176:179], 0
	v_mfma_f32_16x16x32_bf16 v[56:59], v[152:155], v[176:179], 0
	v_mfma_f32_16x16x32_bf16 v[44:47], v[140:143], v[184:187], 0
	v_mfma_f32_16x16x32_bf16 v[40:43], v[152:155], v[184:187], 0
	v_mfma_f32_16x16x32_bf16 v[28:31], v[140:143], v[230:233], 0
	v_mfma_f32_16x16x32_bf16 v[24:27], v[152:155], v[230:233], 0
	v_mfma_f32_16x16x32_bf16 v[12:15], v[140:143], v[238:241], 0
	v_mfma_f32_16x16x32_bf16 v[8:11], v[152:155], v[238:241], 0
	v_mfma_f32_16x16x32_bf16 v[60:63], v[148:151], v[180:183], v[60:63]
	v_mfma_f32_16x16x32_bf16 v[56:59], v[156:159], v[180:183], v[56:59]
	v_mfma_f32_16x16x32_bf16 v[44:47], v[148:151], v[208:211], v[44:47]
	v_mfma_f32_16x16x32_bf16 v[40:43], v[156:159], v[208:211], v[40:43]
	v_mfma_f32_16x16x32_bf16 v[28:31], v[148:151], v[234:237], v[28:31]
	v_mfma_f32_16x16x32_bf16 v[24:27], v[156:159], v[234:237], v[24:27]
	v_mfma_f32_16x16x32_bf16 v[12:15], v[148:151], v[242:245], v[12:15]
	v_mfma_f32_16x16x32_bf16 v[8:11], v[156:159], v[242:245], v[8:11]
	s_setprio 0
	s_setprio 1
	v_mfma_f32_16x16x32_bf16 v[52:55], v[160:163], v[176:179], 0
	v_mfma_f32_16x16x32_bf16 v[48:51], v[168:171], v[176:179], 0
	v_mfma_f32_16x16x32_bf16 v[36:39], v[160:163], v[184:187], 0
	v_mfma_f32_16x16x32_bf16 v[32:35], v[168:171], v[184:187], 0
	v_mfma_f32_16x16x32_bf16 v[20:23], v[160:163], v[230:233], 0
	v_mfma_f32_16x16x32_bf16 v[16:19], v[168:171], v[230:233], 0
	v_mfma_f32_16x16x32_bf16 v[4:7], v[160:163], v[238:241], 0
	v_mfma_f32_16x16x32_bf16 v[0:3], v[168:171], v[238:241], 0
	v_mfma_f32_16x16x32_bf16 v[52:55], v[164:167], v[180:183], v[52:55]
	v_mfma_f32_16x16x32_bf16 v[48:51], v[172:175], v[180:183], v[48:51]
	v_mfma_f32_16x16x32_bf16 v[36:39], v[164:167], v[208:211], v[36:39]
	v_mfma_f32_16x16x32_bf16 v[32:35], v[172:175], v[208:211], v[32:35]
	v_mfma_f32_16x16x32_bf16 v[20:23], v[164:167], v[234:237], v[20:23]
	v_mfma_f32_16x16x32_bf16 v[16:19], v[172:175], v[234:237], v[16:19]
	v_mfma_f32_16x16x32_bf16 v[4:7], v[164:167], v[242:245], v[4:7]
	v_mfma_f32_16x16x32_bf16 v[0:3], v[172:175], v[242:245], v[0:3]
	s_setprio 0
	s_barrier
	s_add_i32 s53, 0, 0x18000
	s_add_i32 s54, 0, 0x1c000
	v_add_u32_e32 v156, s53, v145
	v_add_u32_e32 v172, s54, v145
	ds_read_b128 v[140:143], v156
	ds_read_b128 v[148:151], v156 offset:1024
	ds_read_b128 v[152:155], v156 offset:2048
	ds_read_b128 v[156:159], v156 offset:3072
	ds_read_b128 v[160:163], v172
	ds_read_b128 v[164:167], v172 offset:1024
	ds_read_b128 v[168:171], v172 offset:2048
	ds_read_b128 v[172:175], v172 offset:3072
	s_add_u32 s22, s26, 0x120000
	s_addc_u32 s23, s27, 0
	s_mov_b32 m0, s40
	ds_read_b128 v[176:179], v147 offset:32768
	ds_read_b128 v[180:183], v147 offset:33792
	ds_read_b128 v[184:187], v147 offset:34816
	ds_read_b128 v[208:211], v147 offset:35840
	ds_read_b128 v[230:233], v147 offset:36864
	ds_read_b128 v[234:237], v147 offset:37888
	ds_read_b128 v[238:241], v147 offset:38912
	ds_read_b128 v[242:245], v147 offset:39936
	global_load_lds_dwordx4 v130, s[22:23]
	s_mov_b32 m0, s41
	s_nop 0
	global_load_lds_dwordx4 v132, s[22:23]
	s_waitcnt vmcnt(8)
	s_waitcnt lgkmcnt(0)
	s_barrier
	s_setprio 1
	s_waitcnt lgkmcnt(0)
	v_mfma_f32_16x16x32_bf16 v[126:129], v[140:143], v[176:179], v[126:129]
	v_mfma_f32_16x16x32_bf16 v[122:125], v[152:155], v[176:179], v[122:125]
	v_mfma_f32_16x16x32_bf16 v[108:111], v[140:143], v[184:187], v[108:111]
	v_mfma_f32_16x16x32_bf16 v[104:107], v[152:155], v[184:187], v[104:107]
	v_mfma_f32_16x16x32_bf16 v[92:95], v[140:143], v[230:233], v[92:95]
	v_mfma_f32_16x16x32_bf16 v[88:91], v[152:155], v[230:233], v[88:91]
	v_mfma_f32_16x16x32_bf16 v[76:79], v[140:143], v[238:241], v[76:79]
	v_mfma_f32_16x16x32_bf16 v[72:75], v[152:155], v[238:241], v[72:75]
	v_mfma_f32_16x16x32_bf16 v[126:129], v[148:151], v[180:183], v[126:129]
	v_mfma_f32_16x16x32_bf16 v[122:125], v[156:159], v[180:183], v[122:125]
	v_mfma_f32_16x16x32_bf16 v[108:111], v[148:151], v[208:211], v[108:111]
	v_mfma_f32_16x16x32_bf16 v[104:107], v[156:159], v[208:211], v[104:107]
	v_mfma_f32_16x16x32_bf16 v[92:95], v[148:151], v[234:237], v[92:95]
	v_mfma_f32_16x16x32_bf16 v[88:91], v[156:159], v[234:237], v[88:91]
	v_mfma_f32_16x16x32_bf16 v[76:79], v[148:151], v[242:245], v[76:79]
	v_mfma_f32_16x16x32_bf16 v[72:75], v[156:159], v[242:245], v[72:75]
	s_setprio 0
	s_setprio 1
	v_mfma_f32_16x16x32_bf16 v[118:121], v[160:163], v[176:179], v[118:121]
	v_mfma_f32_16x16x32_bf16 v[114:117], v[168:171], v[176:179], v[114:117]
	v_mfma_f32_16x16x32_bf16 v[100:103], v[160:163], v[184:187], v[100:103]
	v_mfma_f32_16x16x32_bf16 v[96:99], v[168:171], v[184:187], v[96:99]
	v_mfma_f32_16x16x32_bf16 v[84:87], v[160:163], v[230:233], v[84:87]
	v_mfma_f32_16x16x32_bf16 v[80:83], v[168:171], v[230:233], v[80:83]
	v_mfma_f32_16x16x32_bf16 v[68:71], v[160:163], v[238:241], v[68:71]
	v_mfma_f32_16x16x32_bf16 v[64:67], v[168:171], v[238:241], v[64:67]
	v_mfma_f32_16x16x32_bf16 v[118:121], v[164:167], v[180:183], v[118:121]
	v_mfma_f32_16x16x32_bf16 v[114:117], v[172:175], v[180:183], v[114:117]
	v_mfma_f32_16x16x32_bf16 v[100:103], v[164:167], v[208:211], v[100:103]
	v_mfma_f32_16x16x32_bf16 v[96:99], v[172:175], v[208:211], v[96:99]
	v_mfma_f32_16x16x32_bf16 v[84:87], v[164:167], v[234:237], v[84:87]
	v_mfma_f32_16x16x32_bf16 v[80:83], v[172:175], v[234:237], v[80:83]
	v_mfma_f32_16x16x32_bf16 v[68:71], v[164:167], v[242:245], v[68:71]
	v_mfma_f32_16x16x32_bf16 v[64:67], v[172:175], v[242:245], v[64:67]
	s_setprio 0
	s_barrier
	s_add_i32 s22, s53, s30
	s_mov_b32 m0, s22
	ds_read_b128 v[176:179], v147 offset:49152
	ds_read_b128 v[180:183], v147 offset:50176
	ds_read_b128 v[184:187], v147 offset:51200
	ds_read_b128 v[208:211], v147 offset:52224
	ds_read_b128 v[230:233], v147 offset:53248
	ds_read_b128 v[234:237], v147 offset:54272
	ds_read_b128 v[238:241], v147 offset:55296
	ds_read_b128 v[242:245], v147 offset:56320
	s_add_u32 s98, s24, 0x80
	s_addc_u32 s99, s25, 0
	global_load_lds_dwordx4 v112, s[98:99]
	s_add_i32 m0, s22, 0x2000
	s_add_u32 s22, s24, 0x80080
	v_lshl_add_u64 v[188:189], v[212:213], 0, s[96:97]
	s_addc_u32 s23, s25, 0
	s_add_i32 s24, s54, s30
	global_load_lds_dwordx4 v[188:189], off
	s_mov_b32 m0, s24
	s_nop 0
	global_load_lds_dwordx4 v112, s[22:23]
	s_add_i32 m0, s24, 0x2000
	s_nop 0
	global_load_lds_dwordx4 v134, s[22:23]
	s_mov_b32 m0, s43
	s_nop 0
	s_add_u32 s98, s26, 0x80
	s_addc_u32 s99, s27, 0
	global_load_lds_dwordx4 v130, s[98:99]
	s_mov_b32 m0, s44
	s_nop 0
	s_add_u32 s98, s26, 0x80
	s_addc_u32 s99, s27, 0
	global_load_lds_dwordx4 v132, s[98:99]
	s_waitcnt vmcnt(8)
	s_waitcnt lgkmcnt(0)
	s_barrier
	s_setprio 1
	s_waitcnt lgkmcnt(0)
	v_mfma_f32_16x16x32_bf16 v[60:63], v[140:143], v[176:179], v[60:63]
	v_mfma_f32_16x16x32_bf16 v[56:59], v[152:155], v[176:179], v[56:59]
	v_mfma_f32_16x16x32_bf16 v[44:47], v[140:143], v[184:187], v[44:47]
	v_mfma_f32_16x16x32_bf16 v[40:43], v[152:155], v[184:187], v[40:43]
	v_mfma_f32_16x16x32_bf16 v[28:31], v[140:143], v[230:233], v[28:31]
	v_mfma_f32_16x16x32_bf16 v[24:27], v[152:155], v[230:233], v[24:27]
	v_mfma_f32_16x16x32_bf16 v[12:15], v[140:143], v[238:241], v[12:15]
	v_mfma_f32_16x16x32_bf16 v[8:11], v[152:155], v[238:241], v[8:11]
	v_mfma_f32_16x16x32_bf16 v[60:63], v[148:151], v[180:183], v[60:63]
	v_mfma_f32_16x16x32_bf16 v[56:59], v[156:159], v[180:183], v[56:59]
	v_mfma_f32_16x16x32_bf16 v[44:47], v[148:151], v[208:211], v[44:47]
	v_mfma_f32_16x16x32_bf16 v[40:43], v[156:159], v[208:211], v[40:43]
	v_mfma_f32_16x16x32_bf16 v[28:31], v[148:151], v[234:237], v[28:31]
	v_mfma_f32_16x16x32_bf16 v[24:27], v[156:159], v[234:237], v[24:27]
	v_mfma_f32_16x16x32_bf16 v[12:15], v[148:151], v[242:245], v[12:15]
	v_mfma_f32_16x16x32_bf16 v[8:11], v[156:159], v[242:245], v[8:11]
	s_setprio 0
	s_setprio 1
	v_mfma_f32_16x16x32_bf16 v[52:55], v[160:163], v[176:179], v[52:55]
	v_mfma_f32_16x16x32_bf16 v[48:51], v[168:171], v[176:179], v[48:51]
	v_mfma_f32_16x16x32_bf16 v[36:39], v[160:163], v[184:187], v[36:39]
	v_mfma_f32_16x16x32_bf16 v[32:35], v[168:171], v[184:187], v[32:35]
	v_mfma_f32_16x16x32_bf16 v[20:23], v[160:163], v[230:233], v[20:23]
	v_mfma_f32_16x16x32_bf16 v[16:19], v[168:171], v[230:233], v[16:19]
	v_mfma_f32_16x16x32_bf16 v[4:7], v[160:163], v[238:241], v[4:7]
	v_mfma_f32_16x16x32_bf16 v[0:3], v[168:171], v[238:241], v[0:3]
	v_mfma_f32_16x16x32_bf16 v[52:55], v[164:167], v[180:183], v[52:55]
	v_mfma_f32_16x16x32_bf16 v[48:51], v[172:175], v[180:183], v[48:51]
	v_mfma_f32_16x16x32_bf16 v[36:39], v[164:167], v[208:211], v[36:39]
	v_mfma_f32_16x16x32_bf16 v[32:35], v[172:175], v[208:211], v[32:35]
	v_mfma_f32_16x16x32_bf16 v[20:23], v[164:167], v[234:237], v[20:23]
	v_mfma_f32_16x16x32_bf16 v[16:19], v[172:175], v[234:237], v[16:19]
	v_mfma_f32_16x16x32_bf16 v[4:7], v[164:167], v[242:245], v[4:7]
	v_mfma_f32_16x16x32_bf16 v[0:3], v[172:175], v[242:245], v[0:3]
	s_setprio 0
	s_barrier
	s_add_i32 s52, s52, 2
	s_add_u32 s50, s50, 0x100
	s_addc_u32 s51, s51, 0
	s_cmp_gt_u32 s52, 29
	s_mov_b64 s[22:23], s[0:1]
	s_cbranch_scc0 .LBB0_804
	s_branch .Lpeel_exit_804
.LBB0_804:
	s_add_u32 s0, s22, 0x100
	s_addc_u32 s1, s23, 0
	s_add_i32 s53, 0, 0x10000
	s_cmp_eq_u32 s52, 28
	s_cselect_b32 s27, s17, s1
	s_cselect_b32 s26, s16, s0
	s_cselect_b32 s25, s15, s51
	s_cselect_b32 s24, s21, s50
	s_add_i32 s54, 0, 0x14000
	v_add_u32_e32 v156, s53, v145
	v_add_u32_e32 v172, s54, v145
	ds_read_b128 v[140:143], v156
	ds_read_b128 v[148:151], v156 offset:1024
	ds_read_b128 v[152:155], v156 offset:2048
	ds_read_b128 v[156:159], v156 offset:3072
	ds_read_b128 v[160:163], v172
	ds_read_b128 v[164:167], v172 offset:1024
	ds_read_b128 v[168:171], v172 offset:2048
	ds_read_b128 v[172:175], v172 offset:3072
	s_add_i32 m0, s31, 0xc000
	ds_read_b128 v[176:179], v147
	ds_read_b128 v[180:183], v147 offset:1024
	ds_read_b128 v[184:187], v147 offset:2048
	ds_read_b128 v[208:211], v147 offset:3072
	ds_read_b128 v[230:233], v147 offset:4096
	ds_read_b128 v[234:237], v147 offset:5120
	ds_read_b128 v[238:241], v147 offset:6144
	ds_read_b128 v[242:245], v147 offset:7168
	global_load_lds_dwordx4 v138, s[22:23]
	s_add_i32 m0, s31, 0xe000
	s_nop 0
	global_load_lds_dwordx4 v136, s[22:23]
	s_waitcnt vmcnt(8)
	s_waitcnt lgkmcnt(0)
	s_barrier
	s_setprio 1
	s_waitcnt lgkmcnt(0)
	v_mfma_f32_16x16x32_bf16 v[126:129], v[140:143], v[176:179], v[126:129]
	v_mfma_f32_16x16x32_bf16 v[122:125], v[152:155], v[176:179], v[122:125]
	v_mfma_f32_16x16x32_bf16 v[108:111], v[140:143], v[184:187], v[108:111]
	v_mfma_f32_16x16x32_bf16 v[104:107], v[152:155], v[184:187], v[104:107]
	v_mfma_f32_16x16x32_bf16 v[92:95], v[140:143], v[230:233], v[92:95]
	v_mfma_f32_16x16x32_bf16 v[88:91], v[152:155], v[230:233], v[88:91]
	v_mfma_f32_16x16x32_bf16 v[76:79], v[140:143], v[238:241], v[76:79]
	v_mfma_f32_16x16x32_bf16 v[72:75], v[152:155], v[238:241], v[72:75]
	v_mfma_f32_16x16x32_bf16 v[126:129], v[148:151], v[180:183], v[126:129]
	v_mfma_f32_16x16x32_bf16 v[122:125], v[156:159], v[180:183], v[122:125]
	v_mfma_f32_16x16x32_bf16 v[108:111], v[148:151], v[208:211], v[108:111]
	v_mfma_f32_16x16x32_bf16 v[104:107], v[156:159], v[208:211], v[104:107]
	v_mfma_f32_16x16x32_bf16 v[92:95], v[148:151], v[234:237], v[92:95]
	v_mfma_f32_16x16x32_bf16 v[88:91], v[156:159], v[234:237], v[88:91]
	v_mfma_f32_16x16x32_bf16 v[76:79], v[148:151], v[242:245], v[76:79]
	v_mfma_f32_16x16x32_bf16 v[72:75], v[156:159], v[242:245], v[72:75]
	s_setprio 0
	s_setprio 1
	v_mfma_f32_16x16x32_bf16 v[118:121], v[160:163], v[176:179], v[118:121]
	v_mfma_f32_16x16x32_bf16 v[114:117], v[168:171], v[176:179], v[114:117]
	v_mfma_f32_16x16x32_bf16 v[100:103], v[160:163], v[184:187], v[100:103]
	v_mfma_f32_16x16x32_bf16 v[96:99], v[168:171], v[184:187], v[96:99]
	v_mfma_f32_16x16x32_bf16 v[84:87], v[160:163], v[230:233], v[84:87]
	v_mfma_f32_16x16x32_bf16 v[80:83], v[168:171], v[230:233], v[80:83]
	v_mfma_f32_16x16x32_bf16 v[68:71], v[160:163], v[238:241], v[68:71]
	v_mfma_f32_16x16x32_bf16 v[64:67], v[168:171], v[238:241], v[64:67]
	v_mfma_f32_16x16x32_bf16 v[118:121], v[164:167], v[180:183], v[118:121]
	v_mfma_f32_16x16x32_bf16 v[114:117], v[172:175], v[180:183], v[114:117]
	v_mfma_f32_16x16x32_bf16 v[100:103], v[164:167], v[208:211], v[100:103]
	v_mfma_f32_16x16x32_bf16 v[96:99], v[172:175], v[208:211], v[96:99]
	v_mfma_f32_16x16x32_bf16 v[84:87], v[164:167], v[234:237], v[84:87]
	v_mfma_f32_16x16x32_bf16 v[80:83], v[172:175], v[234:237], v[80:83]
	v_mfma_f32_16x16x32_bf16 v[68:71], v[164:167], v[242:245], v[68:71]
	v_mfma_f32_16x16x32_bf16 v[64:67], v[172:175], v[242:245], v[64:67]
	s_setprio 0
	s_barrier
	s_add_i32 s22, s53, s30
	s_mov_b32 m0, s22
	ds_read_b128 v[176:179], v147 offset:16384
	ds_read_b128 v[180:183], v147 offset:17408
	ds_read_b128 v[184:187], v147 offset:18432
	ds_read_b128 v[208:211], v147 offset:19456
	ds_read_b128 v[230:233], v147 offset:20480
	ds_read_b128 v[234:237], v147 offset:21504
	ds_read_b128 v[238:241], v147 offset:22528
	ds_read_b128 v[242:245], v147 offset:23552
	global_load_lds_dwordx4 v112, s[24:25]
	s_add_i32 m0, s22, 0x2000
	s_add_u32 s22, s24, 0x80000
	v_lshl_add_u64 v[212:213], s[24:25], 0, v[134:135]
	s_addc_u32 s23, s25, 0
	s_add_i32 s53, s54, s30
	global_load_lds_dwordx4 v134, s[24:25]
	s_mov_b32 m0, s53
	s_nop 0
	global_load_lds_dwordx4 v112, s[22:23]
	s_add_i32 m0, s53, 0x2000
	s_nop 0
	global_load_lds_dwordx4 v134, s[22:23]
	s_mov_b32 m0, s31
	s_nop 0
	global_load_lds_dwordx4 v130, s[26:27]
	s_mov_b32 m0, s35
	s_nop 0
	global_load_lds_dwordx4 v132, s[26:27]
	s_waitcnt vmcnt(8)
	s_waitcnt lgkmcnt(0)
	s_barrier
	s_setprio 1
	s_waitcnt lgkmcnt(0)
	v_mfma_f32_16x16x32_bf16 v[60:63], v[140:143], v[176:179], v[60:63]
	v_mfma_f32_16x16x32_bf16 v[56:59], v[152:155], v[176:179], v[56:59]
	v_mfma_f32_16x16x32_bf16 v[44:47], v[140:143], v[184:187], v[44:47]
	v_mfma_f32_16x16x32_bf16 v[40:43], v[152:155], v[184:187], v[40:43]
	v_mfma_f32_16x16x32_bf16 v[28:31], v[140:143], v[230:233], v[28:31]
	v_mfma_f32_16x16x32_bf16 v[24:27], v[152:155], v[230:233], v[24:27]
	v_mfma_f32_16x16x32_bf16 v[12:15], v[140:143], v[238:241], v[12:15]
	v_mfma_f32_16x16x32_bf16 v[8:11], v[152:155], v[238:241], v[8:11]
	v_mfma_f32_16x16x32_bf16 v[60:63], v[148:151], v[180:183], v[60:63]
	v_mfma_f32_16x16x32_bf16 v[56:59], v[156:159], v[180:183], v[56:59]
	v_mfma_f32_16x16x32_bf16 v[44:47], v[148:151], v[208:211], v[44:47]
	v_mfma_f32_16x16x32_bf16 v[40:43], v[156:159], v[208:211], v[40:43]
	v_mfma_f32_16x16x32_bf16 v[28:31], v[148:151], v[234:237], v[28:31]
	v_mfma_f32_16x16x32_bf16 v[24:27], v[156:159], v[234:237], v[24:27]
	v_mfma_f32_16x16x32_bf16 v[12:15], v[148:151], v[242:245], v[12:15]
	v_mfma_f32_16x16x32_bf16 v[8:11], v[156:159], v[242:245], v[8:11]
	s_setprio 0
	s_setprio 1
	v_mfma_f32_16x16x32_bf16 v[52:55], v[160:163], v[176:179], v[52:55]
	v_mfma_f32_16x16x32_bf16 v[48:51], v[168:171], v[176:179], v[48:51]
	v_mfma_f32_16x16x32_bf16 v[36:39], v[160:163], v[184:187], v[36:39]
	v_mfma_f32_16x16x32_bf16 v[32:35], v[168:171], v[184:187], v[32:35]
	v_mfma_f32_16x16x32_bf16 v[20:23], v[160:163], v[230:233], v[20:23]
	v_mfma_f32_16x16x32_bf16 v[16:19], v[168:171], v[230:233], v[16:19]
	v_mfma_f32_16x16x32_bf16 v[4:7], v[160:163], v[238:241], v[4:7]
	v_mfma_f32_16x16x32_bf16 v[0:3], v[168:171], v[238:241], v[0:3]
	v_mfma_f32_16x16x32_bf16 v[52:55], v[164:167], v[180:183], v[52:55]
	v_mfma_f32_16x16x32_bf16 v[48:51], v[172:175], v[180:183], v[48:51]
	v_mfma_f32_16x16x32_bf16 v[36:39], v[164:167], v[208:211], v[36:39]
	v_mfma_f32_16x16x32_bf16 v[32:35], v[172:175], v[208:211], v[32:35]
	v_mfma_f32_16x16x32_bf16 v[20:23], v[164:167], v[234:237], v[20:23]
	v_mfma_f32_16x16x32_bf16 v[16:19], v[172:175], v[234:237], v[16:19]
	v_mfma_f32_16x16x32_bf16 v[4:7], v[164:167], v[242:245], v[4:7]
	v_mfma_f32_16x16x32_bf16 v[0:3], v[172:175], v[242:245], v[0:3]
	s_setprio 0
	s_barrier
	s_add_i32 s53, 0, 0x18000
	s_add_i32 s54, 0, 0x1c000
	v_add_u32_e32 v156, s53, v145
	v_add_u32_e32 v172, s54, v145
	ds_read_b128 v[140:143], v156
	ds_read_b128 v[148:151], v156 offset:1024
	ds_read_b128 v[152:155], v156 offset:2048
	ds_read_b128 v[156:159], v156 offset:3072
	ds_read_b128 v[160:163], v172
	ds_read_b128 v[164:167], v172 offset:1024
	ds_read_b128 v[168:171], v172 offset:2048
	ds_read_b128 v[172:175], v172 offset:3072
	s_add_u32 s22, s26, 0x120000
	s_addc_u32 s23, s27, 0
	s_mov_b32 m0, s40
	ds_read_b128 v[176:179], v147 offset:32768
	ds_read_b128 v[180:183], v147 offset:33792
	ds_read_b128 v[184:187], v147 offset:34816
	ds_read_b128 v[208:211], v147 offset:35840
	ds_read_b128 v[230:233], v147 offset:36864
	ds_read_b128 v[234:237], v147 offset:37888
	ds_read_b128 v[238:241], v147 offset:38912
	ds_read_b128 v[242:245], v147 offset:39936
	global_load_lds_dwordx4 v130, s[22:23]
	s_mov_b32 m0, s41
	s_nop 0
	global_load_lds_dwordx4 v132, s[22:23]
	s_waitcnt vmcnt(8)
	s_waitcnt lgkmcnt(0)
	s_barrier
	s_setprio 1
	s_waitcnt lgkmcnt(0)
	v_mfma_f32_16x16x32_bf16 v[126:129], v[140:143], v[176:179], v[126:129]
	v_mfma_f32_16x16x32_bf16 v[122:125], v[152:155], v[176:179], v[122:125]
	v_mfma_f32_16x16x32_bf16 v[108:111], v[140:143], v[184:187], v[108:111]
	v_mfma_f32_16x16x32_bf16 v[104:107], v[152:155], v[184:187], v[104:107]
	v_mfma_f32_16x16x32_bf16 v[92:95], v[140:143], v[230:233], v[92:95]
	v_mfma_f32_16x16x32_bf16 v[88:91], v[152:155], v[230:233], v[88:91]
	v_mfma_f32_16x16x32_bf16 v[76:79], v[140:143], v[238:241], v[76:79]
	v_mfma_f32_16x16x32_bf16 v[72:75], v[152:155], v[238:241], v[72:75]
	v_mfma_f32_16x16x32_bf16 v[126:129], v[148:151], v[180:183], v[126:129]
	v_mfma_f32_16x16x32_bf16 v[122:125], v[156:159], v[180:183], v[122:125]
	v_mfma_f32_16x16x32_bf16 v[108:111], v[148:151], v[208:211], v[108:111]
	v_mfma_f32_16x16x32_bf16 v[104:107], v[156:159], v[208:211], v[104:107]
	v_mfma_f32_16x16x32_bf16 v[92:95], v[148:151], v[234:237], v[92:95]
	v_mfma_f32_16x16x32_bf16 v[88:91], v[156:159], v[234:237], v[88:91]
	v_mfma_f32_16x16x32_bf16 v[76:79], v[148:151], v[242:245], v[76:79]
	v_mfma_f32_16x16x32_bf16 v[72:75], v[156:159], v[242:245], v[72:75]
	s_setprio 0
	s_setprio 1
	v_mfma_f32_16x16x32_bf16 v[118:121], v[160:163], v[176:179], v[118:121]
	v_mfma_f32_16x16x32_bf16 v[114:117], v[168:171], v[176:179], v[114:117]
	v_mfma_f32_16x16x32_bf16 v[100:103], v[160:163], v[184:187], v[100:103]
	v_mfma_f32_16x16x32_bf16 v[96:99], v[168:171], v[184:187], v[96:99]
	v_mfma_f32_16x16x32_bf16 v[84:87], v[160:163], v[230:233], v[84:87]
	v_mfma_f32_16x16x32_bf16 v[80:83], v[168:171], v[230:233], v[80:83]
	v_mfma_f32_16x16x32_bf16 v[68:71], v[160:163], v[238:241], v[68:71]
	v_mfma_f32_16x16x32_bf16 v[64:67], v[168:171], v[238:241], v[64:67]
	v_mfma_f32_16x16x32_bf16 v[118:121], v[164:167], v[180:183], v[118:121]
	v_mfma_f32_16x16x32_bf16 v[114:117], v[172:175], v[180:183], v[114:117]
	v_mfma_f32_16x16x32_bf16 v[100:103], v[164:167], v[208:211], v[100:103]
	v_mfma_f32_16x16x32_bf16 v[96:99], v[172:175], v[208:211], v[96:99]
	v_mfma_f32_16x16x32_bf16 v[84:87], v[164:167], v[234:237], v[84:87]
	v_mfma_f32_16x16x32_bf16 v[80:83], v[172:175], v[234:237], v[80:83]
	v_mfma_f32_16x16x32_bf16 v[68:71], v[164:167], v[242:245], v[68:71]
	v_mfma_f32_16x16x32_bf16 v[64:67], v[172:175], v[242:245], v[64:67]
	s_setprio 0
	s_barrier
	s_add_i32 s22, s53, s30
	s_mov_b32 m0, s22
	ds_read_b128 v[176:179], v147 offset:49152
	ds_read_b128 v[180:183], v147 offset:50176
	ds_read_b128 v[184:187], v147 offset:51200
	ds_read_b128 v[208:211], v147 offset:52224
	ds_read_b128 v[230:233], v147 offset:53248
	ds_read_b128 v[234:237], v147 offset:54272
	ds_read_b128 v[238:241], v147 offset:55296
	ds_read_b128 v[242:245], v147 offset:56320
	s_add_u32 s98, s24, 0x80
	s_addc_u32 s99, s25, 0
	global_load_lds_dwordx4 v112, s[98:99]
	s_add_i32 m0, s22, 0x2000
	s_add_u32 s22, s24, 0x80080
	v_lshl_add_u64 v[188:189], v[212:213], 0, s[96:97]
	s_addc_u32 s23, s25, 0
	s_add_i32 s24, s54, s30
	global_load_lds_dwordx4 v[188:189], off
	s_mov_b32 m0, s24
	s_nop 0
	global_load_lds_dwordx4 v112, s[22:23]
	s_add_i32 m0, s24, 0x2000
	s_nop 0
	global_load_lds_dwordx4 v134, s[22:23]
	s_mov_b32 m0, s43
	s_nop 0
	s_add_u32 s98, s26, 0x80
	s_addc_u32 s99, s27, 0
	global_load_lds_dwordx4 v130, s[98:99]
	s_mov_b32 m0, s44
	s_nop 0
	s_add_u32 s98, s26, 0x80
	s_addc_u32 s99, s27, 0
	global_load_lds_dwordx4 v132, s[98:99]
	s_waitcnt vmcnt(8)
	s_waitcnt lgkmcnt(0)
	s_barrier
	s_setprio 1
	s_waitcnt lgkmcnt(0)
	v_mfma_f32_16x16x32_bf16 v[60:63], v[140:143], v[176:179], v[60:63]
	v_mfma_f32_16x16x32_bf16 v[56:59], v[152:155], v[176:179], v[56:59]
	v_mfma_f32_16x16x32_bf16 v[44:47], v[140:143], v[184:187], v[44:47]
	v_mfma_f32_16x16x32_bf16 v[40:43], v[152:155], v[184:187], v[40:43]
	v_mfma_f32_16x16x32_bf16 v[28:31], v[140:143], v[230:233], v[28:31]
	v_mfma_f32_16x16x32_bf16 v[24:27], v[152:155], v[230:233], v[24:27]
	v_mfma_f32_16x16x32_bf16 v[12:15], v[140:143], v[238:241], v[12:15]
	v_mfma_f32_16x16x32_bf16 v[8:11], v[152:155], v[238:241], v[8:11]
	v_mfma_f32_16x16x32_bf16 v[60:63], v[148:151], v[180:183], v[60:63]
	v_mfma_f32_16x16x32_bf16 v[56:59], v[156:159], v[180:183], v[56:59]
	v_mfma_f32_16x16x32_bf16 v[44:47], v[148:151], v[208:211], v[44:47]
	v_mfma_f32_16x16x32_bf16 v[40:43], v[156:159], v[208:211], v[40:43]
	v_mfma_f32_16x16x32_bf16 v[28:31], v[148:151], v[234:237], v[28:31]
	v_mfma_f32_16x16x32_bf16 v[24:27], v[156:159], v[234:237], v[24:27]
	v_mfma_f32_16x16x32_bf16 v[12:15], v[148:151], v[242:245], v[12:15]
	v_mfma_f32_16x16x32_bf16 v[8:11], v[156:159], v[242:245], v[8:11]
	s_setprio 0
	s_setprio 1
	v_mfma_f32_16x16x32_bf16 v[52:55], v[160:163], v[176:179], v[52:55]
	v_mfma_f32_16x16x32_bf16 v[48:51], v[168:171], v[176:179], v[48:51]
	v_mfma_f32_16x16x32_bf16 v[36:39], v[160:163], v[184:187], v[36:39]
	v_mfma_f32_16x16x32_bf16 v[32:35], v[168:171], v[184:187], v[32:35]
	v_mfma_f32_16x16x32_bf16 v[20:23], v[160:163], v[230:233], v[20:23]
	v_mfma_f32_16x16x32_bf16 v[16:19], v[168:171], v[230:233], v[16:19]
	v_mfma_f32_16x16x32_bf16 v[4:7], v[160:163], v[238:241], v[4:7]
	v_mfma_f32_16x16x32_bf16 v[0:3], v[168:171], v[238:241], v[0:3]
	v_mfma_f32_16x16x32_bf16 v[52:55], v[164:167], v[180:183], v[52:55]
	v_mfma_f32_16x16x32_bf16 v[48:51], v[172:175], v[180:183], v[48:51]
	v_mfma_f32_16x16x32_bf16 v[36:39], v[164:167], v[208:211], v[36:39]
	v_mfma_f32_16x16x32_bf16 v[32:35], v[172:175], v[208:211], v[32:35]
	v_mfma_f32_16x16x32_bf16 v[20:23], v[164:167], v[234:237], v[20:23]
	v_mfma_f32_16x16x32_bf16 v[16:19], v[172:175], v[234:237], v[16:19]
	v_mfma_f32_16x16x32_bf16 v[4:7], v[164:167], v[242:245], v[4:7]
	v_mfma_f32_16x16x32_bf16 v[0:3], v[172:175], v[242:245], v[0:3]
	s_setprio 0
	s_barrier
	s_add_i32 s52, s52, 2
	s_add_u32 s50, s50, 0x100
	s_addc_u32 s51, s51, 0
	s_cmp_gt_u32 s52, 29
	s_mov_b64 s[22:23], s[0:1]
	s_cbranch_scc0 .LBB0_804

.LBB0_1136:
	s_add_u32 s48, s18, 0x100
	s_addc_u32 s49, s19, 0
	s_mov_b32 s50, -2
	s_waitcnt lgkmcnt(0)
	s_add_u32 s18, s16, 0x100
	s_addc_u32 s19, s17, 0
	s_add_i32 s51, 0, 0x10000
	s_cmp_eq_u32 s50, 40
	s_cselect_b32 s23, s1, s19
	s_cselect_b32 s22, s0, s18
	s_cselect_b32 s21, s15, s49
	s_cselect_b32 s20, s14, s48
	s_add_i32 s52, 0, 0x14000
	v_add_u32_e32 v156, s51, v145
	v_add_u32_e32 v172, s52, v145
	ds_read_b128 v[140:143], v156
	ds_read_b128 v[148:151], v156 offset:1024
	ds_read_b128 v[152:155], v156 offset:2048
	ds_read_b128 v[156:159], v156 offset:3072
	ds_read_b128 v[160:163], v172
	ds_read_b128 v[164:167], v172 offset:1024
	ds_read_b128 v[168:171], v172 offset:2048
	ds_read_b128 v[172:175], v172 offset:3072
	s_add_i32 m0, s31, 0xc000
	ds_read_b128 v[176:179], v147
	ds_read_b128 v[180:183], v147 offset:1024
	ds_read_b128 v[184:187], v147 offset:2048
	ds_read_b128 v[208:211], v147 offset:3072
	ds_read_b128 v[230:233], v147 offset:4096
	ds_read_b128 v[234:237], v147 offset:5120
	ds_read_b128 v[238:241], v147 offset:6144
	ds_read_b128 v[242:245], v147 offset:7168
	global_load_lds_dwordx4 v138, s[16:17]
	s_add_i32 m0, s31, 0xe000
	s_nop 0
	global_load_lds_dwordx4 v136, s[16:17]
	s_waitcnt vmcnt(8)
	s_waitcnt lgkmcnt(0)
	s_barrier
	s_setprio 1
	s_waitcnt lgkmcnt(0)
	v_mfma_f32_16x16x32_bf16 v[126:129], v[140:143], v[176:179], 0
	v_mfma_f32_16x16x32_bf16 v[122:125], v[152:155], v[176:179], 0
	v_mfma_f32_16x16x32_bf16 v[108:111], v[140:143], v[184:187], 0
	v_mfma_f32_16x16x32_bf16 v[104:107], v[152:155], v[184:187], 0
	v_mfma_f32_16x16x32_bf16 v[92:95], v[140:143], v[230:233], 0
	v_mfma_f32_16x16x32_bf16 v[88:91], v[152:155], v[230:233], 0
	v_mfma_f32_16x16x32_bf16 v[76:79], v[140:143], v[238:241], 0
	v_mfma_f32_16x16x32_bf16 v[72:75], v[152:155], v[238:241], 0
	v_mfma_f32_16x16x32_bf16 v[126:129], v[148:151], v[180:183], v[126:129]
	v_mfma_f32_16x16x32_bf16 v[122:125], v[156:159], v[180:183], v[122:125]
	v_mfma_f32_16x16x32_bf16 v[108:111], v[148:151], v[208:211], v[108:111]
	v_mfma_f32_16x16x32_bf16 v[104:107], v[156:159], v[208:211], v[104:107]
	v_mfma_f32_16x16x32_bf16 v[92:95], v[148:151], v[234:237], v[92:95]
	v_mfma_f32_16x16x32_bf16 v[88:91], v[156:159], v[234:237], v[88:91]
	v_mfma_f32_16x16x32_bf16 v[76:79], v[148:151], v[242:245], v[76:79]
	v_mfma_f32_16x16x32_bf16 v[72:75], v[156:159], v[242:245], v[72:75]
	s_setprio 0
	s_setprio 1
	v_mfma_f32_16x16x32_bf16 v[118:121], v[160:163], v[176:179], 0
	v_mfma_f32_16x16x32_bf16 v[114:117], v[168:171], v[176:179], 0
	v_mfma_f32_16x16x32_bf16 v[100:103], v[160:163], v[184:187], 0
	v_mfma_f32_16x16x32_bf16 v[96:99], v[168:171], v[184:187], 0
	v_mfma_f32_16x16x32_bf16 v[84:87], v[160:163], v[230:233], 0
	v_mfma_f32_16x16x32_bf16 v[80:83], v[168:171], v[230:233], 0
	v_mfma_f32_16x16x32_bf16 v[68:71], v[160:163], v[238:241], 0
	v_mfma_f32_16x16x32_bf16 v[64:67], v[168:171], v[238:241], 0
	v_mfma_f32_16x16x32_bf16 v[118:121], v[164:167], v[180:183], v[118:121]
	v_mfma_f32_16x16x32_bf16 v[114:117], v[172:175], v[180:183], v[114:117]
	v_mfma_f32_16x16x32_bf16 v[100:103], v[164:167], v[208:211], v[100:103]
	v_mfma_f32_16x16x32_bf16 v[96:99], v[172:175], v[208:211], v[96:99]
	v_mfma_f32_16x16x32_bf16 v[84:87], v[164:167], v[234:237], v[84:87]
	v_mfma_f32_16x16x32_bf16 v[80:83], v[172:175], v[234:237], v[80:83]
	v_mfma_f32_16x16x32_bf16 v[68:71], v[164:167], v[242:245], v[68:71]
	v_mfma_f32_16x16x32_bf16 v[64:67], v[172:175], v[242:245], v[64:67]
	s_setprio 0
	s_barrier
	s_add_i32 s16, s51, s30
	s_mov_b32 m0, s16
	ds_read_b128 v[176:179], v147 offset:16384
	ds_read_b128 v[180:183], v147 offset:17408
	ds_read_b128 v[184:187], v147 offset:18432
	ds_read_b128 v[208:211], v147 offset:19456
	ds_read_b128 v[230:233], v147 offset:20480
	ds_read_b128 v[234:237], v147 offset:21504
	ds_read_b128 v[238:241], v147 offset:22528
	ds_read_b128 v[242:245], v147 offset:23552
	global_load_lds_dwordx4 v112, s[20:21]
	s_add_i32 m0, s16, 0x2000
	s_add_u32 s16, s20, 0xb0000
	v_lshl_add_u64 v[212:213], s[20:21], 0, v[134:135]
	s_addc_u32 s17, s21, 0
	s_add_i32 s51, s52, s30
	global_load_lds_dwordx4 v134, s[20:21]
	s_mov_b32 m0, s51
	s_nop 0
	global_load_lds_dwordx4 v112, s[16:17]
	s_add_i32 m0, s51, 0x2000
	s_nop 0
	global_load_lds_dwordx4 v134, s[16:17]
	s_mov_b32 m0, s31
	s_nop 0
	global_load_lds_dwordx4 v130, s[22:23]
	s_mov_b32 m0, s35
	s_nop 0
	global_load_lds_dwordx4 v132, s[22:23]
	s_waitcnt vmcnt(8)
	s_waitcnt lgkmcnt(0)
	s_barrier
	s_setprio 1
	s_waitcnt lgkmcnt(0)
	v_mfma_f32_16x16x32_bf16 v[60:63], v[140:143], v[176:179], 0
	v_mfma_f32_16x16x32_bf16 v[56:59], v[152:155], v[176:179], 0
	v_mfma_f32_16x16x32_bf16 v[44:47], v[140:143], v[184:187], 0
	v_mfma_f32_16x16x32_bf16 v[40:43], v[152:155], v[184:187], 0
	v_mfma_f32_16x16x32_bf16 v[28:31], v[140:143], v[230:233], 0
	v_mfma_f32_16x16x32_bf16 v[24:27], v[152:155], v[230:233], 0
	v_mfma_f32_16x16x32_bf16 v[12:15], v[140:143], v[238:241], 0
	v_mfma_f32_16x16x32_bf16 v[8:11], v[152:155], v[238:241], 0
	v_mfma_f32_16x16x32_bf16 v[60:63], v[148:151], v[180:183], v[60:63]
	v_mfma_f32_16x16x32_bf16 v[56:59], v[156:159], v[180:183], v[56:59]
	v_mfma_f32_16x16x32_bf16 v[44:47], v[148:151], v[208:211], v[44:47]
	v_mfma_f32_16x16x32_bf16 v[40:43], v[156:159], v[208:211], v[40:43]
	v_mfma_f32_16x16x32_bf16 v[28:31], v[148:151], v[234:237], v[28:31]
	v_mfma_f32_16x16x32_bf16 v[24:27], v[156:159], v[234:237], v[24:27]
	v_mfma_f32_16x16x32_bf16 v[12:15], v[148:151], v[242:245], v[12:15]
	v_mfma_f32_16x16x32_bf16 v[8:11], v[156:159], v[242:245], v[8:11]
	s_setprio 0
	s_setprio 1
	v_mfma_f32_16x16x32_bf16 v[52:55], v[160:163], v[176:179], 0
	v_mfma_f32_16x16x32_bf16 v[48:51], v[168:171], v[176:179], 0
	v_mfma_f32_16x16x32_bf16 v[36:39], v[160:163], v[184:187], 0
	v_mfma_f32_16x16x32_bf16 v[32:35], v[168:171], v[184:187], 0
	v_mfma_f32_16x16x32_bf16 v[20:23], v[160:163], v[230:233], 0
	v_mfma_f32_16x16x32_bf16 v[16:19], v[168:171], v[230:233], 0
	v_mfma_f32_16x16x32_bf16 v[4:7], v[160:163], v[238:241], 0
	v_mfma_f32_16x16x32_bf16 v[0:3], v[168:171], v[238:241], 0
	v_mfma_f32_16x16x32_bf16 v[52:55], v[164:167], v[180:183], v[52:55]
	v_mfma_f32_16x16x32_bf16 v[48:51], v[172:175], v[180:183], v[48:51]
	v_mfma_f32_16x16x32_bf16 v[36:39], v[164:167], v[208:211], v[36:39]
	v_mfma_f32_16x16x32_bf16 v[32:35], v[172:175], v[208:211], v[32:35]
	v_mfma_f32_16x16x32_bf16 v[20:23], v[164:167], v[234:237], v[20:23]
	v_mfma_f32_16x16x32_bf16 v[16:19], v[172:175], v[234:237], v[16:19]
	v_mfma_f32_16x16x32_bf16 v[4:7], v[164:167], v[242:245], v[4:7]
	v_mfma_f32_16x16x32_bf16 v[0:3], v[172:175], v[242:245], v[0:3]
	s_setprio 0
	s_barrier
	s_add_i32 s51, 0, 0x18000
	s_add_i32 s52, 0, 0x1c000
	v_add_u32_e32 v156, s51, v145
	v_add_u32_e32 v172, s52, v145
	ds_read_b128 v[140:143], v156
	ds_read_b128 v[148:151], v156 offset:1024
	ds_read_b128 v[152:155], v156 offset:2048
	ds_read_b128 v[156:159], v156 offset:3072
	ds_read_b128 v[160:163], v172
	ds_read_b128 v[164:167], v172 offset:1024
	ds_read_b128 v[168:171], v172 offset:2048
	ds_read_b128 v[172:175], v172 offset:3072
	s_add_u32 s16, s22, 0xb0000
	s_addc_u32 s17, s23, 0
	s_mov_b32 m0, s36
	ds_read_b128 v[176:179], v147 offset:32768
	ds_read_b128 v[180:183], v147 offset:33792
	ds_read_b128 v[184:187], v147 offset:34816
	ds_read_b128 v[208:211], v147 offset:35840
	ds_read_b128 v[230:233], v147 offset:36864
	ds_read_b128 v[234:237], v147 offset:37888
	ds_read_b128 v[238:241], v147 offset:38912
	ds_read_b128 v[242:245], v147 offset:39936
	global_load_lds_dwordx4 v130, s[16:17]
	s_mov_b32 m0, s37
	s_nop 0
	global_load_lds_dwordx4 v132, s[16:17]
	s_waitcnt vmcnt(8)
	s_waitcnt lgkmcnt(0)
	s_barrier
	s_setprio 1
	s_waitcnt lgkmcnt(0)
	v_mfma_f32_16x16x32_bf16 v[126:129], v[140:143], v[176:179], v[126:129]
	v_mfma_f32_16x16x32_bf16 v[122:125], v[152:155], v[176:179], v[122:125]
	v_mfma_f32_16x16x32_bf16 v[108:111], v[140:143], v[184:187], v[108:111]
	v_mfma_f32_16x16x32_bf16 v[104:107], v[152:155], v[184:187], v[104:107]
	v_mfma_f32_16x16x32_bf16 v[92:95], v[140:143], v[230:233], v[92:95]
	v_mfma_f32_16x16x32_bf16 v[88:91], v[152:155], v[230:233], v[88:91]
	v_mfma_f32_16x16x32_bf16 v[76:79], v[140:143], v[238:241], v[76:79]
	v_mfma_f32_16x16x32_bf16 v[72:75], v[152:155], v[238:241], v[72:75]
	v_mfma_f32_16x16x32_bf16 v[126:129], v[148:151], v[180:183], v[126:129]
	v_mfma_f32_16x16x32_bf16 v[122:125], v[156:159], v[180:183], v[122:125]
	v_mfma_f32_16x16x32_bf16 v[108:111], v[148:151], v[208:211], v[108:111]
	v_mfma_f32_16x16x32_bf16 v[104:107], v[156:159], v[208:211], v[104:107]
	v_mfma_f32_16x16x32_bf16 v[92:95], v[148:151], v[234:237], v[92:95]
	v_mfma_f32_16x16x32_bf16 v[88:91], v[156:159], v[234:237], v[88:91]
	v_mfma_f32_16x16x32_bf16 v[76:79], v[148:151], v[242:245], v[76:79]
	v_mfma_f32_16x16x32_bf16 v[72:75], v[156:159], v[242:245], v[72:75]
	s_setprio 0
	s_setprio 1
	v_mfma_f32_16x16x32_bf16 v[118:121], v[160:163], v[176:179], v[118:121]
	v_mfma_f32_16x16x32_bf16 v[114:117], v[168:171], v[176:179], v[114:117]
	v_mfma_f32_16x16x32_bf16 v[100:103], v[160:163], v[184:187], v[100:103]
	v_mfma_f32_16x16x32_bf16 v[96:99], v[168:171], v[184:187], v[96:99]
	v_mfma_f32_16x16x32_bf16 v[84:87], v[160:163], v[230:233], v[84:87]
	v_mfma_f32_16x16x32_bf16 v[80:83], v[168:171], v[230:233], v[80:83]
	v_mfma_f32_16x16x32_bf16 v[68:71], v[160:163], v[238:241], v[68:71]
	v_mfma_f32_16x16x32_bf16 v[64:67], v[168:171], v[238:241], v[64:67]
	v_mfma_f32_16x16x32_bf16 v[118:121], v[164:167], v[180:183], v[118:121]
	v_mfma_f32_16x16x32_bf16 v[114:117], v[172:175], v[180:183], v[114:117]
	v_mfma_f32_16x16x32_bf16 v[100:103], v[164:167], v[208:211], v[100:103]
	v_mfma_f32_16x16x32_bf16 v[96:99], v[172:175], v[208:211], v[96:99]
	v_mfma_f32_16x16x32_bf16 v[84:87], v[164:167], v[234:237], v[84:87]
	v_mfma_f32_16x16x32_bf16 v[80:83], v[172:175], v[234:237], v[80:83]
	v_mfma_f32_16x16x32_bf16 v[68:71], v[164:167], v[242:245], v[68:71]
	v_mfma_f32_16x16x32_bf16 v[64:67], v[172:175], v[242:245], v[64:67]
	s_setprio 0
	s_barrier
	s_add_i32 s16, s51, s30
	s_mov_b32 m0, s16
	ds_read_b128 v[176:179], v147 offset:49152
	ds_read_b128 v[180:183], v147 offset:50176
	ds_read_b128 v[184:187], v147 offset:51200
	ds_read_b128 v[208:211], v147 offset:52224
	ds_read_b128 v[230:233], v147 offset:53248
	ds_read_b128 v[234:237], v147 offset:54272
	ds_read_b128 v[238:241], v147 offset:55296
	ds_read_b128 v[242:245], v147 offset:56320
	s_add_u32 s98, s20, 0x80
	s_addc_u32 s99, s21, 0
	global_load_lds_dwordx4 v112, s[98:99]
	s_add_i32 m0, s16, 0x2000
	s_add_u32 s16, s20, 0xb0080
	v_lshl_add_u64 v[188:189], v[212:213], 0, s[96:97]
	s_addc_u32 s17, s21, 0
	s_add_i32 s20, s52, s30
	global_load_lds_dwordx4 v[188:189], off
	s_mov_b32 m0, s20
	s_nop 0
	global_load_lds_dwordx4 v112, s[16:17]
	s_add_i32 m0, s20, 0x2000
	s_nop 0
	global_load_lds_dwordx4 v134, s[16:17]
	s_mov_b32 m0, s39
	s_nop 0
	s_add_u32 s98, s22, 0x80
	s_addc_u32 s99, s23, 0
	global_load_lds_dwordx4 v130, s[98:99]
	s_mov_b32 m0, s40
	s_nop 0
	s_add_u32 s98, s22, 0x80
	s_addc_u32 s99, s23, 0
	global_load_lds_dwordx4 v132, s[98:99]
	s_waitcnt vmcnt(8)
	s_waitcnt lgkmcnt(0)
	s_barrier
	s_setprio 1
	s_waitcnt lgkmcnt(0)
	v_mfma_f32_16x16x32_bf16 v[60:63], v[140:143], v[176:179], v[60:63]
	v_mfma_f32_16x16x32_bf16 v[56:59], v[152:155], v[176:179], v[56:59]
	v_mfma_f32_16x16x32_bf16 v[44:47], v[140:143], v[184:187], v[44:47]
	v_mfma_f32_16x16x32_bf16 v[40:43], v[152:155], v[184:187], v[40:43]
	v_mfma_f32_16x16x32_bf16 v[28:31], v[140:143], v[230:233], v[28:31]
	v_mfma_f32_16x16x32_bf16 v[24:27], v[152:155], v[230:233], v[24:27]
	v_mfma_f32_16x16x32_bf16 v[12:15], v[140:143], v[238:241], v[12:15]
	v_mfma_f32_16x16x32_bf16 v[8:11], v[152:155], v[238:241], v[8:11]
	v_mfma_f32_16x16x32_bf16 v[60:63], v[148:151], v[180:183], v[60:63]
	v_mfma_f32_16x16x32_bf16 v[56:59], v[156:159], v[180:183], v[56:59]
	v_mfma_f32_16x16x32_bf16 v[44:47], v[148:151], v[208:211], v[44:47]
	v_mfma_f32_16x16x32_bf16 v[40:43], v[156:159], v[208:211], v[40:43]
	v_mfma_f32_16x16x32_bf16 v[28:31], v[148:151], v[234:237], v[28:31]
	v_mfma_f32_16x16x32_bf16 v[24:27], v[156:159], v[234:237], v[24:27]
	v_mfma_f32_16x16x32_bf16 v[12:15], v[148:151], v[242:245], v[12:15]
	v_mfma_f32_16x16x32_bf16 v[8:11], v[156:159], v[242:245], v[8:11]
	s_setprio 0
	s_setprio 1
	v_mfma_f32_16x16x32_bf16 v[52:55], v[160:163], v[176:179], v[52:55]
	v_mfma_f32_16x16x32_bf16 v[48:51], v[168:171], v[176:179], v[48:51]
	v_mfma_f32_16x16x32_bf16 v[36:39], v[160:163], v[184:187], v[36:39]
	v_mfma_f32_16x16x32_bf16 v[32:35], v[168:171], v[184:187], v[32:35]
	v_mfma_f32_16x16x32_bf16 v[20:23], v[160:163], v[230:233], v[20:23]
	v_mfma_f32_16x16x32_bf16 v[16:19], v[168:171], v[230:233], v[16:19]
	v_mfma_f32_16x16x32_bf16 v[4:7], v[160:163], v[238:241], v[4:7]
	v_mfma_f32_16x16x32_bf16 v[0:3], v[168:171], v[238:241], v[0:3]
	v_mfma_f32_16x16x32_bf16 v[52:55], v[164:167], v[180:183], v[52:55]
	v_mfma_f32_16x16x32_bf16 v[48:51], v[172:175], v[180:183], v[48:51]
	v_mfma_f32_16x16x32_bf16 v[36:39], v[164:167], v[208:211], v[36:39]
	v_mfma_f32_16x16x32_bf16 v[32:35], v[172:175], v[208:211], v[32:35]
	v_mfma_f32_16x16x32_bf16 v[20:23], v[164:167], v[234:237], v[20:23]
	v_mfma_f32_16x16x32_bf16 v[16:19], v[172:175], v[234:237], v[16:19]
	v_mfma_f32_16x16x32_bf16 v[4:7], v[164:167], v[242:245], v[4:7]
	v_mfma_f32_16x16x32_bf16 v[0:3], v[172:175], v[242:245], v[0:3]
	s_setprio 0
	s_barrier
	s_add_i32 s50, s50, 2
	s_add_u32 s48, s48, 0x100
	s_addc_u32 s49, s49, 0
	s_cmp_gt_u32 s50, 41
	s_mov_b64 s[16:17], s[18:19]
	s_cbranch_scc0 .LBB0_1137
	s_branch .Lpeel_exit_1137
.LBB0_1137:
	s_add_u32 s18, s16, 0x100
	s_addc_u32 s19, s17, 0
	s_add_i32 s51, 0, 0x10000
	s_cmp_eq_u32 s50, 40
	s_cselect_b32 s23, s1, s19
	s_cselect_b32 s22, s0, s18
	s_cselect_b32 s21, s15, s49
	s_cselect_b32 s20, s14, s48
	s_add_i32 s52, 0, 0x14000
	v_add_u32_e32 v156, s51, v145
	v_add_u32_e32 v172, s52, v145
	ds_read_b128 v[140:143], v156
	ds_read_b128 v[148:151], v156 offset:1024
	ds_read_b128 v[152:155], v156 offset:2048
	ds_read_b128 v[156:159], v156 offset:3072
	ds_read_b128 v[160:163], v172
	ds_read_b128 v[164:167], v172 offset:1024
	ds_read_b128 v[168:171], v172 offset:2048
	ds_read_b128 v[172:175], v172 offset:3072
	s_add_i32 m0, s31, 0xc000
	ds_read_b128 v[176:179], v147
	ds_read_b128 v[180:183], v147 offset:1024
	ds_read_b128 v[184:187], v147 offset:2048
	ds_read_b128 v[208:211], v147 offset:3072
	ds_read_b128 v[230:233], v147 offset:4096
	ds_read_b128 v[234:237], v147 offset:5120
	ds_read_b128 v[238:241], v147 offset:6144
	ds_read_b128 v[242:245], v147 offset:7168
	global_load_lds_dwordx4 v138, s[16:17]
	s_add_i32 m0, s31, 0xe000
	s_nop 0
	global_load_lds_dwordx4 v136, s[16:17]
	s_waitcnt vmcnt(8)
	s_waitcnt lgkmcnt(0)
	s_barrier
	s_setprio 1
	s_waitcnt lgkmcnt(0)
	v_mfma_f32_16x16x32_bf16 v[126:129], v[140:143], v[176:179], v[126:129]
	v_mfma_f32_16x16x32_bf16 v[122:125], v[152:155], v[176:179], v[122:125]
	v_mfma_f32_16x16x32_bf16 v[108:111], v[140:143], v[184:187], v[108:111]
	v_mfma_f32_16x16x32_bf16 v[104:107], v[152:155], v[184:187], v[104:107]
	v_mfma_f32_16x16x32_bf16 v[92:95], v[140:143], v[230:233], v[92:95]
	v_mfma_f32_16x16x32_bf16 v[88:91], v[152:155], v[230:233], v[88:91]
	v_mfma_f32_16x16x32_bf16 v[76:79], v[140:143], v[238:241], v[76:79]
	v_mfma_f32_16x16x32_bf16 v[72:75], v[152:155], v[238:241], v[72:75]
	v_mfma_f32_16x16x32_bf16 v[126:129], v[148:151], v[180:183], v[126:129]
	v_mfma_f32_16x16x32_bf16 v[122:125], v[156:159], v[180:183], v[122:125]
	v_mfma_f32_16x16x32_bf16 v[108:111], v[148:151], v[208:211], v[108:111]
	v_mfma_f32_16x16x32_bf16 v[104:107], v[156:159], v[208:211], v[104:107]
	v_mfma_f32_16x16x32_bf16 v[92:95], v[148:151], v[234:237], v[92:95]
	v_mfma_f32_16x16x32_bf16 v[88:91], v[156:159], v[234:237], v[88:91]
	v_mfma_f32_16x16x32_bf16 v[76:79], v[148:151], v[242:245], v[76:79]
	v_mfma_f32_16x16x32_bf16 v[72:75], v[156:159], v[242:245], v[72:75]
	s_setprio 0
	s_setprio 1
	v_mfma_f32_16x16x32_bf16 v[118:121], v[160:163], v[176:179], v[118:121]
	v_mfma_f32_16x16x32_bf16 v[114:117], v[168:171], v[176:179], v[114:117]
	v_mfma_f32_16x16x32_bf16 v[100:103], v[160:163], v[184:187], v[100:103]
	v_mfma_f32_16x16x32_bf16 v[96:99], v[168:171], v[184:187], v[96:99]
	v_mfma_f32_16x16x32_bf16 v[84:87], v[160:163], v[230:233], v[84:87]
	v_mfma_f32_16x16x32_bf16 v[80:83], v[168:171], v[230:233], v[80:83]
	v_mfma_f32_16x16x32_bf16 v[68:71], v[160:163], v[238:241], v[68:71]
	v_mfma_f32_16x16x32_bf16 v[64:67], v[168:171], v[238:241], v[64:67]
	v_mfma_f32_16x16x32_bf16 v[118:121], v[164:167], v[180:183], v[118:121]
	v_mfma_f32_16x16x32_bf16 v[114:117], v[172:175], v[180:183], v[114:117]
	v_mfma_f32_16x16x32_bf16 v[100:103], v[164:167], v[208:211], v[100:103]
	v_mfma_f32_16x16x32_bf16 v[96:99], v[172:175], v[208:211], v[96:99]
	v_mfma_f32_16x16x32_bf16 v[84:87], v[164:167], v[234:237], v[84:87]
	v_mfma_f32_16x16x32_bf16 v[80:83], v[172:175], v[234:237], v[80:83]
	v_mfma_f32_16x16x32_bf16 v[68:71], v[164:167], v[242:245], v[68:71]
	v_mfma_f32_16x16x32_bf16 v[64:67], v[172:175], v[242:245], v[64:67]
	s_setprio 0
	s_barrier
	s_add_i32 s16, s51, s30
	s_mov_b32 m0, s16
	ds_read_b128 v[176:179], v147 offset:16384
	ds_read_b128 v[180:183], v147 offset:17408
	ds_read_b128 v[184:187], v147 offset:18432
	ds_read_b128 v[208:211], v147 offset:19456
	ds_read_b128 v[230:233], v147 offset:20480
	ds_read_b128 v[234:237], v147 offset:21504
	ds_read_b128 v[238:241], v147 offset:22528
	ds_read_b128 v[242:245], v147 offset:23552
	global_load_lds_dwordx4 v112, s[20:21]
	s_add_i32 m0, s16, 0x2000
	s_add_u32 s16, s20, 0xb0000
	v_lshl_add_u64 v[212:213], s[20:21], 0, v[134:135]
	s_addc_u32 s17, s21, 0
	s_add_i32 s51, s52, s30
	global_load_lds_dwordx4 v134, s[20:21]
	s_mov_b32 m0, s51
	s_nop 0
	global_load_lds_dwordx4 v112, s[16:17]
	s_add_i32 m0, s51, 0x2000
	s_nop 0
	global_load_lds_dwordx4 v134, s[16:17]
	s_mov_b32 m0, s31
	s_nop 0
	global_load_lds_dwordx4 v130, s[22:23]
	s_mov_b32 m0, s35
	s_nop 0
	global_load_lds_dwordx4 v132, s[22:23]
	s_waitcnt vmcnt(8)
	s_waitcnt lgkmcnt(0)
	s_barrier
	s_setprio 1
	s_waitcnt lgkmcnt(0)
	v_mfma_f32_16x16x32_bf16 v[60:63], v[140:143], v[176:179], v[60:63]
	v_mfma_f32_16x16x32_bf16 v[56:59], v[152:155], v[176:179], v[56:59]
	v_mfma_f32_16x16x32_bf16 v[44:47], v[140:143], v[184:187], v[44:47]
	v_mfma_f32_16x16x32_bf16 v[40:43], v[152:155], v[184:187], v[40:43]
	v_mfma_f32_16x16x32_bf16 v[28:31], v[140:143], v[230:233], v[28:31]
	v_mfma_f32_16x16x32_bf16 v[24:27], v[152:155], v[230:233], v[24:27]
	v_mfma_f32_16x16x32_bf16 v[12:15], v[140:143], v[238:241], v[12:15]
	v_mfma_f32_16x16x32_bf16 v[8:11], v[152:155], v[238:241], v[8:11]
	v_mfma_f32_16x16x32_bf16 v[60:63], v[148:151], v[180:183], v[60:63]
	v_mfma_f32_16x16x32_bf16 v[56:59], v[156:159], v[180:183], v[56:59]
	v_mfma_f32_16x16x32_bf16 v[44:47], v[148:151], v[208:211], v[44:47]
	v_mfma_f32_16x16x32_bf16 v[40:43], v[156:159], v[208:211], v[40:43]
	v_mfma_f32_16x16x32_bf16 v[28:31], v[148:151], v[234:237], v[28:31]
	v_mfma_f32_16x16x32_bf16 v[24:27], v[156:159], v[234:237], v[24:27]
	v_mfma_f32_16x16x32_bf16 v[12:15], v[148:151], v[242:245], v[12:15]
	v_mfma_f32_16x16x32_bf16 v[8:11], v[156:159], v[242:245], v[8:11]
	s_setprio 0
	s_setprio 1
	v_mfma_f32_16x16x32_bf16 v[52:55], v[160:163], v[176:179], v[52:55]
	v_mfma_f32_16x16x32_bf16 v[48:51], v[168:171], v[176:179], v[48:51]
	v_mfma_f32_16x16x32_bf16 v[36:39], v[160:163], v[184:187], v[36:39]
	v_mfma_f32_16x16x32_bf16 v[32:35], v[168:171], v[184:187], v[32:35]
	v_mfma_f32_16x16x32_bf16 v[20:23], v[160:163], v[230:233], v[20:23]
	v_mfma_f32_16x16x32_bf16 v[16:19], v[168:171], v[230:233], v[16:19]
	v_mfma_f32_16x16x32_bf16 v[4:7], v[160:163], v[238:241], v[4:7]
	v_mfma_f32_16x16x32_bf16 v[0:3], v[168:171], v[238:241], v[0:3]
	v_mfma_f32_16x16x32_bf16 v[52:55], v[164:167], v[180:183], v[52:55]
	v_mfma_f32_16x16x32_bf16 v[48:51], v[172:175], v[180:183], v[48:51]
	v_mfma_f32_16x16x32_bf16 v[36:39], v[164:167], v[208:211], v[36:39]
	v_mfma_f32_16x16x32_bf16 v[32:35], v[172:175], v[208:211], v[32:35]
	v_mfma_f32_16x16x32_bf16 v[20:23], v[164:167], v[234:237], v[20:23]
	v_mfma_f32_16x16x32_bf16 v[16:19], v[172:175], v[234:237], v[16:19]
	v_mfma_f32_16x16x32_bf16 v[4:7], v[164:167], v[242:245], v[4:7]
	v_mfma_f32_16x16x32_bf16 v[0:3], v[172:175], v[242:245], v[0:3]
	s_setprio 0
	s_barrier
	s_add_i32 s51, 0, 0x18000
	s_add_i32 s52, 0, 0x1c000
	v_add_u32_e32 v156, s51, v145
	v_add_u32_e32 v172, s52, v145
	ds_read_b128 v[140:143], v156
	ds_read_b128 v[148:151], v156 offset:1024
	ds_read_b128 v[152:155], v156 offset:2048
	ds_read_b128 v[156:159], v156 offset:3072
	ds_read_b128 v[160:163], v172
	ds_read_b128 v[164:167], v172 offset:1024
	ds_read_b128 v[168:171], v172 offset:2048
	ds_read_b128 v[172:175], v172 offset:3072
	s_add_u32 s16, s22, 0xb0000
	s_addc_u32 s17, s23, 0
	s_mov_b32 m0, s36
	ds_read_b128 v[176:179], v147 offset:32768
	ds_read_b128 v[180:183], v147 offset:33792
	ds_read_b128 v[184:187], v147 offset:34816
	ds_read_b128 v[208:211], v147 offset:35840
	ds_read_b128 v[230:233], v147 offset:36864
	ds_read_b128 v[234:237], v147 offset:37888
	ds_read_b128 v[238:241], v147 offset:38912
	ds_read_b128 v[242:245], v147 offset:39936
	global_load_lds_dwordx4 v130, s[16:17]
	s_mov_b32 m0, s37
	s_nop 0
	global_load_lds_dwordx4 v132, s[16:17]
	s_waitcnt vmcnt(8)
	s_waitcnt lgkmcnt(0)
	s_barrier
	s_setprio 1
	s_waitcnt lgkmcnt(0)
	v_mfma_f32_16x16x32_bf16 v[126:129], v[140:143], v[176:179], v[126:129]
	v_mfma_f32_16x16x32_bf16 v[122:125], v[152:155], v[176:179], v[122:125]
	v_mfma_f32_16x16x32_bf16 v[108:111], v[140:143], v[184:187], v[108:111]
	v_mfma_f32_16x16x32_bf16 v[104:107], v[152:155], v[184:187], v[104:107]
	v_mfma_f32_16x16x32_bf16 v[92:95], v[140:143], v[230:233], v[92:95]
	v_mfma_f32_16x16x32_bf16 v[88:91], v[152:155], v[230:233], v[88:91]
	v_mfma_f32_16x16x32_bf16 v[76:79], v[140:143], v[238:241], v[76:79]
	v_mfma_f32_16x16x32_bf16 v[72:75], v[152:155], v[238:241], v[72:75]
	v_mfma_f32_16x16x32_bf16 v[126:129], v[148:151], v[180:183], v[126:129]
	v_mfma_f32_16x16x32_bf16 v[122:125], v[156:159], v[180:183], v[122:125]
	v_mfma_f32_16x16x32_bf16 v[108:111], v[148:151], v[208:211], v[108:111]
	v_mfma_f32_16x16x32_bf16 v[104:107], v[156:159], v[208:211], v[104:107]
	v_mfma_f32_16x16x32_bf16 v[92:95], v[148:151], v[234:237], v[92:95]
	v_mfma_f32_16x16x32_bf16 v[88:91], v[156:159], v[234:237], v[88:91]
	v_mfma_f32_16x16x32_bf16 v[76:79], v[148:151], v[242:245], v[76:79]
	v_mfma_f32_16x16x32_bf16 v[72:75], v[156:159], v[242:245], v[72:75]
	s_setprio 0
	s_setprio 1
	v_mfma_f32_16x16x32_bf16 v[118:121], v[160:163], v[176:179], v[118:121]
	v_mfma_f32_16x16x32_bf16 v[114:117], v[168:171], v[176:179], v[114:117]
	v_mfma_f32_16x16x32_bf16 v[100:103], v[160:163], v[184:187], v[100:103]
	v_mfma_f32_16x16x32_bf16 v[96:99], v[168:171], v[184:187], v[96:99]
	v_mfma_f32_16x16x32_bf16 v[84:87], v[160:163], v[230:233], v[84:87]
	v_mfma_f32_16x16x32_bf16 v[80:83], v[168:171], v[230:233], v[80:83]
	v_mfma_f32_16x16x32_bf16 v[68:71], v[160:163], v[238:241], v[68:71]
	v_mfma_f32_16x16x32_bf16 v[64:67], v[168:171], v[238:241], v[64:67]
	v_mfma_f32_16x16x32_bf16 v[118:121], v[164:167], v[180:183], v[118:121]
	v_mfma_f32_16x16x32_bf16 v[114:117], v[172:175], v[180:183], v[114:117]
	v_mfma_f32_16x16x32_bf16 v[100:103], v[164:167], v[208:211], v[100:103]
	v_mfma_f32_16x16x32_bf16 v[96:99], v[172:175], v[208:211], v[96:99]
	v_mfma_f32_16x16x32_bf16 v[84:87], v[164:167], v[234:237], v[84:87]
	v_mfma_f32_16x16x32_bf16 v[80:83], v[172:175], v[234:237], v[80:83]
	v_mfma_f32_16x16x32_bf16 v[68:71], v[164:167], v[242:245], v[68:71]
	v_mfma_f32_16x16x32_bf16 v[64:67], v[172:175], v[242:245], v[64:67]
	s_setprio 0
	s_barrier
	s_add_i32 s16, s51, s30
	s_mov_b32 m0, s16
	ds_read_b128 v[176:179], v147 offset:49152
	ds_read_b128 v[180:183], v147 offset:50176
	ds_read_b128 v[184:187], v147 offset:51200
	ds_read_b128 v[208:211], v147 offset:52224
	ds_read_b128 v[230:233], v147 offset:53248
	ds_read_b128 v[234:237], v147 offset:54272
	ds_read_b128 v[238:241], v147 offset:55296
	ds_read_b128 v[242:245], v147 offset:56320
	s_add_u32 s98, s20, 0x80
	s_addc_u32 s99, s21, 0
	global_load_lds_dwordx4 v112, s[98:99]
	s_add_i32 m0, s16, 0x2000
	s_add_u32 s16, s20, 0xb0080
	v_lshl_add_u64 v[188:189], v[212:213], 0, s[96:97]
	s_addc_u32 s17, s21, 0
	s_add_i32 s20, s52, s30
	global_load_lds_dwordx4 v[188:189], off
	s_mov_b32 m0, s20
	s_nop 0
	global_load_lds_dwordx4 v112, s[16:17]
	s_add_i32 m0, s20, 0x2000
	s_nop 0
	global_load_lds_dwordx4 v134, s[16:17]
	s_mov_b32 m0, s39
	s_nop 0
	s_add_u32 s98, s22, 0x80
	s_addc_u32 s99, s23, 0
	global_load_lds_dwordx4 v130, s[98:99]
	s_mov_b32 m0, s40
	s_nop 0
	s_add_u32 s98, s22, 0x80
	s_addc_u32 s99, s23, 0
	global_load_lds_dwordx4 v132, s[98:99]
	s_waitcnt vmcnt(8)
	s_waitcnt lgkmcnt(0)
	s_barrier
	s_setprio 1
	s_waitcnt lgkmcnt(0)
	v_mfma_f32_16x16x32_bf16 v[60:63], v[140:143], v[176:179], v[60:63]
	v_mfma_f32_16x16x32_bf16 v[56:59], v[152:155], v[176:179], v[56:59]
	v_mfma_f32_16x16x32_bf16 v[44:47], v[140:143], v[184:187], v[44:47]
	v_mfma_f32_16x16x32_bf16 v[40:43], v[152:155], v[184:187], v[40:43]
	v_mfma_f32_16x16x32_bf16 v[28:31], v[140:143], v[230:233], v[28:31]
	v_mfma_f32_16x16x32_bf16 v[24:27], v[152:155], v[230:233], v[24:27]
	v_mfma_f32_16x16x32_bf16 v[12:15], v[140:143], v[238:241], v[12:15]
	v_mfma_f32_16x16x32_bf16 v[8:11], v[152:155], v[238:241], v[8:11]
	v_mfma_f32_16x16x32_bf16 v[60:63], v[148:151], v[180:183], v[60:63]
	v_mfma_f32_16x16x32_bf16 v[56:59], v[156:159], v[180:183], v[56:59]
	v_mfma_f32_16x16x32_bf16 v[44:47], v[148:151], v[208:211], v[44:47]
	v_mfma_f32_16x16x32_bf16 v[40:43], v[156:159], v[208:211], v[40:43]
	v_mfma_f32_16x16x32_bf16 v[28:31], v[148:151], v[234:237], v[28:31]
	v_mfma_f32_16x16x32_bf16 v[24:27], v[156:159], v[234:237], v[24:27]
	v_mfma_f32_16x16x32_bf16 v[12:15], v[148:151], v[242:245], v[12:15]
	v_mfma_f32_16x16x32_bf16 v[8:11], v[156:159], v[242:245], v[8:11]
	s_setprio 0
	s_setprio 1
	v_mfma_f32_16x16x32_bf16 v[52:55], v[160:163], v[176:179], v[52:55]
	v_mfma_f32_16x16x32_bf16 v[48:51], v[168:171], v[176:179], v[48:51]
	v_mfma_f32_16x16x32_bf16 v[36:39], v[160:163], v[184:187], v[36:39]
	v_mfma_f32_16x16x32_bf16 v[32:35], v[168:171], v[184:187], v[32:35]
	v_mfma_f32_16x16x32_bf16 v[20:23], v[160:163], v[230:233], v[20:23]
	v_mfma_f32_16x16x32_bf16 v[16:19], v[168:171], v[230:233], v[16:19]
	v_mfma_f32_16x16x32_bf16 v[4:7], v[160:163], v[238:241], v[4:7]
	v_mfma_f32_16x16x32_bf16 v[0:3], v[168:171], v[238:241], v[0:3]
	v_mfma_f32_16x16x32_bf16 v[52:55], v[164:167], v[180:183], v[52:55]
	v_mfma_f32_16x16x32_bf16 v[48:51], v[172:175], v[180:183], v[48:51]
	v_mfma_f32_16x16x32_bf16 v[36:39], v[164:167], v[208:211], v[36:39]
	v_mfma_f32_16x16x32_bf16 v[32:35], v[172:175], v[208:211], v[32:35]
	v_mfma_f32_16x16x32_bf16 v[20:23], v[164:167], v[234:237], v[20:23]
	v_mfma_f32_16x16x32_bf16 v[16:19], v[172:175], v[234:237], v[16:19]
	v_mfma_f32_16x16x32_bf16 v[4:7], v[164:167], v[242:245], v[4:7]
	v_mfma_f32_16x16x32_bf16 v[0:3], v[172:175], v[242:245], v[0:3]
	s_setprio 0
	s_barrier
	s_add_i32 s50, s50, 2
	s_add_u32 s48, s48, 0x100
	s_addc_u32 s49, s49, 0
	s_cmp_gt_u32 s50, 41
	s_mov_b64 s[16:17], s[18:19]
	s_cbranch_scc0 .LBB0_1137

.LBB0_1951:
	s_ashr_i32 s17, s16, 31
	s_lshl_b64 s[18:19], s[16:17], 19
	s_add_u32 s18, s42, s18
	s_addc_u32 s19, s43, s19
	s_and_b64 s[20:21], s[2:3], exec
	s_cselect_b32 s5, s19, s27
	s_cselect_b32 s17, s18, s26
	s_ashr_i32 s15, s14, 31
	s_lshl_b64 s[20:21], s[14:15], 19
	s_add_u32 s20, s40, s20
	s_addc_u32 s21, s41, s21
	s_and_b64 s[28:29], s[2:3], exec
	s_cselect_b32 s15, s21, s25
	s_cselect_b32 s51, s20, s24
	s_add_u32 s52, s24, 0x100
	s_addc_u32 s53, s25, 0
	s_add_u32 s24, s26, 0x40080
	s_addc_u32 s25, s27, 0
	s_mov_b32 s54, -2
	s_add_u32 s26, s24, 0xfffc0080
	s_addc_u32 s27, s25, -1
	s_add_i32 s55, 0, 0x10000
	s_cmp_eq_u32 s54, 12
	s_cselect_b32 s29, s5, s27
	s_cselect_b32 s28, s17, s26
	v_add_u32_e32 v144, s55, v146
	s_cselect_b32 s27, s15, s53
	s_cselect_b32 s26, s51, s52
	s_add_i32 s58, 0, 0x14000
	ds_read_b128 v[140:143], v144
	ds_read_b128 v[150:153], v144 offset:1024
	ds_read_b128 v[154:157], v144 offset:2048
	ds_read_b128 v[158:161], v144 offset:3072
	v_add_u32_e32 v144, s58, v146
	ds_read_b128 v[162:165], v144
	ds_read_b128 v[166:169], v144 offset:1024
	ds_read_b128 v[170:173], v144 offset:2048
	ds_read_b128 v[174:177], v144 offset:3072
	s_add_i32 m0, s23, 0xc000
	ds_read_b128 v[178:181], v149
	ds_read_b128 v[182:185], v149 offset:1024
	ds_read_b128 v[186:189], v149 offset:2048
	ds_read_b128 v[208:211], v149 offset:3072
	ds_read_b128 v[230:233], v149 offset:4096
	ds_read_b128 v[234:237], v149 offset:5120
	ds_read_b128 v[238:241], v149 offset:6144
	ds_read_b128 v[242:245], v149 offset:7168
	global_load_lds_dwordx4 v138, s[24:25]
	s_add_i32 m0, s23, 0xe000
	s_nop 0
	global_load_lds_dwordx4 v136, s[24:25]
	s_waitcnt vmcnt(8)
	s_waitcnt lgkmcnt(0)
	s_barrier
	s_setprio 1
	s_waitcnt lgkmcnt(0)
	v_mfma_f32_16x16x32_bf16 v[126:129], v[140:143], v[178:181], 0
	v_mfma_f32_16x16x32_bf16 v[118:121], v[154:157], v[178:181], 0
	v_mfma_f32_16x16x32_bf16 v[108:111], v[140:143], v[186:189], 0
	v_mfma_f32_16x16x32_bf16 v[100:103], v[154:157], v[186:189], 0
	v_mfma_f32_16x16x32_bf16 v[92:95], v[140:143], v[230:233], 0
	v_mfma_f32_16x16x32_bf16 v[84:87], v[154:157], v[230:233], 0
	v_mfma_f32_16x16x32_bf16 v[76:79], v[140:143], v[238:241], 0
	v_mfma_f32_16x16x32_bf16 v[68:71], v[154:157], v[238:241], 0
	v_mfma_f32_16x16x32_bf16 v[126:129], v[150:153], v[182:185], v[126:129]
	v_mfma_f32_16x16x32_bf16 v[118:121], v[158:161], v[182:185], v[118:121]
	v_mfma_f32_16x16x32_bf16 v[108:111], v[150:153], v[208:211], v[108:111]
	v_mfma_f32_16x16x32_bf16 v[100:103], v[158:161], v[208:211], v[100:103]
	v_mfma_f32_16x16x32_bf16 v[92:95], v[150:153], v[234:237], v[92:95]
	v_mfma_f32_16x16x32_bf16 v[84:87], v[158:161], v[234:237], v[84:87]
	v_mfma_f32_16x16x32_bf16 v[76:79], v[150:153], v[242:245], v[76:79]
	v_mfma_f32_16x16x32_bf16 v[68:71], v[158:161], v[242:245], v[68:71]
	s_setprio 0
	s_setprio 1
	v_mfma_f32_16x16x32_bf16 v[122:125], v[162:165], v[178:181], 0
	v_mfma_f32_16x16x32_bf16 v[114:117], v[170:173], v[178:181], 0
	v_mfma_f32_16x16x32_bf16 v[104:107], v[162:165], v[186:189], 0
	v_mfma_f32_16x16x32_bf16 v[96:99], v[170:173], v[186:189], 0
	v_mfma_f32_16x16x32_bf16 v[88:91], v[162:165], v[230:233], 0
	v_mfma_f32_16x16x32_bf16 v[80:83], v[170:173], v[230:233], 0
	v_mfma_f32_16x16x32_bf16 v[72:75], v[162:165], v[238:241], 0
	v_mfma_f32_16x16x32_bf16 v[64:67], v[170:173], v[238:241], 0
	v_mfma_f32_16x16x32_bf16 v[122:125], v[166:169], v[182:185], v[122:125]
	v_mfma_f32_16x16x32_bf16 v[114:117], v[174:177], v[182:185], v[114:117]
	v_mfma_f32_16x16x32_bf16 v[104:107], v[166:169], v[208:211], v[104:107]
	v_mfma_f32_16x16x32_bf16 v[96:99], v[174:177], v[208:211], v[96:99]
	v_mfma_f32_16x16x32_bf16 v[88:91], v[166:169], v[234:237], v[88:91]
	v_mfma_f32_16x16x32_bf16 v[80:83], v[174:177], v[234:237], v[80:83]
	v_mfma_f32_16x16x32_bf16 v[72:75], v[166:169], v[242:245], v[72:75]
	v_mfma_f32_16x16x32_bf16 v[64:67], v[174:177], v[242:245], v[64:67]
	s_setprio 0
	s_barrier
	s_add_i32 s55, s55, s35
	s_mov_b32 m0, s55
	ds_read_b128 v[178:181], v149 offset:16384
	ds_read_b128 v[182:185], v149 offset:17408
	ds_read_b128 v[186:189], v149 offset:18432
	ds_read_b128 v[208:211], v149 offset:19456
	ds_read_b128 v[230:233], v149 offset:20480
	ds_read_b128 v[234:237], v149 offset:21504
	ds_read_b128 v[238:241], v149 offset:22528
	ds_read_b128 v[242:245], v149 offset:23552
	global_load_lds_dwordx4 v112, s[26:27]
	s_add_i32 m0, s55, 0x2000
	s_add_u32 s56, s26, 0x40000
	v_lshl_add_u64 v[246:247], s[26:27], 0, v[134:135]
	s_addc_u32 s57, s27, 0
	s_add_i32 s55, s58, s35
	global_load_lds_dwordx4 v134, s[26:27]
	s_mov_b32 m0, s55
	v_lshl_add_u64 v[250:251], s[28:29], 0, v[132:133]
	global_load_lds_dwordx4 v112, s[56:57]
	s_add_i32 m0, s55, 0x2000
	s_nop 0
	global_load_lds_dwordx4 v134, s[56:57]
	v_lshl_add_u64 v[248:249], s[28:29], 0, v[130:131]
	s_mov_b32 m0, s23
	s_nop 0
	global_load_lds_dwordx4 v130, s[28:29]
	s_mov_b32 m0, s44
	s_nop 0
	global_load_lds_dwordx4 v132, s[28:29]
	s_waitcnt vmcnt(8)
	s_waitcnt lgkmcnt(0)
	s_barrier
	s_setprio 1
	s_waitcnt lgkmcnt(0)
	v_mfma_f32_16x16x32_bf16 v[60:63], v[140:143], v[178:181], 0
	v_mfma_f32_16x16x32_bf16 v[52:55], v[154:157], v[178:181], 0
	v_mfma_f32_16x16x32_bf16 v[44:47], v[140:143], v[186:189], 0
	v_mfma_f32_16x16x32_bf16 v[36:39], v[154:157], v[186:189], 0
	v_mfma_f32_16x16x32_bf16 v[28:31], v[140:143], v[230:233], 0
	v_mfma_f32_16x16x32_bf16 v[20:23], v[154:157], v[230:233], 0
	v_mfma_f32_16x16x32_bf16 v[12:15], v[140:143], v[238:241], 0
	v_mfma_f32_16x16x32_bf16 v[4:7], v[154:157], v[238:241], 0
	v_mfma_f32_16x16x32_bf16 v[60:63], v[150:153], v[182:185], v[60:63]
	v_mfma_f32_16x16x32_bf16 v[52:55], v[158:161], v[182:185], v[52:55]
	v_mfma_f32_16x16x32_bf16 v[44:47], v[150:153], v[208:211], v[44:47]
	v_mfma_f32_16x16x32_bf16 v[36:39], v[158:161], v[208:211], v[36:39]
	v_mfma_f32_16x16x32_bf16 v[28:31], v[150:153], v[234:237], v[28:31]
	v_mfma_f32_16x16x32_bf16 v[20:23], v[158:161], v[234:237], v[20:23]
	v_mfma_f32_16x16x32_bf16 v[12:15], v[150:153], v[242:245], v[12:15]
	v_mfma_f32_16x16x32_bf16 v[4:7], v[158:161], v[242:245], v[4:7]
	s_setprio 0
	s_setprio 1
	v_mfma_f32_16x16x32_bf16 v[56:59], v[162:165], v[178:181], 0
	v_mfma_f32_16x16x32_bf16 v[48:51], v[170:173], v[178:181], 0
	v_mfma_f32_16x16x32_bf16 v[40:43], v[162:165], v[186:189], 0
	v_mfma_f32_16x16x32_bf16 v[32:35], v[170:173], v[186:189], 0
	v_mfma_f32_16x16x32_bf16 v[24:27], v[162:165], v[230:233], 0
	v_mfma_f32_16x16x32_bf16 v[16:19], v[170:173], v[230:233], 0
	v_mfma_f32_16x16x32_bf16 v[8:11], v[162:165], v[238:241], 0
	v_mfma_f32_16x16x32_bf16 v[0:3], v[170:173], v[238:241], 0
	v_mfma_f32_16x16x32_bf16 v[56:59], v[166:169], v[182:185], v[56:59]
	v_mfma_f32_16x16x32_bf16 v[48:51], v[174:177], v[182:185], v[48:51]
	v_mfma_f32_16x16x32_bf16 v[40:43], v[166:169], v[208:211], v[40:43]
	v_mfma_f32_16x16x32_bf16 v[32:35], v[174:177], v[208:211], v[32:35]
	v_mfma_f32_16x16x32_bf16 v[24:27], v[166:169], v[234:237], v[24:27]
	v_mfma_f32_16x16x32_bf16 v[16:19], v[174:177], v[234:237], v[16:19]
	v_mfma_f32_16x16x32_bf16 v[8:11], v[166:169], v[242:245], v[8:11]
	v_mfma_f32_16x16x32_bf16 v[0:3], v[174:177], v[242:245], v[0:3]
	s_setprio 0
	s_barrier
	s_add_i32 s55, 0, 0x18000
	v_add_u32_e32 v144, s55, v146
	s_add_i32 s56, 0, 0x1c000
	ds_read_b128 v[140:143], v144
	ds_read_b128 v[150:153], v144 offset:1024
	ds_read_b128 v[154:157], v144 offset:2048
	ds_read_b128 v[158:161], v144 offset:3072
	v_add_u32_e32 v144, s56, v146
	ds_read_b128 v[162:165], v144
	ds_read_b128 v[166:169], v144 offset:1024
	ds_read_b128 v[170:173], v144 offset:2048
	ds_read_b128 v[174:177], v144 offset:3072
	s_add_u32 s28, s28, 0x40000
	s_addc_u32 s29, s29, 0
	s_mov_b32 m0, s45
	ds_read_b128 v[178:181], v149 offset:32768
	ds_read_b128 v[182:185], v149 offset:33792
	ds_read_b128 v[186:189], v149 offset:34816
	ds_read_b128 v[208:211], v149 offset:35840
	ds_read_b128 v[230:233], v149 offset:36864
	ds_read_b128 v[234:237], v149 offset:37888
	ds_read_b128 v[238:241], v149 offset:38912
	ds_read_b128 v[242:245], v149 offset:39936
	global_load_lds_dwordx4 v130, s[28:29]
	s_mov_b32 m0, s46
	s_nop 0
	global_load_lds_dwordx4 v132, s[28:29]
	s_waitcnt vmcnt(8)
	s_waitcnt lgkmcnt(0)
	s_barrier
	s_setprio 1
	s_waitcnt lgkmcnt(0)
	v_mfma_f32_16x16x32_bf16 v[126:129], v[140:143], v[178:181], v[126:129]
	v_mfma_f32_16x16x32_bf16 v[118:121], v[154:157], v[178:181], v[118:121]
	v_mfma_f32_16x16x32_bf16 v[108:111], v[140:143], v[186:189], v[108:111]
	v_mfma_f32_16x16x32_bf16 v[100:103], v[154:157], v[186:189], v[100:103]
	v_mfma_f32_16x16x32_bf16 v[92:95], v[140:143], v[230:233], v[92:95]
	v_mfma_f32_16x16x32_bf16 v[84:87], v[154:157], v[230:233], v[84:87]
	v_mfma_f32_16x16x32_bf16 v[76:79], v[140:143], v[238:241], v[76:79]
	v_mfma_f32_16x16x32_bf16 v[68:71], v[154:157], v[238:241], v[68:71]
	v_mfma_f32_16x16x32_bf16 v[126:129], v[150:153], v[182:185], v[126:129]
	v_mfma_f32_16x16x32_bf16 v[118:121], v[158:161], v[182:185], v[118:121]
	v_mfma_f32_16x16x32_bf16 v[108:111], v[150:153], v[208:211], v[108:111]
	v_mfma_f32_16x16x32_bf16 v[100:103], v[158:161], v[208:211], v[100:103]
	v_mfma_f32_16x16x32_bf16 v[92:95], v[150:153], v[234:237], v[92:95]
	v_mfma_f32_16x16x32_bf16 v[84:87], v[158:161], v[234:237], v[84:87]
	v_mfma_f32_16x16x32_bf16 v[76:79], v[150:153], v[242:245], v[76:79]
	v_mfma_f32_16x16x32_bf16 v[68:71], v[158:161], v[242:245], v[68:71]
	s_setprio 0
	s_setprio 1
	v_mfma_f32_16x16x32_bf16 v[122:125], v[162:165], v[178:181], v[122:125]
	v_mfma_f32_16x16x32_bf16 v[114:117], v[170:173], v[178:181], v[114:117]
	v_mfma_f32_16x16x32_bf16 v[104:107], v[162:165], v[186:189], v[104:107]
	v_mfma_f32_16x16x32_bf16 v[96:99], v[170:173], v[186:189], v[96:99]
	v_mfma_f32_16x16x32_bf16 v[88:91], v[162:165], v[230:233], v[88:91]
	v_mfma_f32_16x16x32_bf16 v[80:83], v[170:173], v[230:233], v[80:83]
	v_mfma_f32_16x16x32_bf16 v[72:75], v[162:165], v[238:241], v[72:75]
	v_mfma_f32_16x16x32_bf16 v[64:67], v[170:173], v[238:241], v[64:67]
	v_mfma_f32_16x16x32_bf16 v[122:125], v[166:169], v[182:185], v[122:125]
	v_mfma_f32_16x16x32_bf16 v[114:117], v[174:177], v[182:185], v[114:117]
	v_mfma_f32_16x16x32_bf16 v[104:107], v[166:169], v[208:211], v[104:107]
	v_mfma_f32_16x16x32_bf16 v[96:99], v[174:177], v[208:211], v[96:99]
	v_mfma_f32_16x16x32_bf16 v[88:91], v[166:169], v[234:237], v[88:91]
	v_mfma_f32_16x16x32_bf16 v[80:83], v[174:177], v[234:237], v[80:83]
	v_mfma_f32_16x16x32_bf16 v[72:75], v[166:169], v[242:245], v[72:75]
	v_mfma_f32_16x16x32_bf16 v[64:67], v[174:177], v[242:245], v[64:67]
	s_setprio 0
	s_barrier
	s_add_i32 s28, s55, s35
	s_mov_b32 m0, s28
	ds_read_b128 v[178:181], v149 offset:49152
	ds_read_b128 v[182:185], v149 offset:50176
	ds_read_b128 v[186:189], v149 offset:51200
	ds_read_b128 v[208:211], v149 offset:52224
	ds_read_b128 v[230:233], v149 offset:53248
	ds_read_b128 v[234:237], v149 offset:54272
	ds_read_b128 v[238:241], v149 offset:55296
	ds_read_b128 v[242:245], v149 offset:56320
	s_add_u32 s98, s26, 0x80
	s_addc_u32 s99, s27, 0
	global_load_lds_dwordx4 v112, s[98:99]
	s_add_i32 m0, s28, 0x2000
	s_add_u32 s26, s26, 0x40080
	v_lshl_add_u64 v[212:213], v[246:247], 0, s[96:97]
	s_addc_u32 s27, s27, 0
	s_add_i32 s28, s56, s35
	global_load_lds_dwordx4 v[212:213], off
	s_mov_b32 m0, s28
	s_nop 0
	global_load_lds_dwordx4 v112, s[26:27]
	s_add_i32 m0, s28, 0x2000
	s_nop 0
	global_load_lds_dwordx4 v134, s[26:27]
	v_lshl_add_u64 v[212:213], v[248:249], 0, s[96:97]
	s_mov_b32 m0, s47
	s_nop 0
	global_load_lds_dwordx4 v[212:213], off
	v_lshl_add_u64 v[212:213], v[250:251], 0, s[96:97]
	s_mov_b32 m0, s48
	s_nop 0
	global_load_lds_dwordx4 v[212:213], off
	s_waitcnt vmcnt(8)
	s_waitcnt lgkmcnt(0)
	s_barrier
	s_setprio 1
	s_waitcnt lgkmcnt(0)
	v_mfma_f32_16x16x32_bf16 v[60:63], v[140:143], v[178:181], v[60:63]
	v_mfma_f32_16x16x32_bf16 v[52:55], v[154:157], v[178:181], v[52:55]
	v_mfma_f32_16x16x32_bf16 v[44:47], v[140:143], v[186:189], v[44:47]
	v_mfma_f32_16x16x32_bf16 v[36:39], v[154:157], v[186:189], v[36:39]
	v_mfma_f32_16x16x32_bf16 v[28:31], v[140:143], v[230:233], v[28:31]
	v_mfma_f32_16x16x32_bf16 v[20:23], v[154:157], v[230:233], v[20:23]
	v_mfma_f32_16x16x32_bf16 v[12:15], v[140:143], v[238:241], v[12:15]
	v_mfma_f32_16x16x32_bf16 v[4:7], v[154:157], v[238:241], v[4:7]
	v_mfma_f32_16x16x32_bf16 v[60:63], v[150:153], v[182:185], v[60:63]
	v_mfma_f32_16x16x32_bf16 v[52:55], v[158:161], v[182:185], v[52:55]
	v_mfma_f32_16x16x32_bf16 v[44:47], v[150:153], v[208:211], v[44:47]
	v_mfma_f32_16x16x32_bf16 v[36:39], v[158:161], v[208:211], v[36:39]
	v_mfma_f32_16x16x32_bf16 v[28:31], v[150:153], v[234:237], v[28:31]
	v_mfma_f32_16x16x32_bf16 v[20:23], v[158:161], v[234:237], v[20:23]
	v_mfma_f32_16x16x32_bf16 v[12:15], v[150:153], v[242:245], v[12:15]
	v_mfma_f32_16x16x32_bf16 v[4:7], v[158:161], v[242:245], v[4:7]
	s_setprio 0
	s_setprio 1
	v_mfma_f32_16x16x32_bf16 v[56:59], v[162:165], v[178:181], v[56:59]
	v_mfma_f32_16x16x32_bf16 v[48:51], v[170:173], v[178:181], v[48:51]
	v_mfma_f32_16x16x32_bf16 v[40:43], v[162:165], v[186:189], v[40:43]
	v_mfma_f32_16x16x32_bf16 v[32:35], v[170:173], v[186:189], v[32:35]
	v_mfma_f32_16x16x32_bf16 v[24:27], v[162:165], v[230:233], v[24:27]
	v_mfma_f32_16x16x32_bf16 v[16:19], v[170:173], v[230:233], v[16:19]
	v_mfma_f32_16x16x32_bf16 v[8:11], v[162:165], v[238:241], v[8:11]
	v_mfma_f32_16x16x32_bf16 v[0:3], v[170:173], v[238:241], v[0:3]
	v_mfma_f32_16x16x32_bf16 v[56:59], v[166:169], v[182:185], v[56:59]
	v_mfma_f32_16x16x32_bf16 v[48:51], v[174:177], v[182:185], v[48:51]
	v_mfma_f32_16x16x32_bf16 v[40:43], v[166:169], v[208:211], v[40:43]
	v_mfma_f32_16x16x32_bf16 v[32:35], v[174:177], v[208:211], v[32:35]
	v_mfma_f32_16x16x32_bf16 v[24:27], v[166:169], v[234:237], v[24:27]
	v_mfma_f32_16x16x32_bf16 v[16:19], v[174:177], v[234:237], v[16:19]
	v_mfma_f32_16x16x32_bf16 v[8:11], v[166:169], v[242:245], v[8:11]
	v_mfma_f32_16x16x32_bf16 v[0:3], v[174:177], v[242:245], v[0:3]
	s_setprio 0
	s_barrier
	s_add_i32 s54, s54, 2
	s_add_u32 s52, s52, 0x100
	s_addc_u32 s53, s53, 0
	s_add_u32 s24, s24, 0x100
	s_addc_u32 s25, s25, 0
	s_cmp_gt_u32 s54, 13
	s_cbranch_scc0 .LBB0_1952
	s_branch .Lpeel_exit_1952
.LBB0_1952:
	s_add_u32 s26, s24, 0xfffc0080
	s_addc_u32 s27, s25, -1
	s_add_i32 s55, 0, 0x10000
	s_cmp_eq_u32 s54, 12
	s_cselect_b32 s29, s5, s27
	s_cselect_b32 s28, s17, s26
	v_add_u32_e32 v144, s55, v146
	s_cselect_b32 s27, s15, s53
	s_cselect_b32 s26, s51, s52
	s_add_i32 s58, 0, 0x14000
	ds_read_b128 v[140:143], v144
	ds_read_b128 v[150:153], v144 offset:1024
	ds_read_b128 v[154:157], v144 offset:2048
	ds_read_b128 v[158:161], v144 offset:3072
	v_add_u32_e32 v144, s58, v146
	ds_read_b128 v[162:165], v144
	ds_read_b128 v[166:169], v144 offset:1024
	ds_read_b128 v[170:173], v144 offset:2048
	ds_read_b128 v[174:177], v144 offset:3072
	s_add_i32 m0, s23, 0xc000
	ds_read_b128 v[178:181], v149
	ds_read_b128 v[182:185], v149 offset:1024
	ds_read_b128 v[186:189], v149 offset:2048
	ds_read_b128 v[208:211], v149 offset:3072
	ds_read_b128 v[230:233], v149 offset:4096
	ds_read_b128 v[234:237], v149 offset:5120
	ds_read_b128 v[238:241], v149 offset:6144
	ds_read_b128 v[242:245], v149 offset:7168
	global_load_lds_dwordx4 v138, s[24:25]
	s_add_i32 m0, s23, 0xe000
	s_nop 0
	global_load_lds_dwordx4 v136, s[24:25]
	s_waitcnt vmcnt(8)
	s_waitcnt lgkmcnt(0)
	s_barrier
	s_setprio 1
	s_waitcnt lgkmcnt(0)
	v_mfma_f32_16x16x32_bf16 v[126:129], v[140:143], v[178:181], v[126:129]
	v_mfma_f32_16x16x32_bf16 v[118:121], v[154:157], v[178:181], v[118:121]
	v_mfma_f32_16x16x32_bf16 v[108:111], v[140:143], v[186:189], v[108:111]
	v_mfma_f32_16x16x32_bf16 v[100:103], v[154:157], v[186:189], v[100:103]
	v_mfma_f32_16x16x32_bf16 v[92:95], v[140:143], v[230:233], v[92:95]
	v_mfma_f32_16x16x32_bf16 v[84:87], v[154:157], v[230:233], v[84:87]
	v_mfma_f32_16x16x32_bf16 v[76:79], v[140:143], v[238:241], v[76:79]
	v_mfma_f32_16x16x32_bf16 v[68:71], v[154:157], v[238:241], v[68:71]
	v_mfma_f32_16x16x32_bf16 v[126:129], v[150:153], v[182:185], v[126:129]
	v_mfma_f32_16x16x32_bf16 v[118:121], v[158:161], v[182:185], v[118:121]
	v_mfma_f32_16x16x32_bf16 v[108:111], v[150:153], v[208:211], v[108:111]
	v_mfma_f32_16x16x32_bf16 v[100:103], v[158:161], v[208:211], v[100:103]
	v_mfma_f32_16x16x32_bf16 v[92:95], v[150:153], v[234:237], v[92:95]
	v_mfma_f32_16x16x32_bf16 v[84:87], v[158:161], v[234:237], v[84:87]
	v_mfma_f32_16x16x32_bf16 v[76:79], v[150:153], v[242:245], v[76:79]
	v_mfma_f32_16x16x32_bf16 v[68:71], v[158:161], v[242:245], v[68:71]
	s_setprio 0
	s_setprio 1
	v_mfma_f32_16x16x32_bf16 v[122:125], v[162:165], v[178:181], v[122:125]
	v_mfma_f32_16x16x32_bf16 v[114:117], v[170:173], v[178:181], v[114:117]
	v_mfma_f32_16x16x32_bf16 v[104:107], v[162:165], v[186:189], v[104:107]
	v_mfma_f32_16x16x32_bf16 v[96:99], v[170:173], v[186:189], v[96:99]
	v_mfma_f32_16x16x32_bf16 v[88:91], v[162:165], v[230:233], v[88:91]
	v_mfma_f32_16x16x32_bf16 v[80:83], v[170:173], v[230:233], v[80:83]
	v_mfma_f32_16x16x32_bf16 v[72:75], v[162:165], v[238:241], v[72:75]
	v_mfma_f32_16x16x32_bf16 v[64:67], v[170:173], v[238:241], v[64:67]
	v_mfma_f32_16x16x32_bf16 v[122:125], v[166:169], v[182:185], v[122:125]
	v_mfma_f32_16x16x32_bf16 v[114:117], v[174:177], v[182:185], v[114:117]
	v_mfma_f32_16x16x32_bf16 v[104:107], v[166:169], v[208:211], v[104:107]
	v_mfma_f32_16x16x32_bf16 v[96:99], v[174:177], v[208:211], v[96:99]
	v_mfma_f32_16x16x32_bf16 v[88:91], v[166:169], v[234:237], v[88:91]
	v_mfma_f32_16x16x32_bf16 v[80:83], v[174:177], v[234:237], v[80:83]
	v_mfma_f32_16x16x32_bf16 v[72:75], v[166:169], v[242:245], v[72:75]
	v_mfma_f32_16x16x32_bf16 v[64:67], v[174:177], v[242:245], v[64:67]
	s_setprio 0
	s_barrier
	s_add_i32 s55, s55, s35
	s_mov_b32 m0, s55
	ds_read_b128 v[178:181], v149 offset:16384
	ds_read_b128 v[182:185], v149 offset:17408
	ds_read_b128 v[186:189], v149 offset:18432
	ds_read_b128 v[208:211], v149 offset:19456
	ds_read_b128 v[230:233], v149 offset:20480
	ds_read_b128 v[234:237], v149 offset:21504
	ds_read_b128 v[238:241], v149 offset:22528
	ds_read_b128 v[242:245], v149 offset:23552
	global_load_lds_dwordx4 v112, s[26:27]
	s_add_i32 m0, s55, 0x2000
	s_add_u32 s56, s26, 0x40000
	v_lshl_add_u64 v[246:247], s[26:27], 0, v[134:135]
	s_addc_u32 s57, s27, 0
	s_add_i32 s55, s58, s35
	global_load_lds_dwordx4 v134, s[26:27]
	s_mov_b32 m0, s55
	v_lshl_add_u64 v[250:251], s[28:29], 0, v[132:133]
	global_load_lds_dwordx4 v112, s[56:57]
	s_add_i32 m0, s55, 0x2000
	s_nop 0
	global_load_lds_dwordx4 v134, s[56:57]
	v_lshl_add_u64 v[248:249], s[28:29], 0, v[130:131]
	s_mov_b32 m0, s23
	s_nop 0
	global_load_lds_dwordx4 v130, s[28:29]
	s_mov_b32 m0, s44
	s_nop 0
	global_load_lds_dwordx4 v132, s[28:29]
	s_waitcnt vmcnt(8)
	s_waitcnt lgkmcnt(0)
	s_barrier
	s_setprio 1
	s_waitcnt lgkmcnt(0)
	v_mfma_f32_16x16x32_bf16 v[60:63], v[140:143], v[178:181], v[60:63]
	v_mfma_f32_16x16x32_bf16 v[52:55], v[154:157], v[178:181], v[52:55]
	v_mfma_f32_16x16x32_bf16 v[44:47], v[140:143], v[186:189], v[44:47]
	v_mfma_f32_16x16x32_bf16 v[36:39], v[154:157], v[186:189], v[36:39]
	v_mfma_f32_16x16x32_bf16 v[28:31], v[140:143], v[230:233], v[28:31]
	v_mfma_f32_16x16x32_bf16 v[20:23], v[154:157], v[230:233], v[20:23]
	v_mfma_f32_16x16x32_bf16 v[12:15], v[140:143], v[238:241], v[12:15]
	v_mfma_f32_16x16x32_bf16 v[4:7], v[154:157], v[238:241], v[4:7]
	v_mfma_f32_16x16x32_bf16 v[60:63], v[150:153], v[182:185], v[60:63]
	v_mfma_f32_16x16x32_bf16 v[52:55], v[158:161], v[182:185], v[52:55]
	v_mfma_f32_16x16x32_bf16 v[44:47], v[150:153], v[208:211], v[44:47]
	v_mfma_f32_16x16x32_bf16 v[36:39], v[158:161], v[208:211], v[36:39]
	v_mfma_f32_16x16x32_bf16 v[28:31], v[150:153], v[234:237], v[28:31]
	v_mfma_f32_16x16x32_bf16 v[20:23], v[158:161], v[234:237], v[20:23]
	v_mfma_f32_16x16x32_bf16 v[12:15], v[150:153], v[242:245], v[12:15]
	v_mfma_f32_16x16x32_bf16 v[4:7], v[158:161], v[242:245], v[4:7]
	s_setprio 0
	s_setprio 1
	v_mfma_f32_16x16x32_bf16 v[56:59], v[162:165], v[178:181], v[56:59]
	v_mfma_f32_16x16x32_bf16 v[48:51], v[170:173], v[178:181], v[48:51]
	v_mfma_f32_16x16x32_bf16 v[40:43], v[162:165], v[186:189], v[40:43]
	v_mfma_f32_16x16x32_bf16 v[32:35], v[170:173], v[186:189], v[32:35]
	v_mfma_f32_16x16x32_bf16 v[24:27], v[162:165], v[230:233], v[24:27]
	v_mfma_f32_16x16x32_bf16 v[16:19], v[170:173], v[230:233], v[16:19]
	v_mfma_f32_16x16x32_bf16 v[8:11], v[162:165], v[238:241], v[8:11]
	v_mfma_f32_16x16x32_bf16 v[0:3], v[170:173], v[238:241], v[0:3]
	v_mfma_f32_16x16x32_bf16 v[56:59], v[166:169], v[182:185], v[56:59]
	v_mfma_f32_16x16x32_bf16 v[48:51], v[174:177], v[182:185], v[48:51]
	v_mfma_f32_16x16x32_bf16 v[40:43], v[166:169], v[208:211], v[40:43]
	v_mfma_f32_16x16x32_bf16 v[32:35], v[174:177], v[208:211], v[32:35]
	v_mfma_f32_16x16x32_bf16 v[24:27], v[166:169], v[234:237], v[24:27]
	v_mfma_f32_16x16x32_bf16 v[16:19], v[174:177], v[234:237], v[16:19]
	v_mfma_f32_16x16x32_bf16 v[8:11], v[166:169], v[242:245], v[8:11]
	v_mfma_f32_16x16x32_bf16 v[0:3], v[174:177], v[242:245], v[0:3]
	s_setprio 0
	s_barrier
	s_add_i32 s55, 0, 0x18000
	v_add_u32_e32 v144, s55, v146
	s_add_i32 s56, 0, 0x1c000
	ds_read_b128 v[140:143], v144
	ds_read_b128 v[150:153], v144 offset:1024
	ds_read_b128 v[154:157], v144 offset:2048
	ds_read_b128 v[158:161], v144 offset:3072
	v_add_u32_e32 v144, s56, v146
	ds_read_b128 v[162:165], v144
	ds_read_b128 v[166:169], v144 offset:1024
	ds_read_b128 v[170:173], v144 offset:2048
	ds_read_b128 v[174:177], v144 offset:3072
	s_add_u32 s28, s28, 0x40000
	s_addc_u32 s29, s29, 0
	s_mov_b32 m0, s45
	ds_read_b128 v[178:181], v149 offset:32768
	ds_read_b128 v[182:185], v149 offset:33792
	ds_read_b128 v[186:189], v149 offset:34816
	ds_read_b128 v[208:211], v149 offset:35840
	ds_read_b128 v[230:233], v149 offset:36864
	ds_read_b128 v[234:237], v149 offset:37888
	ds_read_b128 v[238:241], v149 offset:38912
	ds_read_b128 v[242:245], v149 offset:39936
	global_load_lds_dwordx4 v130, s[28:29]
	s_mov_b32 m0, s46
	s_nop 0
	global_load_lds_dwordx4 v132, s[28:29]
	s_waitcnt vmcnt(8)
	s_waitcnt lgkmcnt(0)
	s_barrier
	s_setprio 1
	s_waitcnt lgkmcnt(0)
	v_mfma_f32_16x16x32_bf16 v[126:129], v[140:143], v[178:181], v[126:129]
	v_mfma_f32_16x16x32_bf16 v[118:121], v[154:157], v[178:181], v[118:121]
	v_mfma_f32_16x16x32_bf16 v[108:111], v[140:143], v[186:189], v[108:111]
	v_mfma_f32_16x16x32_bf16 v[100:103], v[154:157], v[186:189], v[100:103]
	v_mfma_f32_16x16x32_bf16 v[92:95], v[140:143], v[230:233], v[92:95]
	v_mfma_f32_16x16x32_bf16 v[84:87], v[154:157], v[230:233], v[84:87]
	v_mfma_f32_16x16x32_bf16 v[76:79], v[140:143], v[238:241], v[76:79]
	v_mfma_f32_16x16x32_bf16 v[68:71], v[154:157], v[238:241], v[68:71]
	v_mfma_f32_16x16x32_bf16 v[126:129], v[150:153], v[182:185], v[126:129]
	v_mfma_f32_16x16x32_bf16 v[118:121], v[158:161], v[182:185], v[118:121]
	v_mfma_f32_16x16x32_bf16 v[108:111], v[150:153], v[208:211], v[108:111]
	v_mfma_f32_16x16x32_bf16 v[100:103], v[158:161], v[208:211], v[100:103]
	v_mfma_f32_16x16x32_bf16 v[92:95], v[150:153], v[234:237], v[92:95]
	v_mfma_f32_16x16x32_bf16 v[84:87], v[158:161], v[234:237], v[84:87]
	v_mfma_f32_16x16x32_bf16 v[76:79], v[150:153], v[242:245], v[76:79]
	v_mfma_f32_16x16x32_bf16 v[68:71], v[158:161], v[242:245], v[68:71]
	s_setprio 0
	s_setprio 1
	v_mfma_f32_16x16x32_bf16 v[122:125], v[162:165], v[178:181], v[122:125]
	v_mfma_f32_16x16x32_bf16 v[114:117], v[170:173], v[178:181], v[114:117]
	v_mfma_f32_16x16x32_bf16 v[104:107], v[162:165], v[186:189], v[104:107]
	v_mfma_f32_16x16x32_bf16 v[96:99], v[170:173], v[186:189], v[96:99]
	v_mfma_f32_16x16x32_bf16 v[88:91], v[162:165], v[230:233], v[88:91]
	v_mfma_f32_16x16x32_bf16 v[80:83], v[170:173], v[230:233], v[80:83]
	v_mfma_f32_16x16x32_bf16 v[72:75], v[162:165], v[238:241], v[72:75]
	v_mfma_f32_16x16x32_bf16 v[64:67], v[170:173], v[238:241], v[64:67]
	v_mfma_f32_16x16x32_bf16 v[122:125], v[166:169], v[182:185], v[122:125]
	v_mfma_f32_16x16x32_bf16 v[114:117], v[174:177], v[182:185], v[114:117]
	v_mfma_f32_16x16x32_bf16 v[104:107], v[166:169], v[208:211], v[104:107]
	v_mfma_f32_16x16x32_bf16 v[96:99], v[174:177], v[208:211], v[96:99]
	v_mfma_f32_16x16x32_bf16 v[88:91], v[166:169], v[234:237], v[88:91]
	v_mfma_f32_16x16x32_bf16 v[80:83], v[174:177], v[234:237], v[80:83]
	v_mfma_f32_16x16x32_bf16 v[72:75], v[166:169], v[242:245], v[72:75]
	v_mfma_f32_16x16x32_bf16 v[64:67], v[174:177], v[242:245], v[64:67]
	s_setprio 0
	s_barrier
	s_add_i32 s28, s55, s35
	s_mov_b32 m0, s28
	ds_read_b128 v[178:181], v149 offset:49152
	ds_read_b128 v[182:185], v149 offset:50176
	ds_read_b128 v[186:189], v149 offset:51200
	ds_read_b128 v[208:211], v149 offset:52224
	ds_read_b128 v[230:233], v149 offset:53248
	ds_read_b128 v[234:237], v149 offset:54272
	ds_read_b128 v[238:241], v149 offset:55296
	ds_read_b128 v[242:245], v149 offset:56320
	s_add_u32 s98, s26, 0x80
	s_addc_u32 s99, s27, 0
	global_load_lds_dwordx4 v112, s[98:99]
	s_add_i32 m0, s28, 0x2000
	s_add_u32 s26, s26, 0x40080
	v_lshl_add_u64 v[212:213], v[246:247], 0, s[96:97]
	s_addc_u32 s27, s27, 0
	s_add_i32 s28, s56, s35
	global_load_lds_dwordx4 v[212:213], off
	s_mov_b32 m0, s28
	s_nop 0
	global_load_lds_dwordx4 v112, s[26:27]
	s_add_i32 m0, s28, 0x2000
	s_nop 0
	global_load_lds_dwordx4 v134, s[26:27]
	v_lshl_add_u64 v[212:213], v[248:249], 0, s[96:97]
	s_mov_b32 m0, s47
	s_nop 0
	global_load_lds_dwordx4 v[212:213], off
	v_lshl_add_u64 v[212:213], v[250:251], 0, s[96:97]
	s_mov_b32 m0, s48
	s_nop 0
	global_load_lds_dwordx4 v[212:213], off
	s_waitcnt vmcnt(8)
	s_waitcnt lgkmcnt(0)
	s_barrier
	s_setprio 1
	s_waitcnt lgkmcnt(0)
	v_mfma_f32_16x16x32_bf16 v[60:63], v[140:143], v[178:181], v[60:63]
	v_mfma_f32_16x16x32_bf16 v[52:55], v[154:157], v[178:181], v[52:55]
	v_mfma_f32_16x16x32_bf16 v[44:47], v[140:143], v[186:189], v[44:47]
	v_mfma_f32_16x16x32_bf16 v[36:39], v[154:157], v[186:189], v[36:39]
	v_mfma_f32_16x16x32_bf16 v[28:31], v[140:143], v[230:233], v[28:31]
	v_mfma_f32_16x16x32_bf16 v[20:23], v[154:157], v[230:233], v[20:23]
	v_mfma_f32_16x16x32_bf16 v[12:15], v[140:143], v[238:241], v[12:15]
	v_mfma_f32_16x16x32_bf16 v[4:7], v[154:157], v[238:241], v[4:7]
	v_mfma_f32_16x16x32_bf16 v[60:63], v[150:153], v[182:185], v[60:63]
	v_mfma_f32_16x16x32_bf16 v[52:55], v[158:161], v[182:185], v[52:55]
	v_mfma_f32_16x16x32_bf16 v[44:47], v[150:153], v[208:211], v[44:47]
	v_mfma_f32_16x16x32_bf16 v[36:39], v[158:161], v[208:211], v[36:39]
	v_mfma_f32_16x16x32_bf16 v[28:31], v[150:153], v[234:237], v[28:31]
	v_mfma_f32_16x16x32_bf16 v[20:23], v[158:161], v[234:237], v[20:23]
	v_mfma_f32_16x16x32_bf16 v[12:15], v[150:153], v[242:245], v[12:15]
	v_mfma_f32_16x16x32_bf16 v[4:7], v[158:161], v[242:245], v[4:7]
	s_setprio 0
	s_setprio 1
	v_mfma_f32_16x16x32_bf16 v[56:59], v[162:165], v[178:181], v[56:59]
	v_mfma_f32_16x16x32_bf16 v[48:51], v[170:173], v[178:181], v[48:51]
	v_mfma_f32_16x16x32_bf16 v[40:43], v[162:165], v[186:189], v[40:43]
	v_mfma_f32_16x16x32_bf16 v[32:35], v[170:173], v[186:189], v[32:35]
	v_mfma_f32_16x16x32_bf16 v[24:27], v[162:165], v[230:233], v[24:27]
	v_mfma_f32_16x16x32_bf16 v[16:19], v[170:173], v[230:233], v[16:19]
	v_mfma_f32_16x16x32_bf16 v[8:11], v[162:165], v[238:241], v[8:11]
	v_mfma_f32_16x16x32_bf16 v[0:3], v[170:173], v[238:241], v[0:3]
	v_mfma_f32_16x16x32_bf16 v[56:59], v[166:169], v[182:185], v[56:59]
	v_mfma_f32_16x16x32_bf16 v[48:51], v[174:177], v[182:185], v[48:51]
	v_mfma_f32_16x16x32_bf16 v[40:43], v[166:169], v[208:211], v[40:43]
	v_mfma_f32_16x16x32_bf16 v[32:35], v[174:177], v[208:211], v[32:35]
	v_mfma_f32_16x16x32_bf16 v[24:27], v[166:169], v[234:237], v[24:27]
	v_mfma_f32_16x16x32_bf16 v[16:19], v[174:177], v[234:237], v[16:19]
	v_mfma_f32_16x16x32_bf16 v[8:11], v[166:169], v[242:245], v[8:11]
	v_mfma_f32_16x16x32_bf16 v[0:3], v[174:177], v[242:245], v[0:3]
	s_setprio 0
	s_barrier
	s_add_i32 s54, s54, 2
	s_add_u32 s52, s52, 0x100
	s_addc_u32 s53, s53, 0
	s_add_u32 s24, s24, 0x100
	s_addc_u32 s25, s25, 0
	s_cmp_gt_u32 s54, 13
	s_cbranch_scc0 .LBB0_1952

.LBB0_2150:
	s_ashr_i32 s29, s28, 31
	s_lshl_b64 s[30:31], s[28:29], 19
	s_add_u32 s30, s49, s30
	s_addc_u32 s31, s50, s31
	s_and_b64 s[40:41], s[6:7], exec
	s_cselect_b32 s11, s31, s39
	s_cselect_b32 s29, s30, s38
	s_ashr_i32 s27, s26, 31
	s_lshl_b64 s[40:41], s[26:27], 19
	s_add_u32 s46, s51, s40
	s_addc_u32 s47, s52, s41
	s_and_b64 s[40:41], s[6:7], exec
	s_cselect_b32 s27, s47, s9
	s_cselect_b32 s35, s46, s8
	s_add_u32 s42, s8, 0x100
	s_addc_u32 s43, s9, 0
	s_add_u32 s8, s38, 0x40080
	s_addc_u32 s9, s39, 0
	s_mov_b32 s44, -2
	s_add_u32 s38, s8, 0xfffc0080
	s_addc_u32 s39, s9, -1
	s_add_i32 s45, 0, 0x10000
	s_cmp_eq_u32 s44, 12
	s_cselect_b32 s41, s11, s39
	s_cselect_b32 s40, s29, s38
	v_add_u32_e32 v112, s45, v169
	s_cselect_b32 s39, s27, s43
	s_cselect_b32 s38, s35, s42
	s_add_i32 s68, 0, 0x14000
	ds_read_b128 v[130:133], v112
	ds_read_b128 v[134:137], v112 offset:1024
	ds_read_b128 v[150:153], v112 offset:2048
	ds_read_b128 v[154:157], v112 offset:3072
	v_add_u32_e32 v112, s68, v169
	ds_read_b128 v[158:161], v112
	ds_read_b128 v[162:165], v112 offset:1024
	ds_read_b128 v[174:177], v112 offset:2048
	ds_read_b128 v[178:181], v112 offset:3072
	s_add_i32 m0, s37, 0xc000
	ds_read_b128 v[182:185], v172
	ds_read_b128 v[186:189], v172 offset:1024
	ds_read_b128 v[208:211], v172 offset:2048
	ds_read_b128 v[230:233], v172 offset:3072
	ds_read_b128 v[234:237], v172 offset:4096
	ds_read_b128 v[238:241], v172 offset:5120
	ds_read_b128 v[242:245], v172 offset:6144
	ds_read_b128 v[246:249], v172 offset:7168
	global_load_lds_dwordx4 v148, s[8:9]
	s_add_i32 m0, s37, 0xe000
	s_nop 0
	global_load_lds_dwordx4 v146, s[8:9]
	s_waitcnt vmcnt(8)
	s_waitcnt lgkmcnt(0)
	s_barrier
	s_setprio 1
	s_waitcnt lgkmcnt(0)
	v_mfma_f32_16x16x32_bf16 v[126:129], v[130:133], v[182:185], 0
	v_mfma_f32_16x16x32_bf16 v[122:125], v[150:153], v[182:185], 0
	v_mfma_f32_16x16x32_bf16 v[108:111], v[130:133], v[208:211], 0
	v_mfma_f32_16x16x32_bf16 v[104:107], v[150:153], v[208:211], 0
	v_mfma_f32_16x16x32_bf16 v[92:95], v[130:133], v[234:237], 0
	v_mfma_f32_16x16x32_bf16 v[88:91], v[150:153], v[234:237], 0
	v_mfma_f32_16x16x32_bf16 v[76:79], v[130:133], v[242:245], 0
	v_mfma_f32_16x16x32_bf16 v[72:75], v[150:153], v[242:245], 0
	v_mfma_f32_16x16x32_bf16 v[126:129], v[134:137], v[186:189], v[126:129]
	v_mfma_f32_16x16x32_bf16 v[122:125], v[154:157], v[186:189], v[122:125]
	v_mfma_f32_16x16x32_bf16 v[108:111], v[134:137], v[230:233], v[108:111]
	v_mfma_f32_16x16x32_bf16 v[104:107], v[154:157], v[230:233], v[104:107]
	v_mfma_f32_16x16x32_bf16 v[92:95], v[134:137], v[238:241], v[92:95]
	v_mfma_f32_16x16x32_bf16 v[88:91], v[154:157], v[238:241], v[88:91]
	v_mfma_f32_16x16x32_bf16 v[76:79], v[134:137], v[246:249], v[76:79]
	v_mfma_f32_16x16x32_bf16 v[72:75], v[154:157], v[246:249], v[72:75]
	s_setprio 0
	s_setprio 1
	v_mfma_f32_16x16x32_bf16 v[118:121], v[158:161], v[182:185], 0
	v_mfma_f32_16x16x32_bf16 v[114:117], v[174:177], v[182:185], 0
	v_mfma_f32_16x16x32_bf16 v[100:103], v[158:161], v[208:211], 0
	v_mfma_f32_16x16x32_bf16 v[96:99], v[174:177], v[208:211], 0
	v_mfma_f32_16x16x32_bf16 v[84:87], v[158:161], v[234:237], 0
	v_mfma_f32_16x16x32_bf16 v[80:83], v[174:177], v[234:237], 0
	v_mfma_f32_16x16x32_bf16 v[68:71], v[158:161], v[242:245], 0
	v_mfma_f32_16x16x32_bf16 v[64:67], v[174:177], v[242:245], 0
	v_mfma_f32_16x16x32_bf16 v[118:121], v[162:165], v[186:189], v[118:121]
	v_mfma_f32_16x16x32_bf16 v[114:117], v[178:181], v[186:189], v[114:117]
	v_mfma_f32_16x16x32_bf16 v[100:103], v[162:165], v[230:233], v[100:103]
	v_mfma_f32_16x16x32_bf16 v[96:99], v[178:181], v[230:233], v[96:99]
	v_mfma_f32_16x16x32_bf16 v[84:87], v[162:165], v[238:241], v[84:87]
	v_mfma_f32_16x16x32_bf16 v[80:83], v[178:181], v[238:241], v[80:83]
	v_mfma_f32_16x16x32_bf16 v[68:71], v[162:165], v[246:249], v[68:71]
	v_mfma_f32_16x16x32_bf16 v[64:67], v[178:181], v[246:249], v[64:67]
	s_setprio 0
	s_barrier
	s_add_i32 s45, s45, s58
	s_mov_b32 m0, s45
	ds_read_b128 v[182:185], v172 offset:16384
	ds_read_b128 v[186:189], v172 offset:17408
	ds_read_b128 v[208:211], v172 offset:18432
	ds_read_b128 v[230:233], v172 offset:19456
	ds_read_b128 v[234:237], v172 offset:20480
	ds_read_b128 v[238:241], v172 offset:21504
	ds_read_b128 v[242:245], v172 offset:22528
	ds_read_b128 v[246:249], v172 offset:23552
	global_load_lds_dwordx4 v140, s[38:39]
	s_add_i32 m0, s45, 0x2000
	s_add_u32 s66, s38, 0x40000
	v_lshl_add_u64 v[212:213], s[38:39], 0, v[144:145]
	s_addc_u32 s67, s39, 0
	s_add_i32 s45, s68, s58
	global_load_lds_dwordx4 v144, s[38:39]
	s_mov_b32 m0, s45
	v_lshl_add_u64 v[250:251], s[40:41], 0, v[142:143]
	global_load_lds_dwordx4 v140, s[66:67]
	s_add_i32 m0, s45, 0x2000
	s_nop 0
	global_load_lds_dwordx4 v144, s[66:67]
	v_lshl_add_u64 v[228:229], s[40:41], 0, v[138:139]
	s_mov_b32 m0, s37
	s_nop 0
	global_load_lds_dwordx4 v138, s[40:41]
	s_mov_b32 m0, s59
	s_nop 0
	global_load_lds_dwordx4 v142, s[40:41]
	s_waitcnt vmcnt(8)
	s_waitcnt lgkmcnt(0)
	s_barrier
	s_setprio 1
	s_waitcnt lgkmcnt(0)
	v_mfma_f32_16x16x32_bf16 v[60:63], v[130:133], v[182:185], 0
	v_mfma_f32_16x16x32_bf16 v[56:59], v[150:153], v[182:185], 0
	v_mfma_f32_16x16x32_bf16 v[44:47], v[130:133], v[208:211], 0
	v_mfma_f32_16x16x32_bf16 v[40:43], v[150:153], v[208:211], 0
	v_mfma_f32_16x16x32_bf16 v[28:31], v[130:133], v[234:237], 0
	v_mfma_f32_16x16x32_bf16 v[24:27], v[150:153], v[234:237], 0
	v_mfma_f32_16x16x32_bf16 v[12:15], v[130:133], v[242:245], 0
	v_mfma_f32_16x16x32_bf16 v[8:11], v[150:153], v[242:245], 0
	v_mfma_f32_16x16x32_bf16 v[60:63], v[134:137], v[186:189], v[60:63]
	v_mfma_f32_16x16x32_bf16 v[56:59], v[154:157], v[186:189], v[56:59]
	v_mfma_f32_16x16x32_bf16 v[44:47], v[134:137], v[230:233], v[44:47]
	v_mfma_f32_16x16x32_bf16 v[40:43], v[154:157], v[230:233], v[40:43]
	v_mfma_f32_16x16x32_bf16 v[28:31], v[134:137], v[238:241], v[28:31]
	v_mfma_f32_16x16x32_bf16 v[24:27], v[154:157], v[238:241], v[24:27]
	v_mfma_f32_16x16x32_bf16 v[12:15], v[134:137], v[246:249], v[12:15]
	v_mfma_f32_16x16x32_bf16 v[8:11], v[154:157], v[246:249], v[8:11]
	s_setprio 0
	s_setprio 1
	v_mfma_f32_16x16x32_bf16 v[52:55], v[158:161], v[182:185], 0
	v_mfma_f32_16x16x32_bf16 v[48:51], v[174:177], v[182:185], 0
	v_mfma_f32_16x16x32_bf16 v[36:39], v[158:161], v[208:211], 0
	v_mfma_f32_16x16x32_bf16 v[32:35], v[174:177], v[208:211], 0
	v_mfma_f32_16x16x32_bf16 v[20:23], v[158:161], v[234:237], 0
	v_mfma_f32_16x16x32_bf16 v[16:19], v[174:177], v[234:237], 0
	v_mfma_f32_16x16x32_bf16 v[4:7], v[158:161], v[242:245], 0
	v_mfma_f32_16x16x32_bf16 v[0:3], v[174:177], v[242:245], 0
	v_mfma_f32_16x16x32_bf16 v[52:55], v[162:165], v[186:189], v[52:55]
	v_mfma_f32_16x16x32_bf16 v[48:51], v[178:181], v[186:189], v[48:51]
	v_mfma_f32_16x16x32_bf16 v[36:39], v[162:165], v[230:233], v[36:39]
	v_mfma_f32_16x16x32_bf16 v[32:35], v[178:181], v[230:233], v[32:35]
	v_mfma_f32_16x16x32_bf16 v[20:23], v[162:165], v[238:241], v[20:23]
	v_mfma_f32_16x16x32_bf16 v[16:19], v[178:181], v[238:241], v[16:19]
	v_mfma_f32_16x16x32_bf16 v[4:7], v[162:165], v[246:249], v[4:7]
	v_mfma_f32_16x16x32_bf16 v[0:3], v[178:181], v[246:249], v[0:3]
	s_setprio 0
	s_barrier
	s_add_i32 s45, 0, 0x18000
	v_add_u32_e32 v112, s45, v169
	s_add_i32 s66, 0, 0x1c000
	ds_read_b128 v[130:133], v112
	ds_read_b128 v[134:137], v112 offset:1024
	ds_read_b128 v[150:153], v112 offset:2048
	ds_read_b128 v[154:157], v112 offset:3072
	v_add_u32_e32 v112, s66, v169
	ds_read_b128 v[158:161], v112
	ds_read_b128 v[162:165], v112 offset:1024
	ds_read_b128 v[174:177], v112 offset:2048
	ds_read_b128 v[178:181], v112 offset:3072
	s_add_u32 s40, s40, 0x40000
	s_addc_u32 s41, s41, 0
	s_mov_b32 m0, s60
	ds_read_b128 v[182:185], v172 offset:32768
	ds_read_b128 v[186:189], v172 offset:33792
	ds_read_b128 v[208:211], v172 offset:34816
	ds_read_b128 v[230:233], v172 offset:35840
	ds_read_b128 v[234:237], v172 offset:36864
	ds_read_b128 v[238:241], v172 offset:37888
	ds_read_b128 v[242:245], v172 offset:38912
	ds_read_b128 v[246:249], v172 offset:39936
	global_load_lds_dwordx4 v138, s[40:41]
	s_mov_b32 m0, s61
	s_nop 0
	global_load_lds_dwordx4 v142, s[40:41]
	s_waitcnt vmcnt(8)
	s_waitcnt lgkmcnt(0)
	s_barrier
	s_setprio 1
	s_waitcnt lgkmcnt(0)
	v_mfma_f32_16x16x32_bf16 v[126:129], v[130:133], v[182:185], v[126:129]
	v_mfma_f32_16x16x32_bf16 v[122:125], v[150:153], v[182:185], v[122:125]
	v_mfma_f32_16x16x32_bf16 v[108:111], v[130:133], v[208:211], v[108:111]
	v_mfma_f32_16x16x32_bf16 v[104:107], v[150:153], v[208:211], v[104:107]
	v_mfma_f32_16x16x32_bf16 v[92:95], v[130:133], v[234:237], v[92:95]
	v_mfma_f32_16x16x32_bf16 v[88:91], v[150:153], v[234:237], v[88:91]
	v_mfma_f32_16x16x32_bf16 v[76:79], v[130:133], v[242:245], v[76:79]
	v_mfma_f32_16x16x32_bf16 v[72:75], v[150:153], v[242:245], v[72:75]
	v_mfma_f32_16x16x32_bf16 v[126:129], v[134:137], v[186:189], v[126:129]
	v_mfma_f32_16x16x32_bf16 v[122:125], v[154:157], v[186:189], v[122:125]
	v_mfma_f32_16x16x32_bf16 v[108:111], v[134:137], v[230:233], v[108:111]
	v_mfma_f32_16x16x32_bf16 v[104:107], v[154:157], v[230:233], v[104:107]
	v_mfma_f32_16x16x32_bf16 v[92:95], v[134:137], v[238:241], v[92:95]
	v_mfma_f32_16x16x32_bf16 v[88:91], v[154:157], v[238:241], v[88:91]
	v_mfma_f32_16x16x32_bf16 v[76:79], v[134:137], v[246:249], v[76:79]
	v_mfma_f32_16x16x32_bf16 v[72:75], v[154:157], v[246:249], v[72:75]
	s_setprio 0
	s_setprio 1
	v_mfma_f32_16x16x32_bf16 v[118:121], v[158:161], v[182:185], v[118:121]
	v_mfma_f32_16x16x32_bf16 v[114:117], v[174:177], v[182:185], v[114:117]
	v_mfma_f32_16x16x32_bf16 v[100:103], v[158:161], v[208:211], v[100:103]
	v_mfma_f32_16x16x32_bf16 v[96:99], v[174:177], v[208:211], v[96:99]
	v_mfma_f32_16x16x32_bf16 v[84:87], v[158:161], v[234:237], v[84:87]
	v_mfma_f32_16x16x32_bf16 v[80:83], v[174:177], v[234:237], v[80:83]
	v_mfma_f32_16x16x32_bf16 v[68:71], v[158:161], v[242:245], v[68:71]
	v_mfma_f32_16x16x32_bf16 v[64:67], v[174:177], v[242:245], v[64:67]
	v_mfma_f32_16x16x32_bf16 v[118:121], v[162:165], v[186:189], v[118:121]
	v_mfma_f32_16x16x32_bf16 v[114:117], v[178:181], v[186:189], v[114:117]
	v_mfma_f32_16x16x32_bf16 v[100:103], v[162:165], v[230:233], v[100:103]
	v_mfma_f32_16x16x32_bf16 v[96:99], v[178:181], v[230:233], v[96:99]
	v_mfma_f32_16x16x32_bf16 v[84:87], v[162:165], v[238:241], v[84:87]
	v_mfma_f32_16x16x32_bf16 v[80:83], v[178:181], v[238:241], v[80:83]
	v_mfma_f32_16x16x32_bf16 v[68:71], v[162:165], v[246:249], v[68:71]
	v_mfma_f32_16x16x32_bf16 v[64:67], v[178:181], v[246:249], v[64:67]
	s_setprio 0
	s_barrier
	s_add_i32 s40, s45, s58
	s_mov_b32 m0, s40
	ds_read_b128 v[182:185], v172 offset:49152
	ds_read_b128 v[186:189], v172 offset:50176
	ds_read_b128 v[208:211], v172 offset:51200
	ds_read_b128 v[230:233], v172 offset:52224
	ds_read_b128 v[234:237], v172 offset:53248
	ds_read_b128 v[238:241], v172 offset:54272
	ds_read_b128 v[242:245], v172 offset:55296
	ds_read_b128 v[246:249], v172 offset:56320
	s_add_u32 s98, s38, 0x80
	s_addc_u32 s99, s39, 0
	global_load_lds_dwordx4 v140, s[98:99]
	s_add_i32 m0, s40, 0x2000
	s_add_u32 s38, s38, 0x40080
	v_lshl_add_u64 v[166:167], v[212:213], 0, s[96:97]
	s_addc_u32 s39, s39, 0
	s_add_i32 s40, s66, s58
	global_load_lds_dwordx4 v[166:167], off
	s_mov_b32 m0, s40
	s_nop 0
	global_load_lds_dwordx4 v140, s[38:39]
	s_add_i32 m0, s40, 0x2000
	s_nop 0
	global_load_lds_dwordx4 v144, s[38:39]
	v_lshl_add_u64 v[166:167], v[228:229], 0, s[96:97]
	s_mov_b32 m0, s62
	s_nop 0
	global_load_lds_dwordx4 v[166:167], off
	v_lshl_add_u64 v[166:167], v[250:251], 0, s[96:97]
	s_mov_b32 m0, s63
	s_nop 0
	global_load_lds_dwordx4 v[166:167], off
	s_waitcnt vmcnt(8)
	s_waitcnt lgkmcnt(0)
	s_barrier
	s_setprio 1
	s_waitcnt lgkmcnt(0)
	v_mfma_f32_16x16x32_bf16 v[60:63], v[130:133], v[182:185], v[60:63]
	v_mfma_f32_16x16x32_bf16 v[56:59], v[150:153], v[182:185], v[56:59]
	v_mfma_f32_16x16x32_bf16 v[44:47], v[130:133], v[208:211], v[44:47]
	v_mfma_f32_16x16x32_bf16 v[40:43], v[150:153], v[208:211], v[40:43]
	v_mfma_f32_16x16x32_bf16 v[28:31], v[130:133], v[234:237], v[28:31]
	v_mfma_f32_16x16x32_bf16 v[24:27], v[150:153], v[234:237], v[24:27]
	v_mfma_f32_16x16x32_bf16 v[12:15], v[130:133], v[242:245], v[12:15]
	v_mfma_f32_16x16x32_bf16 v[8:11], v[150:153], v[242:245], v[8:11]
	v_mfma_f32_16x16x32_bf16 v[60:63], v[134:137], v[186:189], v[60:63]
	v_mfma_f32_16x16x32_bf16 v[56:59], v[154:157], v[186:189], v[56:59]
	v_mfma_f32_16x16x32_bf16 v[44:47], v[134:137], v[230:233], v[44:47]
	v_mfma_f32_16x16x32_bf16 v[40:43], v[154:157], v[230:233], v[40:43]
	v_mfma_f32_16x16x32_bf16 v[28:31], v[134:137], v[238:241], v[28:31]
	v_mfma_f32_16x16x32_bf16 v[24:27], v[154:157], v[238:241], v[24:27]
	v_mfma_f32_16x16x32_bf16 v[12:15], v[134:137], v[246:249], v[12:15]
	v_mfma_f32_16x16x32_bf16 v[8:11], v[154:157], v[246:249], v[8:11]
	s_setprio 0
	s_setprio 1
	v_mfma_f32_16x16x32_bf16 v[52:55], v[158:161], v[182:185], v[52:55]
	v_mfma_f32_16x16x32_bf16 v[48:51], v[174:177], v[182:185], v[48:51]
	v_mfma_f32_16x16x32_bf16 v[36:39], v[158:161], v[208:211], v[36:39]
	v_mfma_f32_16x16x32_bf16 v[32:35], v[174:177], v[208:211], v[32:35]
	v_mfma_f32_16x16x32_bf16 v[20:23], v[158:161], v[234:237], v[20:23]
	v_mfma_f32_16x16x32_bf16 v[16:19], v[174:177], v[234:237], v[16:19]
	v_mfma_f32_16x16x32_bf16 v[4:7], v[158:161], v[242:245], v[4:7]
	v_mfma_f32_16x16x32_bf16 v[0:3], v[174:177], v[242:245], v[0:3]
	v_mfma_f32_16x16x32_bf16 v[52:55], v[162:165], v[186:189], v[52:55]
	v_mfma_f32_16x16x32_bf16 v[48:51], v[178:181], v[186:189], v[48:51]
	v_mfma_f32_16x16x32_bf16 v[36:39], v[162:165], v[230:233], v[36:39]
	v_mfma_f32_16x16x32_bf16 v[32:35], v[178:181], v[230:233], v[32:35]
	v_mfma_f32_16x16x32_bf16 v[20:23], v[162:165], v[238:241], v[20:23]
	v_mfma_f32_16x16x32_bf16 v[16:19], v[178:181], v[238:241], v[16:19]
	v_mfma_f32_16x16x32_bf16 v[4:7], v[162:165], v[246:249], v[4:7]
	v_mfma_f32_16x16x32_bf16 v[0:3], v[178:181], v[246:249], v[0:3]
	s_setprio 0
	s_barrier
	s_add_i32 s44, s44, 2
	s_add_u32 s42, s42, 0x100
	s_addc_u32 s43, s43, 0
	s_add_u32 s8, s8, 0x100
	s_addc_u32 s9, s9, 0
	s_cmp_gt_u32 s44, 13
	s_cbranch_scc0 .LBB0_2151
	s_branch .Lpeel_exit_2151
.LBB0_2151:
	s_add_u32 s38, s8, 0xfffc0080
	s_addc_u32 s39, s9, -1
	s_add_i32 s45, 0, 0x10000
	s_cmp_eq_u32 s44, 12
	s_cselect_b32 s41, s11, s39
	s_cselect_b32 s40, s29, s38
	v_add_u32_e32 v112, s45, v169
	s_cselect_b32 s39, s27, s43
	s_cselect_b32 s38, s35, s42
	s_add_i32 s68, 0, 0x14000
	ds_read_b128 v[130:133], v112
	ds_read_b128 v[134:137], v112 offset:1024
	ds_read_b128 v[150:153], v112 offset:2048
	ds_read_b128 v[154:157], v112 offset:3072
	v_add_u32_e32 v112, s68, v169
	ds_read_b128 v[158:161], v112
	ds_read_b128 v[162:165], v112 offset:1024
	ds_read_b128 v[174:177], v112 offset:2048
	ds_read_b128 v[178:181], v112 offset:3072
	s_add_i32 m0, s37, 0xc000
	ds_read_b128 v[182:185], v172
	ds_read_b128 v[186:189], v172 offset:1024
	ds_read_b128 v[208:211], v172 offset:2048
	ds_read_b128 v[230:233], v172 offset:3072
	ds_read_b128 v[234:237], v172 offset:4096
	ds_read_b128 v[238:241], v172 offset:5120
	ds_read_b128 v[242:245], v172 offset:6144
	ds_read_b128 v[246:249], v172 offset:7168
	global_load_lds_dwordx4 v148, s[8:9]
	s_add_i32 m0, s37, 0xe000
	s_nop 0
	global_load_lds_dwordx4 v146, s[8:9]
	s_waitcnt vmcnt(8)
	s_waitcnt lgkmcnt(0)
	s_barrier
	s_setprio 1
	s_waitcnt lgkmcnt(0)
	v_mfma_f32_16x16x32_bf16 v[126:129], v[130:133], v[182:185], v[126:129]
	v_mfma_f32_16x16x32_bf16 v[122:125], v[150:153], v[182:185], v[122:125]
	v_mfma_f32_16x16x32_bf16 v[108:111], v[130:133], v[208:211], v[108:111]
	v_mfma_f32_16x16x32_bf16 v[104:107], v[150:153], v[208:211], v[104:107]
	v_mfma_f32_16x16x32_bf16 v[92:95], v[130:133], v[234:237], v[92:95]
	v_mfma_f32_16x16x32_bf16 v[88:91], v[150:153], v[234:237], v[88:91]
	v_mfma_f32_16x16x32_bf16 v[76:79], v[130:133], v[242:245], v[76:79]
	v_mfma_f32_16x16x32_bf16 v[72:75], v[150:153], v[242:245], v[72:75]
	v_mfma_f32_16x16x32_bf16 v[126:129], v[134:137], v[186:189], v[126:129]
	v_mfma_f32_16x16x32_bf16 v[122:125], v[154:157], v[186:189], v[122:125]
	v_mfma_f32_16x16x32_bf16 v[108:111], v[134:137], v[230:233], v[108:111]
	v_mfma_f32_16x16x32_bf16 v[104:107], v[154:157], v[230:233], v[104:107]
	v_mfma_f32_16x16x32_bf16 v[92:95], v[134:137], v[238:241], v[92:95]
	v_mfma_f32_16x16x32_bf16 v[88:91], v[154:157], v[238:241], v[88:91]
	v_mfma_f32_16x16x32_bf16 v[76:79], v[134:137], v[246:249], v[76:79]
	v_mfma_f32_16x16x32_bf16 v[72:75], v[154:157], v[246:249], v[72:75]
	s_setprio 0
	s_setprio 1
	v_mfma_f32_16x16x32_bf16 v[118:121], v[158:161], v[182:185], v[118:121]
	v_mfma_f32_16x16x32_bf16 v[114:117], v[174:177], v[182:185], v[114:117]
	v_mfma_f32_16x16x32_bf16 v[100:103], v[158:161], v[208:211], v[100:103]
	v_mfma_f32_16x16x32_bf16 v[96:99], v[174:177], v[208:211], v[96:99]
	v_mfma_f32_16x16x32_bf16 v[84:87], v[158:161], v[234:237], v[84:87]
	v_mfma_f32_16x16x32_bf16 v[80:83], v[174:177], v[234:237], v[80:83]
	v_mfma_f32_16x16x32_bf16 v[68:71], v[158:161], v[242:245], v[68:71]
	v_mfma_f32_16x16x32_bf16 v[64:67], v[174:177], v[242:245], v[64:67]
	v_mfma_f32_16x16x32_bf16 v[118:121], v[162:165], v[186:189], v[118:121]
	v_mfma_f32_16x16x32_bf16 v[114:117], v[178:181], v[186:189], v[114:117]
	v_mfma_f32_16x16x32_bf16 v[100:103], v[162:165], v[230:233], v[100:103]
	v_mfma_f32_16x16x32_bf16 v[96:99], v[178:181], v[230:233], v[96:99]
	v_mfma_f32_16x16x32_bf16 v[84:87], v[162:165], v[238:241], v[84:87]
	v_mfma_f32_16x16x32_bf16 v[80:83], v[178:181], v[238:241], v[80:83]
	v_mfma_f32_16x16x32_bf16 v[68:71], v[162:165], v[246:249], v[68:71]
	v_mfma_f32_16x16x32_bf16 v[64:67], v[178:181], v[246:249], v[64:67]
	s_setprio 0
	s_barrier
	s_add_i32 s45, s45, s58
	s_mov_b32 m0, s45
	ds_read_b128 v[182:185], v172 offset:16384
	ds_read_b128 v[186:189], v172 offset:17408
	ds_read_b128 v[208:211], v172 offset:18432
	ds_read_b128 v[230:233], v172 offset:19456
	ds_read_b128 v[234:237], v172 offset:20480
	ds_read_b128 v[238:241], v172 offset:21504
	ds_read_b128 v[242:245], v172 offset:22528
	ds_read_b128 v[246:249], v172 offset:23552
	global_load_lds_dwordx4 v140, s[38:39]
	s_add_i32 m0, s45, 0x2000
	s_add_u32 s66, s38, 0x40000
	v_lshl_add_u64 v[212:213], s[38:39], 0, v[144:145]
	s_addc_u32 s67, s39, 0
	s_add_i32 s45, s68, s58
	global_load_lds_dwordx4 v144, s[38:39]
	s_mov_b32 m0, s45
	v_lshl_add_u64 v[250:251], s[40:41], 0, v[142:143]
	global_load_lds_dwordx4 v140, s[66:67]
	s_add_i32 m0, s45, 0x2000
	s_nop 0
	global_load_lds_dwordx4 v144, s[66:67]
	v_lshl_add_u64 v[228:229], s[40:41], 0, v[138:139]
	s_mov_b32 m0, s37
	s_nop 0
	global_load_lds_dwordx4 v138, s[40:41]
	s_mov_b32 m0, s59
	s_nop 0
	global_load_lds_dwordx4 v142, s[40:41]
	s_waitcnt vmcnt(8)
	s_waitcnt lgkmcnt(0)
	s_barrier
	s_setprio 1
	s_waitcnt lgkmcnt(0)
	v_mfma_f32_16x16x32_bf16 v[60:63], v[130:133], v[182:185], v[60:63]
	v_mfma_f32_16x16x32_bf16 v[56:59], v[150:153], v[182:185], v[56:59]
	v_mfma_f32_16x16x32_bf16 v[44:47], v[130:133], v[208:211], v[44:47]
	v_mfma_f32_16x16x32_bf16 v[40:43], v[150:153], v[208:211], v[40:43]
	v_mfma_f32_16x16x32_bf16 v[28:31], v[130:133], v[234:237], v[28:31]
	v_mfma_f32_16x16x32_bf16 v[24:27], v[150:153], v[234:237], v[24:27]
	v_mfma_f32_16x16x32_bf16 v[12:15], v[130:133], v[242:245], v[12:15]
	v_mfma_f32_16x16x32_bf16 v[8:11], v[150:153], v[242:245], v[8:11]
	v_mfma_f32_16x16x32_bf16 v[60:63], v[134:137], v[186:189], v[60:63]
	v_mfma_f32_16x16x32_bf16 v[56:59], v[154:157], v[186:189], v[56:59]
	v_mfma_f32_16x16x32_bf16 v[44:47], v[134:137], v[230:233], v[44:47]
	v_mfma_f32_16x16x32_bf16 v[40:43], v[154:157], v[230:233], v[40:43]
	v_mfma_f32_16x16x32_bf16 v[28:31], v[134:137], v[238:241], v[28:31]
	v_mfma_f32_16x16x32_bf16 v[24:27], v[154:157], v[238:241], v[24:27]
	v_mfma_f32_16x16x32_bf16 v[12:15], v[134:137], v[246:249], v[12:15]
	v_mfma_f32_16x16x32_bf16 v[8:11], v[154:157], v[246:249], v[8:11]
	s_setprio 0
	s_setprio 1
	v_mfma_f32_16x16x32_bf16 v[52:55], v[158:161], v[182:185], v[52:55]
	v_mfma_f32_16x16x32_bf16 v[48:51], v[174:177], v[182:185], v[48:51]
	v_mfma_f32_16x16x32_bf16 v[36:39], v[158:161], v[208:211], v[36:39]
	v_mfma_f32_16x16x32_bf16 v[32:35], v[174:177], v[208:211], v[32:35]
	v_mfma_f32_16x16x32_bf16 v[20:23], v[158:161], v[234:237], v[20:23]
	v_mfma_f32_16x16x32_bf16 v[16:19], v[174:177], v[234:237], v[16:19]
	v_mfma_f32_16x16x32_bf16 v[4:7], v[158:161], v[242:245], v[4:7]
	v_mfma_f32_16x16x32_bf16 v[0:3], v[174:177], v[242:245], v[0:3]
	v_mfma_f32_16x16x32_bf16 v[52:55], v[162:165], v[186:189], v[52:55]
	v_mfma_f32_16x16x32_bf16 v[48:51], v[178:181], v[186:189], v[48:51]
	v_mfma_f32_16x16x32_bf16 v[36:39], v[162:165], v[230:233], v[36:39]
	v_mfma_f32_16x16x32_bf16 v[32:35], v[178:181], v[230:233], v[32:35]
	v_mfma_f32_16x16x32_bf16 v[20:23], v[162:165], v[238:241], v[20:23]
	v_mfma_f32_16x16x32_bf16 v[16:19], v[178:181], v[238:241], v[16:19]
	v_mfma_f32_16x16x32_bf16 v[4:7], v[162:165], v[246:249], v[4:7]
	v_mfma_f32_16x16x32_bf16 v[0:3], v[178:181], v[246:249], v[0:3]
	s_setprio 0
	s_barrier
	s_add_i32 s45, 0, 0x18000
	v_add_u32_e32 v112, s45, v169
	s_add_i32 s66, 0, 0x1c000
	ds_read_b128 v[130:133], v112
	ds_read_b128 v[134:137], v112 offset:1024
	ds_read_b128 v[150:153], v112 offset:2048
	ds_read_b128 v[154:157], v112 offset:3072
	v_add_u32_e32 v112, s66, v169
	ds_read_b128 v[158:161], v112
	ds_read_b128 v[162:165], v112 offset:1024
	ds_read_b128 v[174:177], v112 offset:2048
	ds_read_b128 v[178:181], v112 offset:3072
	s_add_u32 s40, s40, 0x40000
	s_addc_u32 s41, s41, 0
	s_mov_b32 m0, s60
	ds_read_b128 v[182:185], v172 offset:32768
	ds_read_b128 v[186:189], v172 offset:33792
	ds_read_b128 v[208:211], v172 offset:34816
	ds_read_b128 v[230:233], v172 offset:35840
	ds_read_b128 v[234:237], v172 offset:36864
	ds_read_b128 v[238:241], v172 offset:37888
	ds_read_b128 v[242:245], v172 offset:38912
	ds_read_b128 v[246:249], v172 offset:39936
	global_load_lds_dwordx4 v138, s[40:41]
	s_mov_b32 m0, s61
	s_nop 0
	global_load_lds_dwordx4 v142, s[40:41]
	s_waitcnt vmcnt(8)
	s_waitcnt lgkmcnt(0)
	s_barrier
	s_setprio 1
	s_waitcnt lgkmcnt(0)
	v_mfma_f32_16x16x32_bf16 v[126:129], v[130:133], v[182:185], v[126:129]
	v_mfma_f32_16x16x32_bf16 v[122:125], v[150:153], v[182:185], v[122:125]
	v_mfma_f32_16x16x32_bf16 v[108:111], v[130:133], v[208:211], v[108:111]
	v_mfma_f32_16x16x32_bf16 v[104:107], v[150:153], v[208:211], v[104:107]
	v_mfma_f32_16x16x32_bf16 v[92:95], v[130:133], v[234:237], v[92:95]
	v_mfma_f32_16x16x32_bf16 v[88:91], v[150:153], v[234:237], v[88:91]
	v_mfma_f32_16x16x32_bf16 v[76:79], v[130:133], v[242:245], v[76:79]
	v_mfma_f32_16x16x32_bf16 v[72:75], v[150:153], v[242:245], v[72:75]
	v_mfma_f32_16x16x32_bf16 v[126:129], v[134:137], v[186:189], v[126:129]
	v_mfma_f32_16x16x32_bf16 v[122:125], v[154:157], v[186:189], v[122:125]
	v_mfma_f32_16x16x32_bf16 v[108:111], v[134:137], v[230:233], v[108:111]
	v_mfma_f32_16x16x32_bf16 v[104:107], v[154:157], v[230:233], v[104:107]
	v_mfma_f32_16x16x32_bf16 v[92:95], v[134:137], v[238:241], v[92:95]
	v_mfma_f32_16x16x32_bf16 v[88:91], v[154:157], v[238:241], v[88:91]
	v_mfma_f32_16x16x32_bf16 v[76:79], v[134:137], v[246:249], v[76:79]
	v_mfma_f32_16x16x32_bf16 v[72:75], v[154:157], v[246:249], v[72:75]
	s_setprio 0
	s_setprio 1
	v_mfma_f32_16x16x32_bf16 v[118:121], v[158:161], v[182:185], v[118:121]
	v_mfma_f32_16x16x32_bf16 v[114:117], v[174:177], v[182:185], v[114:117]
	v_mfma_f32_16x16x32_bf16 v[100:103], v[158:161], v[208:211], v[100:103]
	v_mfma_f32_16x16x32_bf16 v[96:99], v[174:177], v[208:211], v[96:99]
	v_mfma_f32_16x16x32_bf16 v[84:87], v[158:161], v[234:237], v[84:87]
	v_mfma_f32_16x16x32_bf16 v[80:83], v[174:177], v[234:237], v[80:83]
	v_mfma_f32_16x16x32_bf16 v[68:71], v[158:161], v[242:245], v[68:71]
	v_mfma_f32_16x16x32_bf16 v[64:67], v[174:177], v[242:245], v[64:67]
	v_mfma_f32_16x16x32_bf16 v[118:121], v[162:165], v[186:189], v[118:121]
	v_mfma_f32_16x16x32_bf16 v[114:117], v[178:181], v[186:189], v[114:117]
	v_mfma_f32_16x16x32_bf16 v[100:103], v[162:165], v[230:233], v[100:103]
	v_mfma_f32_16x16x32_bf16 v[96:99], v[178:181], v[230:233], v[96:99]
	v_mfma_f32_16x16x32_bf16 v[84:87], v[162:165], v[238:241], v[84:87]
	v_mfma_f32_16x16x32_bf16 v[80:83], v[178:181], v[238:241], v[80:83]
	v_mfma_f32_16x16x32_bf16 v[68:71], v[162:165], v[246:249], v[68:71]
	v_mfma_f32_16x16x32_bf16 v[64:67], v[178:181], v[246:249], v[64:67]
	s_setprio 0
	s_barrier
	s_add_i32 s40, s45, s58
	s_mov_b32 m0, s40
	ds_read_b128 v[182:185], v172 offset:49152
	ds_read_b128 v[186:189], v172 offset:50176
	ds_read_b128 v[208:211], v172 offset:51200
	ds_read_b128 v[230:233], v172 offset:52224
	ds_read_b128 v[234:237], v172 offset:53248
	ds_read_b128 v[238:241], v172 offset:54272
	ds_read_b128 v[242:245], v172 offset:55296
	ds_read_b128 v[246:249], v172 offset:56320
	s_add_u32 s98, s38, 0x80
	s_addc_u32 s99, s39, 0
	global_load_lds_dwordx4 v140, s[98:99]
	s_add_i32 m0, s40, 0x2000
	s_add_u32 s38, s38, 0x40080
	v_lshl_add_u64 v[166:167], v[212:213], 0, s[96:97]
	s_addc_u32 s39, s39, 0
	s_add_i32 s40, s66, s58
	global_load_lds_dwordx4 v[166:167], off
	s_mov_b32 m0, s40
	s_nop 0
	global_load_lds_dwordx4 v140, s[38:39]
	s_add_i32 m0, s40, 0x2000
	s_nop 0
	global_load_lds_dwordx4 v144, s[38:39]
	v_lshl_add_u64 v[166:167], v[228:229], 0, s[96:97]
	s_mov_b32 m0, s62
	s_nop 0
	global_load_lds_dwordx4 v[166:167], off
	v_lshl_add_u64 v[166:167], v[250:251], 0, s[96:97]
	s_mov_b32 m0, s63
	s_nop 0
	global_load_lds_dwordx4 v[166:167], off
	s_waitcnt vmcnt(8)
	s_waitcnt lgkmcnt(0)
	s_barrier
	s_setprio 1
	s_waitcnt lgkmcnt(0)
	v_mfma_f32_16x16x32_bf16 v[60:63], v[130:133], v[182:185], v[60:63]
	v_mfma_f32_16x16x32_bf16 v[56:59], v[150:153], v[182:185], v[56:59]
	v_mfma_f32_16x16x32_bf16 v[44:47], v[130:133], v[208:211], v[44:47]
	v_mfma_f32_16x16x32_bf16 v[40:43], v[150:153], v[208:211], v[40:43]
	v_mfma_f32_16x16x32_bf16 v[28:31], v[130:133], v[234:237], v[28:31]
	v_mfma_f32_16x16x32_bf16 v[24:27], v[150:153], v[234:237], v[24:27]
	v_mfma_f32_16x16x32_bf16 v[12:15], v[130:133], v[242:245], v[12:15]
	v_mfma_f32_16x16x32_bf16 v[8:11], v[150:153], v[242:245], v[8:11]
	v_mfma_f32_16x16x32_bf16 v[60:63], v[134:137], v[186:189], v[60:63]
	v_mfma_f32_16x16x32_bf16 v[56:59], v[154:157], v[186:189], v[56:59]
	v_mfma_f32_16x16x32_bf16 v[44:47], v[134:137], v[230:233], v[44:47]
	v_mfma_f32_16x16x32_bf16 v[40:43], v[154:157], v[230:233], v[40:43]
	v_mfma_f32_16x16x32_bf16 v[28:31], v[134:137], v[238:241], v[28:31]
	v_mfma_f32_16x16x32_bf16 v[24:27], v[154:157], v[238:241], v[24:27]
	v_mfma_f32_16x16x32_bf16 v[12:15], v[134:137], v[246:249], v[12:15]
	v_mfma_f32_16x16x32_bf16 v[8:11], v[154:157], v[246:249], v[8:11]
	s_setprio 0
	s_setprio 1
	v_mfma_f32_16x16x32_bf16 v[52:55], v[158:161], v[182:185], v[52:55]
	v_mfma_f32_16x16x32_bf16 v[48:51], v[174:177], v[182:185], v[48:51]
	v_mfma_f32_16x16x32_bf16 v[36:39], v[158:161], v[208:211], v[36:39]
	v_mfma_f32_16x16x32_bf16 v[32:35], v[174:177], v[208:211], v[32:35]
	v_mfma_f32_16x16x32_bf16 v[20:23], v[158:161], v[234:237], v[20:23]
	v_mfma_f32_16x16x32_bf16 v[16:19], v[174:177], v[234:237], v[16:19]
	v_mfma_f32_16x16x32_bf16 v[4:7], v[158:161], v[242:245], v[4:7]
	v_mfma_f32_16x16x32_bf16 v[0:3], v[174:177], v[242:245], v[0:3]
	v_mfma_f32_16x16x32_bf16 v[52:55], v[162:165], v[186:189], v[52:55]
	v_mfma_f32_16x16x32_bf16 v[48:51], v[178:181], v[186:189], v[48:51]
	v_mfma_f32_16x16x32_bf16 v[36:39], v[162:165], v[230:233], v[36:39]
	v_mfma_f32_16x16x32_bf16 v[32:35], v[178:181], v[230:233], v[32:35]
	v_mfma_f32_16x16x32_bf16 v[20:23], v[162:165], v[238:241], v[20:23]
	v_mfma_f32_16x16x32_bf16 v[16:19], v[178:181], v[238:241], v[16:19]
	v_mfma_f32_16x16x32_bf16 v[4:7], v[162:165], v[246:249], v[4:7]
	v_mfma_f32_16x16x32_bf16 v[0:3], v[178:181], v[246:249], v[0:3]
	s_setprio 0
	s_barrier
	s_add_i32 s44, s44, 2
	s_add_u32 s42, s42, 0x100
	s_addc_u32 s43, s43, 0
	s_add_u32 s8, s8, 0x100
	s_addc_u32 s9, s9, 0
	s_cmp_gt_u32 s44, 13
	s_cbranch_scc0 .LBB0_2151

.LBB0_2368:
	s_ashr_i32 s23, s22, 31
	s_lshl_b64 s[24:25], s[22:23], 19
	s_add_u32 s24, s49, s24
	s_addc_u32 s25, s50, s25
	s_and_b64 s[26:27], s[2:3], exec
	s_cselect_b32 s5, s25, s29
	s_cselect_b32 s23, s24, s28
	s_ashr_i32 s15, s14, 31
	s_lshl_b64 s[26:27], s[14:15], 19
	s_add_u32 s26, s51, s26
	s_addc_u32 s27, s52, s27
	s_and_b64 s[30:31], s[2:3], exec
	s_cselect_b32 s15, s27, s7
	s_cselect_b32 s47, s26, s6
	s_add_u32 s54, s6, 0x100
	s_addc_u32 s55, s7, 0
	s_add_u32 s6, s28, 0x40080
	s_addc_u32 s7, s29, 0
	s_mov_b32 s56, -2
	s_waitcnt lgkmcnt(0)
	s_add_u32 s28, s6, 0xfffc0080
	s_addc_u32 s29, s7, -1
	s_add_i32 s57, 0, 0x10000
	s_cmp_eq_u32 s56, 12
	s_cselect_b32 s31, s5, s29
	s_cselect_b32 s30, s23, s28
	v_add_u32_e32 v146, s57, v148
	s_cselect_b32 s29, s15, s55
	s_cselect_b32 s28, s47, s54
	s_add_i32 s60, 0, 0x14000
	ds_read_b128 v[142:145], v146
	ds_read_b128 v[152:155], v146 offset:1024
	ds_read_b128 v[156:159], v146 offset:2048
	ds_read_b128 v[160:163], v146 offset:3072
	v_add_u32_e32 v146, s60, v148
	ds_read_b128 v[164:167], v146
	ds_read_b128 v[168:171], v146 offset:1024
	ds_read_b128 v[172:175], v146 offset:2048
	ds_read_b128 v[176:179], v146 offset:3072
	s_add_i32 m0, s21, 0xc000
	ds_read_b128 v[180:183], v151
	ds_read_b128 v[184:187], v151 offset:1024
	ds_read_b128 v[208:211], v151 offset:2048
	ds_read_b128 v[230:233], v151 offset:3072
	ds_read_b128 v[234:237], v151 offset:4096
	ds_read_b128 v[238:241], v151 offset:5120
	ds_read_b128 v[242:245], v151 offset:6144
	ds_read_b128 v[246:249], v151 offset:7168
	global_load_lds_dwordx4 v140, s[6:7]
	s_add_i32 m0, s21, 0xe000
	s_nop 0
	global_load_lds_dwordx4 v138, s[6:7]
	s_waitcnt vmcnt(8)
	s_waitcnt lgkmcnt(0)
	s_barrier
	s_setprio 1
	s_waitcnt lgkmcnt(0)
	v_mfma_f32_16x16x32_bf16 v[126:129], v[142:145], v[180:183], 0
	v_mfma_f32_16x16x32_bf16 v[122:125], v[156:159], v[180:183], 0
	v_mfma_f32_16x16x32_bf16 v[108:111], v[142:145], v[208:211], 0
	v_mfma_f32_16x16x32_bf16 v[104:107], v[156:159], v[208:211], 0
	v_mfma_f32_16x16x32_bf16 v[92:95], v[142:145], v[234:237], 0
	v_mfma_f32_16x16x32_bf16 v[88:91], v[156:159], v[234:237], 0
	v_mfma_f32_16x16x32_bf16 v[76:79], v[142:145], v[242:245], 0
	v_mfma_f32_16x16x32_bf16 v[72:75], v[156:159], v[242:245], 0
	v_mfma_f32_16x16x32_bf16 v[126:129], v[152:155], v[184:187], v[126:129]
	v_mfma_f32_16x16x32_bf16 v[122:125], v[160:163], v[184:187], v[122:125]
	v_mfma_f32_16x16x32_bf16 v[108:111], v[152:155], v[230:233], v[108:111]
	v_mfma_f32_16x16x32_bf16 v[104:107], v[160:163], v[230:233], v[104:107]
	v_mfma_f32_16x16x32_bf16 v[92:95], v[152:155], v[238:241], v[92:95]
	v_mfma_f32_16x16x32_bf16 v[88:91], v[160:163], v[238:241], v[88:91]
	v_mfma_f32_16x16x32_bf16 v[76:79], v[152:155], v[246:249], v[76:79]
	v_mfma_f32_16x16x32_bf16 v[72:75], v[160:163], v[246:249], v[72:75]
	s_setprio 0
	s_setprio 1
	v_mfma_f32_16x16x32_bf16 v[118:121], v[164:167], v[180:183], 0
	v_mfma_f32_16x16x32_bf16 v[114:117], v[172:175], v[180:183], 0
	v_mfma_f32_16x16x32_bf16 v[100:103], v[164:167], v[208:211], 0
	v_mfma_f32_16x16x32_bf16 v[96:99], v[172:175], v[208:211], 0
	v_mfma_f32_16x16x32_bf16 v[84:87], v[164:167], v[234:237], 0
	v_mfma_f32_16x16x32_bf16 v[80:83], v[172:175], v[234:237], 0
	v_mfma_f32_16x16x32_bf16 v[68:71], v[164:167], v[242:245], 0
	v_mfma_f32_16x16x32_bf16 v[64:67], v[172:175], v[242:245], 0
	v_mfma_f32_16x16x32_bf16 v[118:121], v[168:171], v[184:187], v[118:121]
	v_mfma_f32_16x16x32_bf16 v[114:117], v[176:179], v[184:187], v[114:117]
	v_mfma_f32_16x16x32_bf16 v[100:103], v[168:171], v[230:233], v[100:103]
	v_mfma_f32_16x16x32_bf16 v[96:99], v[176:179], v[230:233], v[96:99]
	v_mfma_f32_16x16x32_bf16 v[84:87], v[168:171], v[238:241], v[84:87]
	v_mfma_f32_16x16x32_bf16 v[80:83], v[176:179], v[238:241], v[80:83]
	v_mfma_f32_16x16x32_bf16 v[68:71], v[168:171], v[246:249], v[68:71]
	v_mfma_f32_16x16x32_bf16 v[64:67], v[176:179], v[246:249], v[64:67]
	s_setprio 0
	s_barrier
	s_add_i32 s57, s57, s39
	s_mov_b32 m0, s57
	ds_read_b128 v[180:183], v151 offset:16384
	ds_read_b128 v[184:187], v151 offset:17408
	ds_read_b128 v[208:211], v151 offset:18432
	ds_read_b128 v[230:233], v151 offset:19456
	ds_read_b128 v[234:237], v151 offset:20480
	ds_read_b128 v[238:241], v151 offset:21504
	ds_read_b128 v[242:245], v151 offset:22528
	ds_read_b128 v[246:249], v151 offset:23552
	global_load_lds_dwordx4 v112, s[28:29]
	s_add_i32 m0, s57, 0x2000
	s_add_u32 s58, s28, 0x40000
	v_lshl_add_u64 v[212:213], s[28:29], 0, v[134:135]
	s_addc_u32 s59, s29, 0
	s_add_i32 s57, s60, s39
	global_load_lds_dwordx4 v134, s[28:29]
	s_mov_b32 m0, s57
	v_lshl_add_u64 v[252:253], s[30:31], 0, v[132:133]
	global_load_lds_dwordx4 v112, s[58:59]
	s_add_i32 m0, s57, 0x2000
	s_nop 0
	global_load_lds_dwordx4 v134, s[58:59]
	v_lshl_add_u64 v[250:251], s[30:31], 0, v[130:131]
	s_mov_b32 m0, s21
	s_nop 0
	global_load_lds_dwordx4 v130, s[30:31]
	s_mov_b32 m0, s40
	s_nop 0
	global_load_lds_dwordx4 v132, s[30:31]
	s_waitcnt vmcnt(8)
	s_waitcnt lgkmcnt(0)
	s_barrier
	s_setprio 1
	s_waitcnt lgkmcnt(0)
	v_mfma_f32_16x16x32_bf16 v[60:63], v[142:145], v[180:183], 0
	v_mfma_f32_16x16x32_bf16 v[56:59], v[156:159], v[180:183], 0
	v_mfma_f32_16x16x32_bf16 v[44:47], v[142:145], v[208:211], 0
	v_mfma_f32_16x16x32_bf16 v[40:43], v[156:159], v[208:211], 0
	v_mfma_f32_16x16x32_bf16 v[28:31], v[142:145], v[234:237], 0
	v_mfma_f32_16x16x32_bf16 v[24:27], v[156:159], v[234:237], 0
	v_mfma_f32_16x16x32_bf16 v[12:15], v[142:145], v[242:245], 0
	v_mfma_f32_16x16x32_bf16 v[8:11], v[156:159], v[242:245], 0
	v_mfma_f32_16x16x32_bf16 v[60:63], v[152:155], v[184:187], v[60:63]
	v_mfma_f32_16x16x32_bf16 v[56:59], v[160:163], v[184:187], v[56:59]
	v_mfma_f32_16x16x32_bf16 v[44:47], v[152:155], v[230:233], v[44:47]
	v_mfma_f32_16x16x32_bf16 v[40:43], v[160:163], v[230:233], v[40:43]
	v_mfma_f32_16x16x32_bf16 v[28:31], v[152:155], v[238:241], v[28:31]
	v_mfma_f32_16x16x32_bf16 v[24:27], v[160:163], v[238:241], v[24:27]
	v_mfma_f32_16x16x32_bf16 v[12:15], v[152:155], v[246:249], v[12:15]
	v_mfma_f32_16x16x32_bf16 v[8:11], v[160:163], v[246:249], v[8:11]
	s_setprio 0
	s_setprio 1
	v_mfma_f32_16x16x32_bf16 v[52:55], v[164:167], v[180:183], 0
	v_mfma_f32_16x16x32_bf16 v[48:51], v[172:175], v[180:183], 0
	v_mfma_f32_16x16x32_bf16 v[36:39], v[164:167], v[208:211], 0
	v_mfma_f32_16x16x32_bf16 v[32:35], v[172:175], v[208:211], 0
	v_mfma_f32_16x16x32_bf16 v[20:23], v[164:167], v[234:237], 0
	v_mfma_f32_16x16x32_bf16 v[16:19], v[172:175], v[234:237], 0
	v_mfma_f32_16x16x32_bf16 v[4:7], v[164:167], v[242:245], 0
	v_mfma_f32_16x16x32_bf16 v[0:3], v[172:175], v[242:245], 0
	v_mfma_f32_16x16x32_bf16 v[52:55], v[168:171], v[184:187], v[52:55]
	v_mfma_f32_16x16x32_bf16 v[48:51], v[176:179], v[184:187], v[48:51]
	v_mfma_f32_16x16x32_bf16 v[36:39], v[168:171], v[230:233], v[36:39]
	v_mfma_f32_16x16x32_bf16 v[32:35], v[176:179], v[230:233], v[32:35]
	v_mfma_f32_16x16x32_bf16 v[20:23], v[168:171], v[238:241], v[20:23]
	v_mfma_f32_16x16x32_bf16 v[16:19], v[176:179], v[238:241], v[16:19]
	v_mfma_f32_16x16x32_bf16 v[4:7], v[168:171], v[246:249], v[4:7]
	v_mfma_f32_16x16x32_bf16 v[0:3], v[176:179], v[246:249], v[0:3]
	s_setprio 0
	s_barrier
	s_add_i32 s57, 0, 0x18000
	v_add_u32_e32 v146, s57, v148
	s_add_i32 s58, 0, 0x1c000
	ds_read_b128 v[142:145], v146
	ds_read_b128 v[152:155], v146 offset:1024
	ds_read_b128 v[156:159], v146 offset:2048
	ds_read_b128 v[160:163], v146 offset:3072
	v_add_u32_e32 v146, s58, v148
	ds_read_b128 v[164:167], v146
	ds_read_b128 v[168:171], v146 offset:1024
	ds_read_b128 v[172:175], v146 offset:2048
	ds_read_b128 v[176:179], v146 offset:3072
	s_add_u32 s30, s30, 0x40000
	s_addc_u32 s31, s31, 0
	s_mov_b32 m0, s41
	ds_read_b128 v[180:183], v151 offset:32768
	ds_read_b128 v[184:187], v151 offset:33792
	ds_read_b128 v[208:211], v151 offset:34816
	ds_read_b128 v[230:233], v151 offset:35840
	ds_read_b128 v[234:237], v151 offset:36864
	ds_read_b128 v[238:241], v151 offset:37888
	ds_read_b128 v[242:245], v151 offset:38912
	ds_read_b128 v[246:249], v151 offset:39936
	global_load_lds_dwordx4 v130, s[30:31]
	s_mov_b32 m0, s42
	s_nop 0
	global_load_lds_dwordx4 v132, s[30:31]
	s_waitcnt vmcnt(8)
	s_waitcnt lgkmcnt(0)
	s_barrier
	s_setprio 1
	s_waitcnt lgkmcnt(0)
	v_mfma_f32_16x16x32_bf16 v[126:129], v[142:145], v[180:183], v[126:129]
	v_mfma_f32_16x16x32_bf16 v[122:125], v[156:159], v[180:183], v[122:125]
	v_mfma_f32_16x16x32_bf16 v[108:111], v[142:145], v[208:211], v[108:111]
	v_mfma_f32_16x16x32_bf16 v[104:107], v[156:159], v[208:211], v[104:107]
	v_mfma_f32_16x16x32_bf16 v[92:95], v[142:145], v[234:237], v[92:95]
	v_mfma_f32_16x16x32_bf16 v[88:91], v[156:159], v[234:237], v[88:91]
	v_mfma_f32_16x16x32_bf16 v[76:79], v[142:145], v[242:245], v[76:79]
	v_mfma_f32_16x16x32_bf16 v[72:75], v[156:159], v[242:245], v[72:75]
	v_mfma_f32_16x16x32_bf16 v[126:129], v[152:155], v[184:187], v[126:129]
	v_mfma_f32_16x16x32_bf16 v[122:125], v[160:163], v[184:187], v[122:125]
	v_mfma_f32_16x16x32_bf16 v[108:111], v[152:155], v[230:233], v[108:111]
	v_mfma_f32_16x16x32_bf16 v[104:107], v[160:163], v[230:233], v[104:107]
	v_mfma_f32_16x16x32_bf16 v[92:95], v[152:155], v[238:241], v[92:95]
	v_mfma_f32_16x16x32_bf16 v[88:91], v[160:163], v[238:241], v[88:91]
	v_mfma_f32_16x16x32_bf16 v[76:79], v[152:155], v[246:249], v[76:79]
	v_mfma_f32_16x16x32_bf16 v[72:75], v[160:163], v[246:249], v[72:75]
	s_setprio 0
	s_setprio 1
	v_mfma_f32_16x16x32_bf16 v[118:121], v[164:167], v[180:183], v[118:121]
	v_mfma_f32_16x16x32_bf16 v[114:117], v[172:175], v[180:183], v[114:117]
	v_mfma_f32_16x16x32_bf16 v[100:103], v[164:167], v[208:211], v[100:103]
	v_mfma_f32_16x16x32_bf16 v[96:99], v[172:175], v[208:211], v[96:99]
	v_mfma_f32_16x16x32_bf16 v[84:87], v[164:167], v[234:237], v[84:87]
	v_mfma_f32_16x16x32_bf16 v[80:83], v[172:175], v[234:237], v[80:83]
	v_mfma_f32_16x16x32_bf16 v[68:71], v[164:167], v[242:245], v[68:71]
	v_mfma_f32_16x16x32_bf16 v[64:67], v[172:175], v[242:245], v[64:67]
	v_mfma_f32_16x16x32_bf16 v[118:121], v[168:171], v[184:187], v[118:121]
	v_mfma_f32_16x16x32_bf16 v[114:117], v[176:179], v[184:187], v[114:117]
	v_mfma_f32_16x16x32_bf16 v[100:103], v[168:171], v[230:233], v[100:103]
	v_mfma_f32_16x16x32_bf16 v[96:99], v[176:179], v[230:233], v[96:99]
	v_mfma_f32_16x16x32_bf16 v[84:87], v[168:171], v[238:241], v[84:87]
	v_mfma_f32_16x16x32_bf16 v[80:83], v[176:179], v[238:241], v[80:83]
	v_mfma_f32_16x16x32_bf16 v[68:71], v[168:171], v[246:249], v[68:71]
	v_mfma_f32_16x16x32_bf16 v[64:67], v[176:179], v[246:249], v[64:67]
	s_setprio 0
	s_barrier
	s_add_i32 s30, s57, s39
	s_mov_b32 m0, s30
	ds_read_b128 v[180:183], v151 offset:49152
	ds_read_b128 v[184:187], v151 offset:50176
	ds_read_b128 v[208:211], v151 offset:51200
	ds_read_b128 v[230:233], v151 offset:52224
	ds_read_b128 v[234:237], v151 offset:53248
	ds_read_b128 v[238:241], v151 offset:54272
	ds_read_b128 v[242:245], v151 offset:55296
	ds_read_b128 v[246:249], v151 offset:56320
	s_add_u32 s98, s28, 0x80
	s_addc_u32 s99, s29, 0
	global_load_lds_dwordx4 v112, s[98:99]
	s_add_i32 m0, s30, 0x2000
	s_add_u32 s28, s28, 0x40080
	v_lshl_add_u64 v[188:189], v[212:213], 0, s[96:97]
	s_addc_u32 s29, s29, 0
	s_add_i32 s30, s58, s39
	global_load_lds_dwordx4 v[188:189], off
	s_mov_b32 m0, s30
	s_nop 0
	global_load_lds_dwordx4 v112, s[28:29]
	s_add_i32 m0, s30, 0x2000
	s_nop 0
	global_load_lds_dwordx4 v134, s[28:29]
	v_lshl_add_u64 v[188:189], v[250:251], 0, s[96:97]
	s_mov_b32 m0, s43
	s_nop 0
	global_load_lds_dwordx4 v[188:189], off
	v_lshl_add_u64 v[188:189], v[252:253], 0, s[96:97]
	s_mov_b32 m0, s44
	s_nop 0
	global_load_lds_dwordx4 v[188:189], off
	s_waitcnt vmcnt(8)
	s_waitcnt lgkmcnt(0)
	s_barrier
	s_setprio 1
	s_waitcnt lgkmcnt(0)
	v_mfma_f32_16x16x32_bf16 v[60:63], v[142:145], v[180:183], v[60:63]
	v_mfma_f32_16x16x32_bf16 v[56:59], v[156:159], v[180:183], v[56:59]
	v_mfma_f32_16x16x32_bf16 v[44:47], v[142:145], v[208:211], v[44:47]
	v_mfma_f32_16x16x32_bf16 v[40:43], v[156:159], v[208:211], v[40:43]
	v_mfma_f32_16x16x32_bf16 v[28:31], v[142:145], v[234:237], v[28:31]
	v_mfma_f32_16x16x32_bf16 v[24:27], v[156:159], v[234:237], v[24:27]
	v_mfma_f32_16x16x32_bf16 v[12:15], v[142:145], v[242:245], v[12:15]
	v_mfma_f32_16x16x32_bf16 v[8:11], v[156:159], v[242:245], v[8:11]
	v_mfma_f32_16x16x32_bf16 v[60:63], v[152:155], v[184:187], v[60:63]
	v_mfma_f32_16x16x32_bf16 v[56:59], v[160:163], v[184:187], v[56:59]
	v_mfma_f32_16x16x32_bf16 v[44:47], v[152:155], v[230:233], v[44:47]
	v_mfma_f32_16x16x32_bf16 v[40:43], v[160:163], v[230:233], v[40:43]
	v_mfma_f32_16x16x32_bf16 v[28:31], v[152:155], v[238:241], v[28:31]
	v_mfma_f32_16x16x32_bf16 v[24:27], v[160:163], v[238:241], v[24:27]
	v_mfma_f32_16x16x32_bf16 v[12:15], v[152:155], v[246:249], v[12:15]
	v_mfma_f32_16x16x32_bf16 v[8:11], v[160:163], v[246:249], v[8:11]
	s_setprio 0
	s_setprio 1
	v_mfma_f32_16x16x32_bf16 v[52:55], v[164:167], v[180:183], v[52:55]
	v_mfma_f32_16x16x32_bf16 v[48:51], v[172:175], v[180:183], v[48:51]
	v_mfma_f32_16x16x32_bf16 v[36:39], v[164:167], v[208:211], v[36:39]
	v_mfma_f32_16x16x32_bf16 v[32:35], v[172:175], v[208:211], v[32:35]
	v_mfma_f32_16x16x32_bf16 v[20:23], v[164:167], v[234:237], v[20:23]
	v_mfma_f32_16x16x32_bf16 v[16:19], v[172:175], v[234:237], v[16:19]
	v_mfma_f32_16x16x32_bf16 v[4:7], v[164:167], v[242:245], v[4:7]
	v_mfma_f32_16x16x32_bf16 v[0:3], v[172:175], v[242:245], v[0:3]
	v_mfma_f32_16x16x32_bf16 v[52:55], v[168:171], v[184:187], v[52:55]
	v_mfma_f32_16x16x32_bf16 v[48:51], v[176:179], v[184:187], v[48:51]
	v_mfma_f32_16x16x32_bf16 v[36:39], v[168:171], v[230:233], v[36:39]
	v_mfma_f32_16x16x32_bf16 v[32:35], v[176:179], v[230:233], v[32:35]
	v_mfma_f32_16x16x32_bf16 v[20:23], v[168:171], v[238:241], v[20:23]
	v_mfma_f32_16x16x32_bf16 v[16:19], v[176:179], v[238:241], v[16:19]
	v_mfma_f32_16x16x32_bf16 v[4:7], v[168:171], v[246:249], v[4:7]
	v_mfma_f32_16x16x32_bf16 v[0:3], v[176:179], v[246:249], v[0:3]
	s_setprio 0
	s_barrier
	s_add_i32 s56, s56, 2
	s_add_u32 s54, s54, 0x100
	s_addc_u32 s55, s55, 0
	s_add_u32 s6, s6, 0x100
	s_addc_u32 s7, s7, 0
	s_cmp_gt_u32 s56, 13
	s_cbranch_scc0 .LBB0_2369
	s_branch .Lpeel_exit_2369
.LBB0_2369:
	s_add_u32 s28, s6, 0xfffc0080
	s_addc_u32 s29, s7, -1
	s_add_i32 s57, 0, 0x10000
	s_cmp_eq_u32 s56, 12
	s_cselect_b32 s31, s5, s29
	s_cselect_b32 s30, s23, s28
	v_add_u32_e32 v146, s57, v148
	s_cselect_b32 s29, s15, s55
	s_cselect_b32 s28, s47, s54
	s_add_i32 s60, 0, 0x14000
	ds_read_b128 v[142:145], v146
	ds_read_b128 v[152:155], v146 offset:1024
	ds_read_b128 v[156:159], v146 offset:2048
	ds_read_b128 v[160:163], v146 offset:3072
	v_add_u32_e32 v146, s60, v148
	ds_read_b128 v[164:167], v146
	ds_read_b128 v[168:171], v146 offset:1024
	ds_read_b128 v[172:175], v146 offset:2048
	ds_read_b128 v[176:179], v146 offset:3072
	s_add_i32 m0, s21, 0xc000
	ds_read_b128 v[180:183], v151
	ds_read_b128 v[184:187], v151 offset:1024
	ds_read_b128 v[208:211], v151 offset:2048
	ds_read_b128 v[230:233], v151 offset:3072
	ds_read_b128 v[234:237], v151 offset:4096
	ds_read_b128 v[238:241], v151 offset:5120
	ds_read_b128 v[242:245], v151 offset:6144
	ds_read_b128 v[246:249], v151 offset:7168
	global_load_lds_dwordx4 v140, s[6:7]
	s_add_i32 m0, s21, 0xe000
	s_nop 0
	global_load_lds_dwordx4 v138, s[6:7]
	s_waitcnt vmcnt(8)
	s_waitcnt lgkmcnt(0)
	s_barrier
	s_setprio 1
	s_waitcnt lgkmcnt(0)
	v_mfma_f32_16x16x32_bf16 v[126:129], v[142:145], v[180:183], v[126:129]
	v_mfma_f32_16x16x32_bf16 v[122:125], v[156:159], v[180:183], v[122:125]
	v_mfma_f32_16x16x32_bf16 v[108:111], v[142:145], v[208:211], v[108:111]
	v_mfma_f32_16x16x32_bf16 v[104:107], v[156:159], v[208:211], v[104:107]
	v_mfma_f32_16x16x32_bf16 v[92:95], v[142:145], v[234:237], v[92:95]
	v_mfma_f32_16x16x32_bf16 v[88:91], v[156:159], v[234:237], v[88:91]
	v_mfma_f32_16x16x32_bf16 v[76:79], v[142:145], v[242:245], v[76:79]
	v_mfma_f32_16x16x32_bf16 v[72:75], v[156:159], v[242:245], v[72:75]
	v_mfma_f32_16x16x32_bf16 v[126:129], v[152:155], v[184:187], v[126:129]
	v_mfma_f32_16x16x32_bf16 v[122:125], v[160:163], v[184:187], v[122:125]
	v_mfma_f32_16x16x32_bf16 v[108:111], v[152:155], v[230:233], v[108:111]
	v_mfma_f32_16x16x32_bf16 v[104:107], v[160:163], v[230:233], v[104:107]
	v_mfma_f32_16x16x32_bf16 v[92:95], v[152:155], v[238:241], v[92:95]
	v_mfma_f32_16x16x32_bf16 v[88:91], v[160:163], v[238:241], v[88:91]
	v_mfma_f32_16x16x32_bf16 v[76:79], v[152:155], v[246:249], v[76:79]
	v_mfma_f32_16x16x32_bf16 v[72:75], v[160:163], v[246:249], v[72:75]
	s_setprio 0
	s_setprio 1
	v_mfma_f32_16x16x32_bf16 v[118:121], v[164:167], v[180:183], v[118:121]
	v_mfma_f32_16x16x32_bf16 v[114:117], v[172:175], v[180:183], v[114:117]
	v_mfma_f32_16x16x32_bf16 v[100:103], v[164:167], v[208:211], v[100:103]
	v_mfma_f32_16x16x32_bf16 v[96:99], v[172:175], v[208:211], v[96:99]
	v_mfma_f32_16x16x32_bf16 v[84:87], v[164:167], v[234:237], v[84:87]
	v_mfma_f32_16x16x32_bf16 v[80:83], v[172:175], v[234:237], v[80:83]
	v_mfma_f32_16x16x32_bf16 v[68:71], v[164:167], v[242:245], v[68:71]
	v_mfma_f32_16x16x32_bf16 v[64:67], v[172:175], v[242:245], v[64:67]
	v_mfma_f32_16x16x32_bf16 v[118:121], v[168:171], v[184:187], v[118:121]
	v_mfma_f32_16x16x32_bf16 v[114:117], v[176:179], v[184:187], v[114:117]
	v_mfma_f32_16x16x32_bf16 v[100:103], v[168:171], v[230:233], v[100:103]
	v_mfma_f32_16x16x32_bf16 v[96:99], v[176:179], v[230:233], v[96:99]
	v_mfma_f32_16x16x32_bf16 v[84:87], v[168:171], v[238:241], v[84:87]
	v_mfma_f32_16x16x32_bf16 v[80:83], v[176:179], v[238:241], v[80:83]
	v_mfma_f32_16x16x32_bf16 v[68:71], v[168:171], v[246:249], v[68:71]
	v_mfma_f32_16x16x32_bf16 v[64:67], v[176:179], v[246:249], v[64:67]
	s_setprio 0
	s_barrier
	s_add_i32 s57, s57, s39
	s_mov_b32 m0, s57
	ds_read_b128 v[180:183], v151 offset:16384
	ds_read_b128 v[184:187], v151 offset:17408
	ds_read_b128 v[208:211], v151 offset:18432
	ds_read_b128 v[230:233], v151 offset:19456
	ds_read_b128 v[234:237], v151 offset:20480
	ds_read_b128 v[238:241], v151 offset:21504
	ds_read_b128 v[242:245], v151 offset:22528
	ds_read_b128 v[246:249], v151 offset:23552
	global_load_lds_dwordx4 v112, s[28:29]
	s_add_i32 m0, s57, 0x2000
	s_add_u32 s58, s28, 0x40000
	v_lshl_add_u64 v[212:213], s[28:29], 0, v[134:135]
	s_addc_u32 s59, s29, 0
	s_add_i32 s57, s60, s39
	global_load_lds_dwordx4 v134, s[28:29]
	s_mov_b32 m0, s57
	v_lshl_add_u64 v[252:253], s[30:31], 0, v[132:133]
	global_load_lds_dwordx4 v112, s[58:59]
	s_add_i32 m0, s57, 0x2000
	s_nop 0
	global_load_lds_dwordx4 v134, s[58:59]
	v_lshl_add_u64 v[250:251], s[30:31], 0, v[130:131]
	s_mov_b32 m0, s21
	s_nop 0
	global_load_lds_dwordx4 v130, s[30:31]
	s_mov_b32 m0, s40
	s_nop 0
	global_load_lds_dwordx4 v132, s[30:31]
	s_waitcnt vmcnt(8)
	s_waitcnt lgkmcnt(0)
	s_barrier
	s_setprio 1
	s_waitcnt lgkmcnt(0)
	v_mfma_f32_16x16x32_bf16 v[60:63], v[142:145], v[180:183], v[60:63]
	v_mfma_f32_16x16x32_bf16 v[56:59], v[156:159], v[180:183], v[56:59]
	v_mfma_f32_16x16x32_bf16 v[44:47], v[142:145], v[208:211], v[44:47]
	v_mfma_f32_16x16x32_bf16 v[40:43], v[156:159], v[208:211], v[40:43]
	v_mfma_f32_16x16x32_bf16 v[28:31], v[142:145], v[234:237], v[28:31]
	v_mfma_f32_16x16x32_bf16 v[24:27], v[156:159], v[234:237], v[24:27]
	v_mfma_f32_16x16x32_bf16 v[12:15], v[142:145], v[242:245], v[12:15]
	v_mfma_f32_16x16x32_bf16 v[8:11], v[156:159], v[242:245], v[8:11]
	v_mfma_f32_16x16x32_bf16 v[60:63], v[152:155], v[184:187], v[60:63]
	v_mfma_f32_16x16x32_bf16 v[56:59], v[160:163], v[184:187], v[56:59]
	v_mfma_f32_16x16x32_bf16 v[44:47], v[152:155], v[230:233], v[44:47]
	v_mfma_f32_16x16x32_bf16 v[40:43], v[160:163], v[230:233], v[40:43]
	v_mfma_f32_16x16x32_bf16 v[28:31], v[152:155], v[238:241], v[28:31]
	v_mfma_f32_16x16x32_bf16 v[24:27], v[160:163], v[238:241], v[24:27]
	v_mfma_f32_16x16x32_bf16 v[12:15], v[152:155], v[246:249], v[12:15]
	v_mfma_f32_16x16x32_bf16 v[8:11], v[160:163], v[246:249], v[8:11]
	s_setprio 0
	s_setprio 1
	v_mfma_f32_16x16x32_bf16 v[52:55], v[164:167], v[180:183], v[52:55]
	v_mfma_f32_16x16x32_bf16 v[48:51], v[172:175], v[180:183], v[48:51]
	v_mfma_f32_16x16x32_bf16 v[36:39], v[164:167], v[208:211], v[36:39]
	v_mfma_f32_16x16x32_bf16 v[32:35], v[172:175], v[208:211], v[32:35]
	v_mfma_f32_16x16x32_bf16 v[20:23], v[164:167], v[234:237], v[20:23]
	v_mfma_f32_16x16x32_bf16 v[16:19], v[172:175], v[234:237], v[16:19]
	v_mfma_f32_16x16x32_bf16 v[4:7], v[164:167], v[242:245], v[4:7]
	v_mfma_f32_16x16x32_bf16 v[0:3], v[172:175], v[242:245], v[0:3]
	v_mfma_f32_16x16x32_bf16 v[52:55], v[168:171], v[184:187], v[52:55]
	v_mfma_f32_16x16x32_bf16 v[48:51], v[176:179], v[184:187], v[48:51]
	v_mfma_f32_16x16x32_bf16 v[36:39], v[168:171], v[230:233], v[36:39]
	v_mfma_f32_16x16x32_bf16 v[32:35], v[176:179], v[230:233], v[32:35]
	v_mfma_f32_16x16x32_bf16 v[20:23], v[168:171], v[238:241], v[20:23]
	v_mfma_f32_16x16x32_bf16 v[16:19], v[176:179], v[238:241], v[16:19]
	v_mfma_f32_16x16x32_bf16 v[4:7], v[168:171], v[246:249], v[4:7]
	v_mfma_f32_16x16x32_bf16 v[0:3], v[176:179], v[246:249], v[0:3]
	s_setprio 0
	s_barrier
	s_add_i32 s57, 0, 0x18000
	v_add_u32_e32 v146, s57, v148
	s_add_i32 s58, 0, 0x1c000
	ds_read_b128 v[142:145], v146
	ds_read_b128 v[152:155], v146 offset:1024
	ds_read_b128 v[156:159], v146 offset:2048
	ds_read_b128 v[160:163], v146 offset:3072
	v_add_u32_e32 v146, s58, v148
	ds_read_b128 v[164:167], v146
	ds_read_b128 v[168:171], v146 offset:1024
	ds_read_b128 v[172:175], v146 offset:2048
	ds_read_b128 v[176:179], v146 offset:3072
	s_add_u32 s30, s30, 0x40000
	s_addc_u32 s31, s31, 0
	s_mov_b32 m0, s41
	ds_read_b128 v[180:183], v151 offset:32768
	ds_read_b128 v[184:187], v151 offset:33792
	ds_read_b128 v[208:211], v151 offset:34816
	ds_read_b128 v[230:233], v151 offset:35840
	ds_read_b128 v[234:237], v151 offset:36864
	ds_read_b128 v[238:241], v151 offset:37888
	ds_read_b128 v[242:245], v151 offset:38912
	ds_read_b128 v[246:249], v151 offset:39936
	global_load_lds_dwordx4 v130, s[30:31]
	s_mov_b32 m0, s42
	s_nop 0
	global_load_lds_dwordx4 v132, s[30:31]
	s_waitcnt vmcnt(8)
	s_waitcnt lgkmcnt(0)
	s_barrier
	s_setprio 1
	s_waitcnt lgkmcnt(0)
	v_mfma_f32_16x16x32_bf16 v[126:129], v[142:145], v[180:183], v[126:129]
	v_mfma_f32_16x16x32_bf16 v[122:125], v[156:159], v[180:183], v[122:125]
	v_mfma_f32_16x16x32_bf16 v[108:111], v[142:145], v[208:211], v[108:111]
	v_mfma_f32_16x16x32_bf16 v[104:107], v[156:159], v[208:211], v[104:107]
	v_mfma_f32_16x16x32_bf16 v[92:95], v[142:145], v[234:237], v[92:95]
	v_mfma_f32_16x16x32_bf16 v[88:91], v[156:159], v[234:237], v[88:91]
	v_mfma_f32_16x16x32_bf16 v[76:79], v[142:145], v[242:245], v[76:79]
	v_mfma_f32_16x16x32_bf16 v[72:75], v[156:159], v[242:245], v[72:75]
	v_mfma_f32_16x16x32_bf16 v[126:129], v[152:155], v[184:187], v[126:129]
	v_mfma_f32_16x16x32_bf16 v[122:125], v[160:163], v[184:187], v[122:125]
	v_mfma_f32_16x16x32_bf16 v[108:111], v[152:155], v[230:233], v[108:111]
	v_mfma_f32_16x16x32_bf16 v[104:107], v[160:163], v[230:233], v[104:107]
	v_mfma_f32_16x16x32_bf16 v[92:95], v[152:155], v[238:241], v[92:95]
	v_mfma_f32_16x16x32_bf16 v[88:91], v[160:163], v[238:241], v[88:91]
	v_mfma_f32_16x16x32_bf16 v[76:79], v[152:155], v[246:249], v[76:79]
	v_mfma_f32_16x16x32_bf16 v[72:75], v[160:163], v[246:249], v[72:75]
	s_setprio 0
	s_setprio 1
	v_mfma_f32_16x16x32_bf16 v[118:121], v[164:167], v[180:183], v[118:121]
	v_mfma_f32_16x16x32_bf16 v[114:117], v[172:175], v[180:183], v[114:117]
	v_mfma_f32_16x16x32_bf16 v[100:103], v[164:167], v[208:211], v[100:103]
	v_mfma_f32_16x16x32_bf16 v[96:99], v[172:175], v[208:211], v[96:99]
	v_mfma_f32_16x16x32_bf16 v[84:87], v[164:167], v[234:237], v[84:87]
	v_mfma_f32_16x16x32_bf16 v[80:83], v[172:175], v[234:237], v[80:83]
	v_mfma_f32_16x16x32_bf16 v[68:71], v[164:167], v[242:245], v[68:71]
	v_mfma_f32_16x16x32_bf16 v[64:67], v[172:175], v[242:245], v[64:67]
	v_mfma_f32_16x16x32_bf16 v[118:121], v[168:171], v[184:187], v[118:121]
	v_mfma_f32_16x16x32_bf16 v[114:117], v[176:179], v[184:187], v[114:117]
	v_mfma_f32_16x16x32_bf16 v[100:103], v[168:171], v[230:233], v[100:103]
	v_mfma_f32_16x16x32_bf16 v[96:99], v[176:179], v[230:233], v[96:99]
	v_mfma_f32_16x16x32_bf16 v[84:87], v[168:171], v[238:241], v[84:87]
	v_mfma_f32_16x16x32_bf16 v[80:83], v[176:179], v[238:241], v[80:83]
	v_mfma_f32_16x16x32_bf16 v[68:71], v[168:171], v[246:249], v[68:71]
	v_mfma_f32_16x16x32_bf16 v[64:67], v[176:179], v[246:249], v[64:67]
	s_setprio 0
	s_barrier
	s_add_i32 s30, s57, s39
	s_mov_b32 m0, s30
	ds_read_b128 v[180:183], v151 offset:49152
	ds_read_b128 v[184:187], v151 offset:50176
	ds_read_b128 v[208:211], v151 offset:51200
	ds_read_b128 v[230:233], v151 offset:52224
	ds_read_b128 v[234:237], v151 offset:53248
	ds_read_b128 v[238:241], v151 offset:54272
	ds_read_b128 v[242:245], v151 offset:55296
	ds_read_b128 v[246:249], v151 offset:56320
	s_add_u32 s98, s28, 0x80
	s_addc_u32 s99, s29, 0
	global_load_lds_dwordx4 v112, s[98:99]
	s_add_i32 m0, s30, 0x2000
	s_add_u32 s28, s28, 0x40080
	v_lshl_add_u64 v[188:189], v[212:213], 0, s[96:97]
	s_addc_u32 s29, s29, 0
	s_add_i32 s30, s58, s39
	global_load_lds_dwordx4 v[188:189], off
	s_mov_b32 m0, s30
	s_nop 0
	global_load_lds_dwordx4 v112, s[28:29]
	s_add_i32 m0, s30, 0x2000
	s_nop 0
	global_load_lds_dwordx4 v134, s[28:29]
	v_lshl_add_u64 v[188:189], v[250:251], 0, s[96:97]
	s_mov_b32 m0, s43
	s_nop 0
	global_load_lds_dwordx4 v[188:189], off
	v_lshl_add_u64 v[188:189], v[252:253], 0, s[96:97]
	s_mov_b32 m0, s44
	s_nop 0
	global_load_lds_dwordx4 v[188:189], off
	s_waitcnt vmcnt(8)
	s_waitcnt lgkmcnt(0)
	s_barrier
	s_setprio 1
	s_waitcnt lgkmcnt(0)
	v_mfma_f32_16x16x32_bf16 v[60:63], v[142:145], v[180:183], v[60:63]
	v_mfma_f32_16x16x32_bf16 v[56:59], v[156:159], v[180:183], v[56:59]
	v_mfma_f32_16x16x32_bf16 v[44:47], v[142:145], v[208:211], v[44:47]
	v_mfma_f32_16x16x32_bf16 v[40:43], v[156:159], v[208:211], v[40:43]
	v_mfma_f32_16x16x32_bf16 v[28:31], v[142:145], v[234:237], v[28:31]
	v_mfma_f32_16x16x32_bf16 v[24:27], v[156:159], v[234:237], v[24:27]
	v_mfma_f32_16x16x32_bf16 v[12:15], v[142:145], v[242:245], v[12:15]
	v_mfma_f32_16x16x32_bf16 v[8:11], v[156:159], v[242:245], v[8:11]
	v_mfma_f32_16x16x32_bf16 v[60:63], v[152:155], v[184:187], v[60:63]
	v_mfma_f32_16x16x32_bf16 v[56:59], v[160:163], v[184:187], v[56:59]
	v_mfma_f32_16x16x32_bf16 v[44:47], v[152:155], v[230:233], v[44:47]
	v_mfma_f32_16x16x32_bf16 v[40:43], v[160:163], v[230:233], v[40:43]
	v_mfma_f32_16x16x32_bf16 v[28:31], v[152:155], v[238:241], v[28:31]
	v_mfma_f32_16x16x32_bf16 v[24:27], v[160:163], v[238:241], v[24:27]
	v_mfma_f32_16x16x32_bf16 v[12:15], v[152:155], v[246:249], v[12:15]
	v_mfma_f32_16x16x32_bf16 v[8:11], v[160:163], v[246:249], v[8:11]
	s_setprio 0
	s_setprio 1
	v_mfma_f32_16x16x32_bf16 v[52:55], v[164:167], v[180:183], v[52:55]
	v_mfma_f32_16x16x32_bf16 v[48:51], v[172:175], v[180:183], v[48:51]
	v_mfma_f32_16x16x32_bf16 v[36:39], v[164:167], v[208:211], v[36:39]
	v_mfma_f32_16x16x32_bf16 v[32:35], v[172:175], v[208:211], v[32:35]
	v_mfma_f32_16x16x32_bf16 v[20:23], v[164:167], v[234:237], v[20:23]
	v_mfma_f32_16x16x32_bf16 v[16:19], v[172:175], v[234:237], v[16:19]
	v_mfma_f32_16x16x32_bf16 v[4:7], v[164:167], v[242:245], v[4:7]
	v_mfma_f32_16x16x32_bf16 v[0:3], v[172:175], v[242:245], v[0:3]
	v_mfma_f32_16x16x32_bf16 v[52:55], v[168:171], v[184:187], v[52:55]
	v_mfma_f32_16x16x32_bf16 v[48:51], v[176:179], v[184:187], v[48:51]
	v_mfma_f32_16x16x32_bf16 v[36:39], v[168:171], v[230:233], v[36:39]
	v_mfma_f32_16x16x32_bf16 v[32:35], v[176:179], v[230:233], v[32:35]
	v_mfma_f32_16x16x32_bf16 v[20:23], v[168:171], v[238:241], v[20:23]
	v_mfma_f32_16x16x32_bf16 v[16:19], v[176:179], v[238:241], v[16:19]
	v_mfma_f32_16x16x32_bf16 v[4:7], v[168:171], v[246:249], v[4:7]
	v_mfma_f32_16x16x32_bf16 v[0:3], v[176:179], v[246:249], v[0:3]
	s_setprio 0
	s_barrier
	s_add_i32 s56, s56, 2
	s_add_u32 s54, s54, 0x100
	s_addc_u32 s55, s55, 0
	s_add_u32 s6, s6, 0x100
	s_addc_u32 s7, s7, 0
	s_cmp_gt_u32 s56, 13
	s_cbranch_scc0 .LBB0_2369
